# EpiRes epilogues: LN gain/bias loads hoisted once per tile, 4 residual loads per row-block issued together with counted waits; triangular solve LDS reads prefetched 12 deep
# speedup vs baseline: 1.0448x; 1.0448x over previous
; __device__ __forceinline__ unsigned pk2(float lo, float hi) { const f32x2_t v = {lo, hi}; const bf16x2_t b = __builtin_convertvector(v, bf16x2_t); return __builtin_bit_cast(unsigned, b); }
; __device__ __forceinline__ float bflo(unsigned w) { return __uint_as_float(w << 16); }
; __device__ __forceinline__ float bfhi(unsigned w) { return __uint_as_float(w & 0xffff0000u); }
;     __device__ __forceinline__ void operator()(const f32x4 (&acc)[2][2][4][2], const pg8::Unit& u, int wr, int wc, int fr, int fq) const {
;     ...
;                 const int row = row0 + ai * 128 + m * 16; float mu, rstd; row_stats(stats_prev, row, mu, rstd);
;                 float s = 0.f, q = 0.f;
; #pragma unroll
;                 for (int bj = 0; bj < 2; ++bj)
; #pragma unroll
;                     for (int n = 0; n < 2; ++n) {
;                         const int col = col0 + bj * 128 + n * 16;
;                         const u32x2 rb = *(const u32x2*)(YB + (size_t)row * D_ + col);
;                         f32x4 r = (f32x4){bflo(rb.x), bfhi(rb.x), bflo(rb.y), bfhi(rb.y)};
;                         if (stats_prev) { const f32x4 g4 = *(const f32x4*)(lng + col), b4 = *(const f32x4*)(lnb + col); r = (r - mu) * rstd * g4 + b4; }
;                         const f32x4 y = r * ALPHA_ + acc[ai][bj][m][n] * coef;
;                         if (Yout) *(f32x4*)(Yout + (size_t)row * D_ + col) = y;
;                         else { u32x2 w; w.x = pk2(y[0], y[1]); w.y = pk2(y[2], y[3]); *(u32x2*)(YB + (size_t)row * D_ + col) = w; }
;                         s += (y[0] + y[1]) + (y[2] + y[3]); q += (y[0] * y[0] + y[1] * y[1]) + (y[2] * y[2] + y[3] * y[3]);
;                     }
.LBB0_69:
	v_lshl_or_b32 v140, s33, 8, v154
	v_lshlrev_b64 v[134:135], 11, v[138:139]
	v_lshl_add_u64 v[134:135], s[16:17], 0, v[134:135]
	v_ashrrev_i32_e32 v141, 31, v140
	v_lshl_add_u64 v[142:143], v[140:141], 1, v[134:135]
	global_load_dwordx2 v[136:137], v[142:143], off
	global_load_dwordx2 v[220:221], v[142:143], off offset:32
	global_load_dwordx2 v[222:223], v[142:143], off offset:256
	global_load_dwordx2 v[224:225], v[142:143], off offset:288
	v_lshlrev_b64 v[156:157], 2, v[140:141]
	v_readlane_b32 s56, v254, 36
	v_mov_b32_e32 v147, v146
	s_and_b64 vcc, exec, s[6:7]
	v_lshl_add_u64 v[134:135], s[18:19], 0, v[156:157]
	v_readlane_b32 s57, v254, 37
	s_waitcnt vmcnt(3)
	v_lshlrev_b32_e32 v148, 16, v136
	v_and_b32_e32 v149, 0xffff0000, v136
	v_lshlrev_b32_e32 v150, 16, v137
	v_and_b32_e32 v151, 0xffff0000, v137
	v_lshl_add_u64 v[136:137], s[20:21], 0, v[156:157]
	s_cbranch_vccnz .LBB0_71
	v_sub_f32_e32 v149, v149, v144
	v_sub_f32_e32 v148, v148, v144
	v_sub_f32_e32 v151, v151, v144
	v_sub_f32_e32 v150, v150, v144
	v_pk_mul_f32 v[160:161], v[146:147], v[148:149]
	v_mov_b32_e32 v148, v146
	v_mov_b32_e32 v149, v146
	v_pk_mul_f32 v[162:163], v[148:149], v[150:151]
	global_load_dwordx4 v[164:167], v[134:135], off
	global_load_dwordx4 v[204:207], v[136:137], off
	global_load_dwordx4 v[168:171], v[134:135], off offset:64
	global_load_dwordx4 v[208:211], v[136:137], off offset:64
	global_load_dwordx4 v[172:175], v[134:135], off offset:512
	global_load_dwordx4 v[212:215], v[136:137], off offset:512
	global_load_dwordx4 v[176:179], v[134:135], off offset:576
	global_load_dwordx4 v[216:219], v[136:137], off offset:576
	s_waitcnt vmcnt(0)
	v_pk_fma_f32 v[150:151], v[162:163], v[166:167], v[206:207]
	v_pk_fma_f32 v[148:149], v[160:161], v[164:165], v[204:205]
.LBB0_71:
	s_mov_b32 s26, 0x3fb504f3
	v_pk_mul_f32 v[150:151], v[150:151], s[26:27] op_sel_hi:[1,0]
	v_pk_mul_f32 v[148:149], v[148:149], s[26:27] op_sel_hi:[1,0]
	v_pk_fma_f32 v[126:127], v[126:127], 0.5, v[150:151] op_sel_hi:[1,0,1]
	v_pk_fma_f32 v[124:125], v[124:125], 0.5, v[148:149] op_sel_hi:[1,0,1]
	v_cvt_pk_bf16_f32 v149, v126, v127
	v_cvt_pk_bf16_f32 v148, v124, v125
	global_store_dwordx2 v[142:143], v[148:149], off
	s_and_b64 vcc, exec, s[6:7]
	s_waitcnt vmcnt(3)
	v_lshlrev_b32_e32 v148, 16, v220
	v_and_b32_e32 v149, 0xffff0000, v220
	v_lshlrev_b32_e32 v150, 16, v221
	v_and_b32_e32 v151, 0xffff0000, v221
	s_cbranch_vccnz .LBB0_73
	v_sub_f32_e32 v149, v149, v144
	v_sub_f32_e32 v148, v148, v144
	v_sub_f32_e32 v151, v151, v144
	v_sub_f32_e32 v150, v150, v144
	v_pk_mul_f32 v[160:161], v[146:147], v[148:149]
	v_mov_b32_e32 v148, v146
	v_mov_b32_e32 v149, v146
	v_pk_mul_f32 v[162:163], v[148:149], v[150:151]
	v_pk_fma_f32 v[150:151], v[162:163], v[170:171], v[210:211]
	v_pk_fma_f32 v[148:149], v[160:161], v[168:169], v[208:209]
.LBB0_73:
	v_pk_mul_f32 v[150:151], v[150:151], s[26:27] op_sel_hi:[1,0]
	v_pk_mul_f32 v[148:149], v[148:149], s[26:27] op_sel_hi:[1,0]
	v_pk_fma_f32 v[122:123], v[122:123], 0.5, v[150:151] op_sel_hi:[1,0,1]
	v_pk_fma_f32 v[120:121], v[120:121], 0.5, v[148:149] op_sel_hi:[1,0,1]
	v_cvt_pk_bf16_f32 v149, v122, v123
	v_cvt_pk_bf16_f32 v148, v120, v121
	global_store_dwordx2 v[142:143], v[148:149], off offset:32
	s_and_b64 vcc, exec, s[6:7]
	s_waitcnt vmcnt(3)
	v_lshlrev_b32_e32 v148, 16, v222
	v_and_b32_e32 v149, 0xffff0000, v222
	v_lshlrev_b32_e32 v150, 16, v223
	v_and_b32_e32 v151, 0xffff0000, v223
	s_cbranch_vccnz .LBB0_75
	v_sub_f32_e32 v149, v149, v144
	v_sub_f32_e32 v148, v148, v144
	v_sub_f32_e32 v151, v151, v144
	v_sub_f32_e32 v150, v150, v144
	v_pk_mul_f32 v[160:161], v[146:147], v[148:149]
	v_mov_b32_e32 v148, v146
	v_mov_b32_e32 v149, v146
	v_pk_mul_f32 v[162:163], v[148:149], v[150:151]
	v_pk_fma_f32 v[150:151], v[162:163], v[174:175], v[214:215]
	v_pk_fma_f32 v[148:149], v[160:161], v[172:173], v[212:213]
.LBB0_75:
	v_pk_mul_f32 v[150:151], v[150:151], s[26:27] op_sel_hi:[1,0]
	v_pk_mul_f32 v[148:149], v[148:149], s[26:27] op_sel_hi:[1,0]
	v_pk_fma_f32 v[118:119], v[118:119], 0.5, v[150:151] op_sel_hi:[1,0,1]
	v_pk_fma_f32 v[116:117], v[116:117], 0.5, v[148:149] op_sel_hi:[1,0,1]
	v_cvt_pk_bf16_f32 v149, v118, v119
	v_cvt_pk_bf16_f32 v148, v116, v117
	global_store_dwordx2 v[142:143], v[148:149], off offset:256
	s_and_b64 vcc, exec, s[6:7]
	s_waitcnt vmcnt(3)
	v_lshlrev_b32_e32 v148, 16, v224
	v_and_b32_e32 v149, 0xffff0000, v224
	v_lshlrev_b32_e32 v150, 16, v225
	v_and_b32_e32 v151, 0xffff0000, v225
	s_cbranch_vccnz .LBB0_77
	v_sub_f32_e32 v151, v151, v144
	v_sub_f32_e32 v150, v150, v144
	v_sub_f32_e32 v145, v149, v144
	v_sub_f32_e32 v144, v148, v144
	v_pk_mul_f32 v[156:157], v[146:147], v[144:145]
	v_mov_b32_e32 v147, v146
	v_pk_mul_f32 v[158:159], v[146:147], v[150:151]
	v_pk_fma_f32 v[150:151], v[158:159], v[178:179], v[218:219]
	v_pk_fma_f32 v[148:149], v[156:157], v[176:177], v[216:217]

; __device__ __forceinline__ unsigned pk2(float lo, float hi) { const f32x2_t v = {lo, hi}; const bf16x2_t b = __builtin_convertvector(v, bf16x2_t); return __builtin_bit_cast(unsigned, b); }
; __device__ __forceinline__ float bflo(unsigned w) { return __uint_as_float(w << 16); }
; __device__ __forceinline__ float bfhi(unsigned w) { return __uint_as_float(w & 0xffff0000u); }
;     __device__ __forceinline__ void operator()(const f32x4 (&acc)[2][2][4][2], const pg8::Unit& u, int wr, int wc, int fr, int fq) const {
;     ...
;                 const int row = row0 + ai * 128 + m * 16; float mu, rstd; row_stats(stats_prev, row, mu, rstd);
;                 float s = 0.f, q = 0.f;
; #pragma unroll
;                 for (int bj = 0; bj < 2; ++bj)
; #pragma unroll
;                     for (int n = 0; n < 2; ++n) {
;                         const int col = col0 + bj * 128 + n * 16;
;                         const u32x2 rb = *(const u32x2*)(YB + (size_t)row * D_ + col);
;                         f32x4 r = (f32x4){bflo(rb.x), bfhi(rb.x), bflo(rb.y), bfhi(rb.y)};
;                         if (stats_prev) { const f32x4 g4 = *(const f32x4*)(lng + col), b4 = *(const f32x4*)(lnb + col); r = (r - mu) * rstd * g4 + b4; }
;                         const f32x4 y = r * ALPHA_ + acc[ai][bj][m][n] * coef;
;                         if (Yout) *(f32x4*)(Yout + (size_t)row * D_ + col) = y;
;                         else { u32x2 w; w.x = pk2(y[0], y[1]); w.y = pk2(y[2], y[3]); *(u32x2*)(YB + (size_t)row * D_ + col) = w; }
;                         s += (y[0] + y[1]) + (y[2] + y[3]); q += (y[0] * y[0] + y[1] * y[1]) + (y[2] * y[2] + y[3] * y[3]);
;                     }
.LBB0_82:
	s_waitcnt lgkmcnt(0)
	v_lshlrev_b64 v[114:115], 11, v[112:113]
	v_lshl_add_u64 v[114:115], s[16:17], 0, v[114:115]
	v_lshl_add_u64 v[114:115], v[140:141], 1, v[114:115]
	global_load_dwordx2 v[122:123], v[114:115], off
	global_load_dwordx2 v[220:221], v[114:115], off offset:32
	global_load_dwordx2 v[222:223], v[114:115], off offset:256
	global_load_dwordx2 v[224:225], v[114:115], off offset:288
	v_mov_b32_e32 v119, v118
	s_and_b64 vcc, exec, s[6:7]
	s_waitcnt vmcnt(3)
	v_lshlrev_b32_e32 v120, 16, v122
	v_and_b32_e32 v121, 0xffff0000, v122
	v_lshlrev_b32_e32 v122, 16, v123
	v_and_b32_e32 v123, 0xffff0000, v123
	s_cbranch_vccnz .LBB0_84
	v_sub_f32_e32 v121, v121, v116
	v_sub_f32_e32 v120, v120, v116
	v_sub_f32_e32 v123, v123, v116
	v_sub_f32_e32 v122, v122, v116
	v_pk_mul_f32 v[126:127], v[118:119], v[120:121]
	v_mov_b32_e32 v120, v118
	v_mov_b32_e32 v121, v118
	v_pk_mul_f32 v[146:147], v[120:121], v[122:123]
	v_pk_fma_f32 v[122:123], v[146:147], v[166:167], v[206:207]
	v_pk_fma_f32 v[120:121], v[126:127], v[164:165], v[204:205]
.LBB0_84:
	s_mov_b32 s28, 0x3fb504f3
	v_pk_mul_f32 v[122:123], v[122:123], s[28:29] op_sel_hi:[1,0]
	v_pk_mul_f32 v[120:121], v[120:121], s[28:29] op_sel_hi:[1,0]
	v_pk_fma_f32 v[110:111], v[110:111], 0.5, v[122:123] op_sel_hi:[1,0,1]
	v_pk_fma_f32 v[108:109], v[108:109], 0.5, v[120:121] op_sel_hi:[1,0,1]
	v_cvt_pk_bf16_f32 v121, v110, v111
	v_cvt_pk_bf16_f32 v120, v108, v109
	global_store_dwordx2 v[114:115], v[120:121], off
	s_and_b64 vcc, exec, s[6:7]
	s_waitcnt vmcnt(3)
	v_lshlrev_b32_e32 v120, 16, v220
	v_and_b32_e32 v121, 0xffff0000, v220
	v_lshlrev_b32_e32 v122, 16, v221
	v_and_b32_e32 v123, 0xffff0000, v221
	s_cbranch_vccnz .LBB0_86
	v_sub_f32_e32 v121, v121, v116
	v_sub_f32_e32 v120, v120, v116
	v_sub_f32_e32 v123, v123, v116
	v_sub_f32_e32 v122, v122, v116
	v_pk_mul_f32 v[126:127], v[118:119], v[120:121]
	v_mov_b32_e32 v120, v118
	v_mov_b32_e32 v121, v118
	v_pk_mul_f32 v[146:147], v[120:121], v[122:123]
	v_pk_fma_f32 v[122:123], v[146:147], v[170:171], v[210:211]
	v_pk_fma_f32 v[120:121], v[126:127], v[168:169], v[208:209]
.LBB0_86:
	v_pk_mul_f32 v[122:123], v[122:123], s[28:29] op_sel_hi:[1,0]
	v_pk_mul_f32 v[120:121], v[120:121], s[28:29] op_sel_hi:[1,0]
	v_pk_fma_f32 v[106:107], v[106:107], 0.5, v[122:123] op_sel_hi:[1,0,1]
	v_pk_fma_f32 v[104:105], v[104:105], 0.5, v[120:121] op_sel_hi:[1,0,1]
	v_cvt_pk_bf16_f32 v121, v106, v107
	v_cvt_pk_bf16_f32 v120, v104, v105
	global_store_dwordx2 v[114:115], v[120:121], off offset:32
	s_and_b64 vcc, exec, s[6:7]
	s_waitcnt vmcnt(3)
	v_lshlrev_b32_e32 v120, 16, v222
	v_and_b32_e32 v121, 0xffff0000, v222
	v_lshlrev_b32_e32 v122, 16, v223
	v_and_b32_e32 v123, 0xffff0000, v223
	s_cbranch_vccnz .LBB0_88
	v_sub_f32_e32 v121, v121, v116
	v_sub_f32_e32 v120, v120, v116
	v_sub_f32_e32 v123, v123, v116
	v_sub_f32_e32 v122, v122, v116
	v_pk_mul_f32 v[126:127], v[118:119], v[120:121]
	v_mov_b32_e32 v120, v118
	v_mov_b32_e32 v121, v118
	v_pk_mul_f32 v[146:147], v[120:121], v[122:123]
	v_pk_fma_f32 v[122:123], v[146:147], v[174:175], v[214:215]
	v_pk_fma_f32 v[120:121], v[126:127], v[172:173], v[212:213]
.LBB0_88:
	v_pk_mul_f32 v[122:123], v[122:123], s[28:29] op_sel_hi:[1,0]
	v_pk_mul_f32 v[120:121], v[120:121], s[28:29] op_sel_hi:[1,0]
	v_pk_fma_f32 v[102:103], v[102:103], 0.5, v[122:123] op_sel_hi:[1,0,1]
	v_pk_fma_f32 v[100:101], v[100:101], 0.5, v[120:121] op_sel_hi:[1,0,1]
	v_cvt_pk_bf16_f32 v121, v102, v103
	v_cvt_pk_bf16_f32 v120, v100, v101
	global_store_dwordx2 v[114:115], v[120:121], off offset:256
	s_and_b64 vcc, exec, s[6:7]
	s_waitcnt vmcnt(3)
	v_lshlrev_b32_e32 v120, 16, v224
	v_and_b32_e32 v121, 0xffff0000, v224
	v_lshlrev_b32_e32 v122, 16, v225
	v_and_b32_e32 v123, 0xffff0000, v225
	s_cbranch_vccnz .LBB0_90
	v_sub_f32_e32 v123, v123, v116
	v_sub_f32_e32 v122, v122, v116
	v_sub_f32_e32 v117, v121, v116
	v_sub_f32_e32 v116, v120, v116
	v_pk_mul_f32 v[126:127], v[118:119], v[116:117]
	v_mov_b32_e32 v119, v118
	v_pk_mul_f32 v[142:143], v[118:119], v[122:123]
	v_pk_fma_f32 v[122:123], v[142:143], v[178:179], v[218:219]
	v_pk_fma_f32 v[120:121], v[126:127], v[176:177], v[216:217]

; __device__ __forceinline__ unsigned pk2(float lo, float hi) { const f32x2_t v = {lo, hi}; const bf16x2_t b = __builtin_convertvector(v, bf16x2_t); return __builtin_bit_cast(unsigned, b); }
; __device__ __forceinline__ float bflo(unsigned w) { return __uint_as_float(w << 16); }
; __device__ __forceinline__ float bfhi(unsigned w) { return __uint_as_float(w & 0xffff0000u); }
;     __device__ __forceinline__ void operator()(const f32x4 (&acc)[2][2][4][2], const pg8::Unit& u, int wr, int wc, int fr, int fq) const {
;     ...
;                 const int row = row0 + ai * 128 + m * 16; float mu, rstd; row_stats(stats_prev, row, mu, rstd);
;                 float s = 0.f, q = 0.f;
; #pragma unroll
;                 for (int bj = 0; bj < 2; ++bj)
; #pragma unroll
;                     for (int n = 0; n < 2; ++n) {
;                         const int col = col0 + bj * 128 + n * 16;
;                         const u32x2 rb = *(const u32x2*)(YB + (size_t)row * D_ + col);
;                         f32x4 r = (f32x4){bflo(rb.x), bfhi(rb.x), bflo(rb.y), bfhi(rb.y)};
;                         if (stats_prev) { const f32x4 g4 = *(const f32x4*)(lng + col), b4 = *(const f32x4*)(lnb + col); r = (r - mu) * rstd * g4 + b4; }
;                         const f32x4 y = r * ALPHA_ + acc[ai][bj][m][n] * coef;
;                         if (Yout) *(f32x4*)(Yout + (size_t)row * D_ + col) = y;
;                         else { u32x2 w; w.x = pk2(y[0], y[1]); w.y = pk2(y[2], y[3]); *(u32x2*)(YB + (size_t)row * D_ + col) = w; }
;                         s += (y[0] + y[1]) + (y[2] + y[3]); q += (y[0] * y[0] + y[1] * y[1]) + (y[2] * y[2] + y[3] * y[3]);
;                     }
.LBB0_95:
	s_waitcnt lgkmcnt(0)
	v_lshlrev_b64 v[98:99], 11, v[96:97]
	v_lshl_add_u64 v[98:99], s[16:17], 0, v[98:99]
	v_lshl_add_u64 v[98:99], v[140:141], 1, v[98:99]
	global_load_dwordx2 v[106:107], v[98:99], off
	global_load_dwordx2 v[220:221], v[98:99], off offset:32
	global_load_dwordx2 v[222:223], v[98:99], off offset:256
	global_load_dwordx2 v[224:225], v[98:99], off offset:288
	v_mov_b32_e32 v103, v102
	s_and_b64 vcc, exec, s[6:7]
	s_waitcnt vmcnt(3)
	v_lshlrev_b32_e32 v104, 16, v106
	v_and_b32_e32 v105, 0xffff0000, v106
	v_lshlrev_b32_e32 v106, 16, v107
	v_and_b32_e32 v107, 0xffff0000, v107
	s_cbranch_vccnz .LBB0_97
	v_sub_f32_e32 v105, v105, v100
	v_sub_f32_e32 v104, v104, v100
	v_sub_f32_e32 v107, v107, v100
	v_sub_f32_e32 v106, v106, v100
	v_pk_mul_f32 v[112:113], v[102:103], v[104:105]
	v_mov_b32_e32 v104, v102
	v_mov_b32_e32 v105, v102
	v_pk_mul_f32 v[114:115], v[104:105], v[106:107]
	v_pk_fma_f32 v[106:107], v[114:115], v[166:167], v[206:207]
	v_pk_fma_f32 v[104:105], v[112:113], v[164:165], v[204:205]
.LBB0_97:
	s_mov_b32 s28, 0x3fb504f3
	v_pk_mul_f32 v[106:107], v[106:107], s[28:29] op_sel_hi:[1,0]
	v_pk_mul_f32 v[104:105], v[104:105], s[28:29] op_sel_hi:[1,0]
	v_pk_fma_f32 v[94:95], v[94:95], 0.5, v[106:107] op_sel_hi:[1,0,1]
	v_pk_fma_f32 v[92:93], v[92:93], 0.5, v[104:105] op_sel_hi:[1,0,1]
	v_cvt_pk_bf16_f32 v105, v94, v95
	v_cvt_pk_bf16_f32 v104, v92, v93
	global_store_dwordx2 v[98:99], v[104:105], off
	s_and_b64 vcc, exec, s[6:7]
	s_waitcnt vmcnt(3)
	v_lshlrev_b32_e32 v104, 16, v220
	v_and_b32_e32 v105, 0xffff0000, v220
	v_lshlrev_b32_e32 v106, 16, v221
	v_and_b32_e32 v107, 0xffff0000, v221
	s_cbranch_vccnz .LBB0_99
	v_sub_f32_e32 v105, v105, v100
	v_sub_f32_e32 v104, v104, v100
	v_sub_f32_e32 v107, v107, v100
	v_sub_f32_e32 v106, v106, v100
	v_pk_mul_f32 v[112:113], v[102:103], v[104:105]
	v_mov_b32_e32 v104, v102
	v_mov_b32_e32 v105, v102
	v_pk_mul_f32 v[114:115], v[104:105], v[106:107]
	v_pk_fma_f32 v[106:107], v[114:115], v[170:171], v[210:211]
	v_pk_fma_f32 v[104:105], v[112:113], v[168:169], v[208:209]
.LBB0_99:
	v_pk_mul_f32 v[106:107], v[106:107], s[28:29] op_sel_hi:[1,0]
	v_pk_mul_f32 v[104:105], v[104:105], s[28:29] op_sel_hi:[1,0]
	v_pk_fma_f32 v[90:91], v[90:91], 0.5, v[106:107] op_sel_hi:[1,0,1]
	v_pk_fma_f32 v[88:89], v[88:89], 0.5, v[104:105] op_sel_hi:[1,0,1]
	v_cvt_pk_bf16_f32 v105, v90, v91
	v_cvt_pk_bf16_f32 v104, v88, v89
	global_store_dwordx2 v[98:99], v[104:105], off offset:32
	s_and_b64 vcc, exec, s[6:7]
	s_waitcnt vmcnt(3)
	v_lshlrev_b32_e32 v104, 16, v222
	v_and_b32_e32 v105, 0xffff0000, v222
	v_lshlrev_b32_e32 v106, 16, v223
	v_and_b32_e32 v107, 0xffff0000, v223
	s_cbranch_vccnz .LBB0_101
	v_sub_f32_e32 v105, v105, v100
	v_sub_f32_e32 v104, v104, v100
	v_sub_f32_e32 v107, v107, v100
	v_sub_f32_e32 v106, v106, v100
	v_pk_mul_f32 v[112:113], v[102:103], v[104:105]
	v_mov_b32_e32 v104, v102
	v_mov_b32_e32 v105, v102
	v_pk_mul_f32 v[114:115], v[104:105], v[106:107]
	v_pk_fma_f32 v[106:107], v[114:115], v[174:175], v[214:215]
	v_pk_fma_f32 v[104:105], v[112:113], v[172:173], v[212:213]
.LBB0_101:
	v_pk_mul_f32 v[106:107], v[106:107], s[28:29] op_sel_hi:[1,0]
	v_pk_mul_f32 v[104:105], v[104:105], s[28:29] op_sel_hi:[1,0]
	v_pk_fma_f32 v[86:87], v[86:87], 0.5, v[106:107] op_sel_hi:[1,0,1]
	v_pk_fma_f32 v[84:85], v[84:85], 0.5, v[104:105] op_sel_hi:[1,0,1]
	v_cvt_pk_bf16_f32 v105, v86, v87
	v_cvt_pk_bf16_f32 v104, v84, v85
	global_store_dwordx2 v[98:99], v[104:105], off offset:256
	s_and_b64 vcc, exec, s[6:7]
	s_waitcnt vmcnt(3)
	v_lshlrev_b32_e32 v104, 16, v224
	v_and_b32_e32 v105, 0xffff0000, v224
	v_lshlrev_b32_e32 v106, 16, v225
	v_and_b32_e32 v107, 0xffff0000, v225
	s_cbranch_vccnz .LBB0_103
	v_sub_f32_e32 v107, v107, v100
	v_sub_f32_e32 v106, v106, v100
	v_sub_f32_e32 v101, v105, v100
	v_sub_f32_e32 v100, v104, v100
	v_pk_mul_f32 v[108:109], v[102:103], v[100:101]
	v_mov_b32_e32 v103, v102
	v_pk_mul_f32 v[110:111], v[102:103], v[106:107]
	v_pk_fma_f32 v[106:107], v[110:111], v[178:179], v[218:219]
	v_pk_fma_f32 v[104:105], v[108:109], v[176:177], v[216:217]

; __device__ __forceinline__ unsigned pk2(float lo, float hi) { const f32x2_t v = {lo, hi}; const bf16x2_t b = __builtin_convertvector(v, bf16x2_t); return __builtin_bit_cast(unsigned, b); }
; __device__ __forceinline__ float bflo(unsigned w) { return __uint_as_float(w << 16); }
; __device__ __forceinline__ float bfhi(unsigned w) { return __uint_as_float(w & 0xffff0000u); }
;     __device__ __forceinline__ void operator()(const f32x4 (&acc)[2][2][4][2], const pg8::Unit& u, int wr, int wc, int fr, int fq) const {
;     ...
;                 const int row = row0 + ai * 128 + m * 16; float mu, rstd; row_stats(stats_prev, row, mu, rstd);
;                 float s = 0.f, q = 0.f;
; #pragma unroll
;                 for (int bj = 0; bj < 2; ++bj)
; #pragma unroll
;                     for (int n = 0; n < 2; ++n) {
;                         const int col = col0 + bj * 128 + n * 16;
;                         const u32x2 rb = *(const u32x2*)(YB + (size_t)row * D_ + col);
;                         f32x4 r = (f32x4){bflo(rb.x), bfhi(rb.x), bflo(rb.y), bfhi(rb.y)};
;                         if (stats_prev) { const f32x4 g4 = *(const f32x4*)(lng + col), b4 = *(const f32x4*)(lnb + col); r = (r - mu) * rstd * g4 + b4; }
;                         const f32x4 y = r * ALPHA_ + acc[ai][bj][m][n] * coef;
;                         if (Yout) *(f32x4*)(Yout + (size_t)row * D_ + col) = y;
;                         else { u32x2 w; w.x = pk2(y[0], y[1]); w.y = pk2(y[2], y[3]); *(u32x2*)(YB + (size_t)row * D_ + col) = w; }
;                         s += (y[0] + y[1]) + (y[2] + y[3]); q += (y[0] * y[0] + y[1] * y[1]) + (y[2] * y[2] + y[3] * y[3]);
;                     }
.LBB0_108:
	s_waitcnt lgkmcnt(0)
	v_lshlrev_b64 v[82:83], 11, v[80:81]
	v_lshl_add_u64 v[82:83], s[16:17], 0, v[82:83]
	v_lshl_add_u64 v[82:83], v[140:141], 1, v[82:83]
	global_load_dwordx2 v[90:91], v[82:83], off
	global_load_dwordx2 v[220:221], v[82:83], off offset:32
	global_load_dwordx2 v[222:223], v[82:83], off offset:256
	global_load_dwordx2 v[224:225], v[82:83], off offset:288
	v_mov_b32_e32 v87, v86
	s_and_b64 vcc, exec, s[6:7]
	s_waitcnt vmcnt(3)
	v_lshlrev_b32_e32 v88, 16, v90
	v_and_b32_e32 v89, 0xffff0000, v90
	v_lshlrev_b32_e32 v90, 16, v91
	v_and_b32_e32 v91, 0xffff0000, v91
	s_cbranch_vccnz .LBB0_110
	v_sub_f32_e32 v89, v89, v84
	v_sub_f32_e32 v88, v88, v84
	v_sub_f32_e32 v91, v91, v84
	v_sub_f32_e32 v90, v90, v84
	v_pk_mul_f32 v[96:97], v[86:87], v[88:89]
	v_mov_b32_e32 v88, v86
	v_mov_b32_e32 v89, v86
	v_pk_mul_f32 v[98:99], v[88:89], v[90:91]
	v_pk_fma_f32 v[90:91], v[98:99], v[166:167], v[206:207]
	v_pk_fma_f32 v[88:89], v[96:97], v[164:165], v[204:205]
.LBB0_110:
	s_mov_b32 s28, 0x3fb504f3
	v_pk_mul_f32 v[90:91], v[90:91], s[28:29] op_sel_hi:[1,0]
	v_pk_mul_f32 v[88:89], v[88:89], s[28:29] op_sel_hi:[1,0]
	v_pk_fma_f32 v[78:79], v[78:79], 0.5, v[90:91] op_sel_hi:[1,0,1]
	v_pk_fma_f32 v[76:77], v[76:77], 0.5, v[88:89] op_sel_hi:[1,0,1]
	v_cvt_pk_bf16_f32 v89, v78, v79
	v_cvt_pk_bf16_f32 v88, v76, v77
	global_store_dwordx2 v[82:83], v[88:89], off
	s_and_b64 vcc, exec, s[6:7]
	s_waitcnt vmcnt(3)
	v_lshlrev_b32_e32 v88, 16, v220
	v_and_b32_e32 v89, 0xffff0000, v220
	v_lshlrev_b32_e32 v90, 16, v221
	v_and_b32_e32 v91, 0xffff0000, v221
	s_cbranch_vccnz .LBB0_112
	v_sub_f32_e32 v89, v89, v84
	v_sub_f32_e32 v88, v88, v84
	v_sub_f32_e32 v91, v91, v84
	v_sub_f32_e32 v90, v90, v84
	v_pk_mul_f32 v[96:97], v[86:87], v[88:89]
	v_mov_b32_e32 v88, v86
	v_mov_b32_e32 v89, v86
	v_pk_mul_f32 v[98:99], v[88:89], v[90:91]
	v_pk_fma_f32 v[90:91], v[98:99], v[170:171], v[210:211]
	v_pk_fma_f32 v[88:89], v[96:97], v[168:169], v[208:209]
.LBB0_112:
	v_pk_mul_f32 v[90:91], v[90:91], s[28:29] op_sel_hi:[1,0]
	v_pk_mul_f32 v[88:89], v[88:89], s[28:29] op_sel_hi:[1,0]
	v_pk_fma_f32 v[74:75], v[74:75], 0.5, v[90:91] op_sel_hi:[1,0,1]
	v_pk_fma_f32 v[72:73], v[72:73], 0.5, v[88:89] op_sel_hi:[1,0,1]
	v_cvt_pk_bf16_f32 v89, v74, v75
	v_cvt_pk_bf16_f32 v88, v72, v73
	global_store_dwordx2 v[82:83], v[88:89], off offset:32
	s_and_b64 vcc, exec, s[6:7]
	s_waitcnt vmcnt(3)
	v_lshlrev_b32_e32 v88, 16, v222
	v_and_b32_e32 v89, 0xffff0000, v222
	v_lshlrev_b32_e32 v90, 16, v223
	v_and_b32_e32 v91, 0xffff0000, v223
	s_cbranch_vccnz .LBB0_114
	v_sub_f32_e32 v89, v89, v84
	v_sub_f32_e32 v88, v88, v84
	v_sub_f32_e32 v91, v91, v84
	v_sub_f32_e32 v90, v90, v84
	v_pk_mul_f32 v[96:97], v[86:87], v[88:89]
	v_mov_b32_e32 v88, v86
	v_mov_b32_e32 v89, v86
	v_pk_mul_f32 v[98:99], v[88:89], v[90:91]
	v_pk_fma_f32 v[90:91], v[98:99], v[174:175], v[214:215]
	v_pk_fma_f32 v[88:89], v[96:97], v[172:173], v[212:213]
.LBB0_114:
	v_pk_mul_f32 v[90:91], v[90:91], s[28:29] op_sel_hi:[1,0]
	v_pk_mul_f32 v[88:89], v[88:89], s[28:29] op_sel_hi:[1,0]
	v_pk_fma_f32 v[70:71], v[70:71], 0.5, v[90:91] op_sel_hi:[1,0,1]
	v_pk_fma_f32 v[68:69], v[68:69], 0.5, v[88:89] op_sel_hi:[1,0,1]
	v_cvt_pk_bf16_f32 v89, v70, v71
	v_cvt_pk_bf16_f32 v88, v68, v69
	global_store_dwordx2 v[82:83], v[88:89], off offset:256
	s_and_b64 vcc, exec, s[6:7]
	s_waitcnt vmcnt(3)
	v_lshlrev_b32_e32 v88, 16, v224
	v_and_b32_e32 v89, 0xffff0000, v224
	v_lshlrev_b32_e32 v90, 16, v225
	v_and_b32_e32 v91, 0xffff0000, v225
	s_cbranch_vccnz .LBB0_116
	v_sub_f32_e32 v91, v91, v84
	v_sub_f32_e32 v90, v90, v84
	v_sub_f32_e32 v85, v89, v84
	v_sub_f32_e32 v84, v88, v84
	v_pk_mul_f32 v[92:93], v[86:87], v[84:85]
	v_mov_b32_e32 v87, v86
	v_pk_mul_f32 v[94:95], v[86:87], v[90:91]
	v_pk_fma_f32 v[90:91], v[94:95], v[178:179], v[218:219]
	v_pk_fma_f32 v[88:89], v[92:93], v[176:177], v[216:217]

; __device__ __forceinline__ unsigned pk2(float lo, float hi) { const f32x2_t v = {lo, hi}; const bf16x2_t b = __builtin_convertvector(v, bf16x2_t); return __builtin_bit_cast(unsigned, b); }
; __device__ __forceinline__ float bflo(unsigned w) { return __uint_as_float(w << 16); }
; __device__ __forceinline__ float bfhi(unsigned w) { return __uint_as_float(w & 0xffff0000u); }
;     __device__ __forceinline__ void operator()(const f32x4 (&acc)[2][2][4][2], const pg8::Unit& u, int wr, int wc, int fr, int fq) const {
;     ...
;                 const int row = row0 + ai * 128 + m * 16; float mu, rstd; row_stats(stats_prev, row, mu, rstd);
;                 float s = 0.f, q = 0.f;
; #pragma unroll
;                 for (int bj = 0; bj < 2; ++bj)
; #pragma unroll
;                     for (int n = 0; n < 2; ++n) {
;                         const int col = col0 + bj * 128 + n * 16;
;                         const u32x2 rb = *(const u32x2*)(YB + (size_t)row * D_ + col);
;                         f32x4 r = (f32x4){bflo(rb.x), bfhi(rb.x), bflo(rb.y), bfhi(rb.y)};
;                         if (stats_prev) { const f32x4 g4 = *(const f32x4*)(lng + col), b4 = *(const f32x4*)(lnb + col); r = (r - mu) * rstd * g4 + b4; }
;                         const f32x4 y = r * ALPHA_ + acc[ai][bj][m][n] * coef;
;                         if (Yout) *(f32x4*)(Yout + (size_t)row * D_ + col) = y;
;                         else { u32x2 w; w.x = pk2(y[0], y[1]); w.y = pk2(y[2], y[3]); *(u32x2*)(YB + (size_t)row * D_ + col) = w; }
;                         s += (y[0] + y[1]) + (y[2] + y[3]); q += (y[0] * y[0] + y[1] * y[1]) + (y[2] * y[2] + y[3] * y[3]);
;                     }
.LBB0_121:
	s_waitcnt lgkmcnt(0)
	v_lshlrev_b64 v[66:67], 11, v[64:65]
	v_lshl_add_u64 v[66:67], s[16:17], 0, v[66:67]
	v_lshl_add_u64 v[66:67], v[140:141], 1, v[66:67]
	global_load_dwordx2 v[74:75], v[66:67], off
	global_load_dwordx2 v[220:221], v[66:67], off offset:32
	global_load_dwordx2 v[222:223], v[66:67], off offset:256
	global_load_dwordx2 v[224:225], v[66:67], off offset:288
	v_mov_b32_e32 v71, v70
	s_and_b64 vcc, exec, s[6:7]
	s_waitcnt vmcnt(3)
	v_lshlrev_b32_e32 v72, 16, v74
	v_and_b32_e32 v73, 0xffff0000, v74
	v_lshlrev_b32_e32 v74, 16, v75
	v_and_b32_e32 v75, 0xffff0000, v75
	s_cbranch_vccnz .LBB0_123
	v_sub_f32_e32 v73, v73, v68
	v_sub_f32_e32 v72, v72, v68
	v_sub_f32_e32 v75, v75, v68
	v_sub_f32_e32 v74, v74, v68
	v_pk_mul_f32 v[80:81], v[70:71], v[72:73]
	v_mov_b32_e32 v72, v70
	v_mov_b32_e32 v73, v70
	v_pk_mul_f32 v[82:83], v[72:73], v[74:75]
	v_pk_fma_f32 v[74:75], v[82:83], v[166:167], v[206:207]
	v_pk_fma_f32 v[72:73], v[80:81], v[164:165], v[204:205]
.LBB0_123:
	s_mov_b32 s28, 0x3fb504f3
	v_pk_mul_f32 v[74:75], v[74:75], s[28:29] op_sel_hi:[1,0]
	v_pk_mul_f32 v[72:73], v[72:73], s[28:29] op_sel_hi:[1,0]
	v_pk_fma_f32 v[62:63], v[62:63], 0.5, v[74:75] op_sel_hi:[1,0,1]
	v_pk_fma_f32 v[60:61], v[60:61], 0.5, v[72:73] op_sel_hi:[1,0,1]
	v_cvt_pk_bf16_f32 v73, v62, v63
	v_cvt_pk_bf16_f32 v72, v60, v61
	global_store_dwordx2 v[66:67], v[72:73], off
	s_and_b64 vcc, exec, s[6:7]
	s_waitcnt vmcnt(3)
	v_lshlrev_b32_e32 v72, 16, v220
	v_and_b32_e32 v73, 0xffff0000, v220
	v_lshlrev_b32_e32 v74, 16, v221
	v_and_b32_e32 v75, 0xffff0000, v221
	s_cbranch_vccnz .LBB0_125
	v_sub_f32_e32 v73, v73, v68
	v_sub_f32_e32 v72, v72, v68
	v_sub_f32_e32 v75, v75, v68
	v_sub_f32_e32 v74, v74, v68
	v_pk_mul_f32 v[80:81], v[70:71], v[72:73]
	v_mov_b32_e32 v72, v70
	v_mov_b32_e32 v73, v70
	v_pk_mul_f32 v[82:83], v[72:73], v[74:75]
	v_pk_fma_f32 v[74:75], v[82:83], v[170:171], v[210:211]
	v_pk_fma_f32 v[72:73], v[80:81], v[168:169], v[208:209]
.LBB0_125:
	v_pk_mul_f32 v[74:75], v[74:75], s[28:29] op_sel_hi:[1,0]
	v_pk_mul_f32 v[72:73], v[72:73], s[28:29] op_sel_hi:[1,0]
	v_pk_fma_f32 v[58:59], v[58:59], 0.5, v[74:75] op_sel_hi:[1,0,1]
	v_pk_fma_f32 v[56:57], v[56:57], 0.5, v[72:73] op_sel_hi:[1,0,1]
	v_cvt_pk_bf16_f32 v73, v58, v59
	v_cvt_pk_bf16_f32 v72, v56, v57
	global_store_dwordx2 v[66:67], v[72:73], off offset:32
	s_and_b64 vcc, exec, s[6:7]
	s_waitcnt vmcnt(3)
	v_lshlrev_b32_e32 v72, 16, v222
	v_and_b32_e32 v73, 0xffff0000, v222
	v_lshlrev_b32_e32 v74, 16, v223
	v_and_b32_e32 v75, 0xffff0000, v223
	s_cbranch_vccnz .LBB0_127
	v_sub_f32_e32 v73, v73, v68
	v_sub_f32_e32 v72, v72, v68
	v_sub_f32_e32 v75, v75, v68
	v_sub_f32_e32 v74, v74, v68
	v_pk_mul_f32 v[80:81], v[70:71], v[72:73]
	v_mov_b32_e32 v72, v70
	v_mov_b32_e32 v73, v70
	v_pk_mul_f32 v[82:83], v[72:73], v[74:75]
	v_pk_fma_f32 v[74:75], v[82:83], v[174:175], v[214:215]
	v_pk_fma_f32 v[72:73], v[80:81], v[172:173], v[212:213]
.LBB0_127:
	v_pk_mul_f32 v[74:75], v[74:75], s[28:29] op_sel_hi:[1,0]
	v_pk_mul_f32 v[72:73], v[72:73], s[28:29] op_sel_hi:[1,0]
	v_pk_fma_f32 v[54:55], v[54:55], 0.5, v[74:75] op_sel_hi:[1,0,1]
	v_pk_fma_f32 v[52:53], v[52:53], 0.5, v[72:73] op_sel_hi:[1,0,1]
	v_cvt_pk_bf16_f32 v73, v54, v55
	v_cvt_pk_bf16_f32 v72, v52, v53
	global_store_dwordx2 v[66:67], v[72:73], off offset:256
	s_and_b64 vcc, exec, s[6:7]
	s_waitcnt vmcnt(3)
	v_lshlrev_b32_e32 v72, 16, v224
	v_and_b32_e32 v73, 0xffff0000, v224
	v_lshlrev_b32_e32 v74, 16, v225
	v_and_b32_e32 v75, 0xffff0000, v225
	s_cbranch_vccnz .LBB0_129
	v_sub_f32_e32 v75, v75, v68
	v_sub_f32_e32 v74, v74, v68
	v_sub_f32_e32 v69, v73, v68
	v_sub_f32_e32 v68, v72, v68
	v_pk_mul_f32 v[76:77], v[70:71], v[68:69]
	v_mov_b32_e32 v71, v70
	v_pk_mul_f32 v[78:79], v[70:71], v[74:75]
	v_pk_fma_f32 v[74:75], v[78:79], v[178:179], v[218:219]
	v_pk_fma_f32 v[72:73], v[76:77], v[176:177], v[216:217]

; __device__ __forceinline__ unsigned pk2(float lo, float hi) { const f32x2_t v = {lo, hi}; const bf16x2_t b = __builtin_convertvector(v, bf16x2_t); return __builtin_bit_cast(unsigned, b); }
; __device__ __forceinline__ float bflo(unsigned w) { return __uint_as_float(w << 16); }
; __device__ __forceinline__ float bfhi(unsigned w) { return __uint_as_float(w & 0xffff0000u); }
;     __device__ __forceinline__ void operator()(const f32x4 (&acc)[2][2][4][2], const pg8::Unit& u, int wr, int wc, int fr, int fq) const {
;     ...
;                 const int row = row0 + ai * 128 + m * 16; float mu, rstd; row_stats(stats_prev, row, mu, rstd);
;                 float s = 0.f, q = 0.f;
; #pragma unroll
;                 for (int bj = 0; bj < 2; ++bj)
; #pragma unroll
;                     for (int n = 0; n < 2; ++n) {
;                         const int col = col0 + bj * 128 + n * 16;
;                         const u32x2 rb = *(const u32x2*)(YB + (size_t)row * D_ + col);
;                         f32x4 r = (f32x4){bflo(rb.x), bfhi(rb.x), bflo(rb.y), bfhi(rb.y)};
;                         if (stats_prev) { const f32x4 g4 = *(const f32x4*)(lng + col), b4 = *(const f32x4*)(lnb + col); r = (r - mu) * rstd * g4 + b4; }
;                         const f32x4 y = r * ALPHA_ + acc[ai][bj][m][n] * coef;
;                         if (Yout) *(f32x4*)(Yout + (size_t)row * D_ + col) = y;
;                         else { u32x2 w; w.x = pk2(y[0], y[1]); w.y = pk2(y[2], y[3]); *(u32x2*)(YB + (size_t)row * D_ + col) = w; }
;                         s += (y[0] + y[1]) + (y[2] + y[3]); q += (y[0] * y[0] + y[1] * y[1]) + (y[2] * y[2] + y[3] * y[3]);
;                     }
.LBB0_134:
	s_waitcnt lgkmcnt(0)
	v_lshlrev_b64 v[50:51], 11, v[48:49]
	v_lshl_add_u64 v[50:51], s[16:17], 0, v[50:51]
	v_lshl_add_u64 v[50:51], v[140:141], 1, v[50:51]
	global_load_dwordx2 v[58:59], v[50:51], off
	global_load_dwordx2 v[220:221], v[50:51], off offset:32
	global_load_dwordx2 v[222:223], v[50:51], off offset:256
	global_load_dwordx2 v[224:225], v[50:51], off offset:288
	v_mov_b32_e32 v55, v54
	s_and_b64 vcc, exec, s[6:7]
	s_waitcnt vmcnt(3)
	v_lshlrev_b32_e32 v56, 16, v58
	v_and_b32_e32 v57, 0xffff0000, v58
	v_lshlrev_b32_e32 v58, 16, v59
	v_and_b32_e32 v59, 0xffff0000, v59
	s_cbranch_vccnz .LBB0_136
	v_sub_f32_e32 v57, v57, v52
	v_sub_f32_e32 v56, v56, v52
	v_sub_f32_e32 v59, v59, v52
	v_sub_f32_e32 v58, v58, v52
	v_pk_mul_f32 v[64:65], v[54:55], v[56:57]
	v_mov_b32_e32 v56, v54
	v_mov_b32_e32 v57, v54
	v_pk_mul_f32 v[66:67], v[56:57], v[58:59]
	v_pk_fma_f32 v[58:59], v[66:67], v[166:167], v[206:207]
	v_pk_fma_f32 v[56:57], v[64:65], v[164:165], v[204:205]
.LBB0_136:
	s_mov_b32 s28, 0x3fb504f3
	v_pk_mul_f32 v[58:59], v[58:59], s[28:29] op_sel_hi:[1,0]
	v_pk_mul_f32 v[56:57], v[56:57], s[28:29] op_sel_hi:[1,0]
	v_pk_fma_f32 v[46:47], v[46:47], 0.5, v[58:59] op_sel_hi:[1,0,1]
	v_pk_fma_f32 v[44:45], v[44:45], 0.5, v[56:57] op_sel_hi:[1,0,1]
	v_cvt_pk_bf16_f32 v57, v46, v47
	v_cvt_pk_bf16_f32 v56, v44, v45
	global_store_dwordx2 v[50:51], v[56:57], off
	s_and_b64 vcc, exec, s[6:7]
	s_waitcnt vmcnt(3)
	v_lshlrev_b32_e32 v56, 16, v220
	v_and_b32_e32 v57, 0xffff0000, v220
	v_lshlrev_b32_e32 v58, 16, v221
	v_and_b32_e32 v59, 0xffff0000, v221
	s_cbranch_vccnz .LBB0_138
	v_sub_f32_e32 v57, v57, v52
	v_sub_f32_e32 v56, v56, v52
	v_sub_f32_e32 v59, v59, v52
	v_sub_f32_e32 v58, v58, v52
	v_pk_mul_f32 v[64:65], v[54:55], v[56:57]
	v_mov_b32_e32 v56, v54
	v_mov_b32_e32 v57, v54
	v_pk_mul_f32 v[66:67], v[56:57], v[58:59]
	v_pk_fma_f32 v[58:59], v[66:67], v[170:171], v[210:211]
	v_pk_fma_f32 v[56:57], v[64:65], v[168:169], v[208:209]
.LBB0_138:
	v_pk_mul_f32 v[58:59], v[58:59], s[28:29] op_sel_hi:[1,0]
	v_pk_mul_f32 v[56:57], v[56:57], s[28:29] op_sel_hi:[1,0]
	v_pk_fma_f32 v[42:43], v[42:43], 0.5, v[58:59] op_sel_hi:[1,0,1]
	v_pk_fma_f32 v[40:41], v[40:41], 0.5, v[56:57] op_sel_hi:[1,0,1]
	v_cvt_pk_bf16_f32 v57, v42, v43
	v_cvt_pk_bf16_f32 v56, v40, v41
	global_store_dwordx2 v[50:51], v[56:57], off offset:32
	s_and_b64 vcc, exec, s[6:7]
	s_waitcnt vmcnt(3)
	v_lshlrev_b32_e32 v56, 16, v222
	v_and_b32_e32 v57, 0xffff0000, v222
	v_lshlrev_b32_e32 v58, 16, v223
	v_and_b32_e32 v59, 0xffff0000, v223
	s_cbranch_vccnz .LBB0_140
	v_sub_f32_e32 v57, v57, v52
	v_sub_f32_e32 v56, v56, v52
	v_sub_f32_e32 v59, v59, v52
	v_sub_f32_e32 v58, v58, v52
	v_pk_mul_f32 v[64:65], v[54:55], v[56:57]
	v_mov_b32_e32 v56, v54
	v_mov_b32_e32 v57, v54
	v_pk_mul_f32 v[66:67], v[56:57], v[58:59]
	v_pk_fma_f32 v[58:59], v[66:67], v[174:175], v[214:215]
	v_pk_fma_f32 v[56:57], v[64:65], v[172:173], v[212:213]
.LBB0_140:
	v_pk_mul_f32 v[58:59], v[58:59], s[28:29] op_sel_hi:[1,0]
	v_pk_mul_f32 v[56:57], v[56:57], s[28:29] op_sel_hi:[1,0]
	v_pk_fma_f32 v[38:39], v[38:39], 0.5, v[58:59] op_sel_hi:[1,0,1]
	v_pk_fma_f32 v[36:37], v[36:37], 0.5, v[56:57] op_sel_hi:[1,0,1]
	v_cvt_pk_bf16_f32 v57, v38, v39
	v_cvt_pk_bf16_f32 v56, v36, v37
	global_store_dwordx2 v[50:51], v[56:57], off offset:256
	s_and_b64 vcc, exec, s[6:7]
	s_waitcnt vmcnt(3)
	v_lshlrev_b32_e32 v56, 16, v224
	v_and_b32_e32 v57, 0xffff0000, v224
	v_lshlrev_b32_e32 v58, 16, v225
	v_and_b32_e32 v59, 0xffff0000, v225
	s_cbranch_vccnz .LBB0_142
	v_sub_f32_e32 v59, v59, v52
	v_sub_f32_e32 v58, v58, v52
	v_sub_f32_e32 v53, v57, v52
	v_sub_f32_e32 v52, v56, v52
	v_pk_mul_f32 v[60:61], v[54:55], v[52:53]
	v_mov_b32_e32 v55, v54
	v_pk_mul_f32 v[62:63], v[54:55], v[58:59]
	v_pk_fma_f32 v[58:59], v[62:63], v[178:179], v[218:219]
	v_pk_fma_f32 v[56:57], v[60:61], v[176:177], v[216:217]

; __device__ __forceinline__ unsigned pk2(float lo, float hi) { const f32x2_t v = {lo, hi}; const bf16x2_t b = __builtin_convertvector(v, bf16x2_t); return __builtin_bit_cast(unsigned, b); }
; __device__ __forceinline__ float bflo(unsigned w) { return __uint_as_float(w << 16); }
; __device__ __forceinline__ float bfhi(unsigned w) { return __uint_as_float(w & 0xffff0000u); }
;     __device__ __forceinline__ void operator()(const f32x4 (&acc)[2][2][4][2], const pg8::Unit& u, int wr, int wc, int fr, int fq) const {
;     ...
;                 const int row = row0 + ai * 128 + m * 16; float mu, rstd; row_stats(stats_prev, row, mu, rstd);
;                 float s = 0.f, q = 0.f;
; #pragma unroll
;                 for (int bj = 0; bj < 2; ++bj)
; #pragma unroll
;                     for (int n = 0; n < 2; ++n) {
;                         const int col = col0 + bj * 128 + n * 16;
;                         const u32x2 rb = *(const u32x2*)(YB + (size_t)row * D_ + col);
;                         f32x4 r = (f32x4){bflo(rb.x), bfhi(rb.x), bflo(rb.y), bfhi(rb.y)};
;                         if (stats_prev) { const f32x4 g4 = *(const f32x4*)(lng + col), b4 = *(const f32x4*)(lnb + col); r = (r - mu) * rstd * g4 + b4; }
;                         const f32x4 y = r * ALPHA_ + acc[ai][bj][m][n] * coef;
;                         if (Yout) *(f32x4*)(Yout + (size_t)row * D_ + col) = y;
;                         else { u32x2 w; w.x = pk2(y[0], y[1]); w.y = pk2(y[2], y[3]); *(u32x2*)(YB + (size_t)row * D_ + col) = w; }
;                         s += (y[0] + y[1]) + (y[2] + y[3]); q += (y[0] * y[0] + y[1] * y[1]) + (y[2] * y[2] + y[3] * y[3]);
;                     }
.LBB0_147:
	s_waitcnt lgkmcnt(0)
	v_lshlrev_b64 v[34:35], 11, v[32:33]
	v_lshl_add_u64 v[34:35], s[16:17], 0, v[34:35]
	v_lshl_add_u64 v[34:35], v[140:141], 1, v[34:35]
	global_load_dwordx2 v[42:43], v[34:35], off
	global_load_dwordx2 v[220:221], v[34:35], off offset:32
	global_load_dwordx2 v[222:223], v[34:35], off offset:256
	global_load_dwordx2 v[224:225], v[34:35], off offset:288
	v_mov_b32_e32 v39, v38
	s_and_b64 vcc, exec, s[6:7]
	s_waitcnt vmcnt(3)
	v_lshlrev_b32_e32 v40, 16, v42
	v_and_b32_e32 v41, 0xffff0000, v42
	v_lshlrev_b32_e32 v42, 16, v43
	v_and_b32_e32 v43, 0xffff0000, v43
	s_cbranch_vccnz .LBB0_149
	v_sub_f32_e32 v41, v41, v36
	v_sub_f32_e32 v40, v40, v36
	v_sub_f32_e32 v43, v43, v36
	v_sub_f32_e32 v42, v42, v36
	v_pk_mul_f32 v[48:49], v[38:39], v[40:41]
	v_mov_b32_e32 v40, v38
	v_mov_b32_e32 v41, v38
	v_pk_mul_f32 v[50:51], v[40:41], v[42:43]
	v_pk_fma_f32 v[42:43], v[50:51], v[166:167], v[206:207]
	v_pk_fma_f32 v[40:41], v[48:49], v[164:165], v[204:205]
.LBB0_149:
	s_mov_b32 s28, 0x3fb504f3
	v_pk_mul_f32 v[42:43], v[42:43], s[28:29] op_sel_hi:[1,0]
	v_pk_mul_f32 v[40:41], v[40:41], s[28:29] op_sel_hi:[1,0]
	v_pk_fma_f32 v[30:31], v[30:31], 0.5, v[42:43] op_sel_hi:[1,0,1]
	v_pk_fma_f32 v[28:29], v[28:29], 0.5, v[40:41] op_sel_hi:[1,0,1]
	v_cvt_pk_bf16_f32 v41, v30, v31
	v_cvt_pk_bf16_f32 v40, v28, v29
	global_store_dwordx2 v[34:35], v[40:41], off
	s_and_b64 vcc, exec, s[6:7]
	s_waitcnt vmcnt(3)
	v_lshlrev_b32_e32 v40, 16, v220
	v_and_b32_e32 v41, 0xffff0000, v220
	v_lshlrev_b32_e32 v42, 16, v221
	v_and_b32_e32 v43, 0xffff0000, v221
	s_cbranch_vccnz .LBB0_151
	v_sub_f32_e32 v41, v41, v36
	v_sub_f32_e32 v40, v40, v36
	v_sub_f32_e32 v43, v43, v36
	v_sub_f32_e32 v42, v42, v36
	v_pk_mul_f32 v[48:49], v[38:39], v[40:41]
	v_mov_b32_e32 v40, v38
	v_mov_b32_e32 v41, v38
	v_pk_mul_f32 v[50:51], v[40:41], v[42:43]
	v_pk_fma_f32 v[42:43], v[50:51], v[170:171], v[210:211]
	v_pk_fma_f32 v[40:41], v[48:49], v[168:169], v[208:209]
.LBB0_151:
	v_pk_mul_f32 v[42:43], v[42:43], s[28:29] op_sel_hi:[1,0]
	v_pk_mul_f32 v[40:41], v[40:41], s[28:29] op_sel_hi:[1,0]
	v_pk_fma_f32 v[26:27], v[26:27], 0.5, v[42:43] op_sel_hi:[1,0,1]
	v_pk_fma_f32 v[24:25], v[24:25], 0.5, v[40:41] op_sel_hi:[1,0,1]
	v_cvt_pk_bf16_f32 v41, v26, v27
	v_cvt_pk_bf16_f32 v40, v24, v25
	global_store_dwordx2 v[34:35], v[40:41], off offset:32
	s_and_b64 vcc, exec, s[6:7]
	s_waitcnt vmcnt(3)
	v_lshlrev_b32_e32 v40, 16, v222
	v_and_b32_e32 v41, 0xffff0000, v222
	v_lshlrev_b32_e32 v42, 16, v223
	v_and_b32_e32 v43, 0xffff0000, v223
	s_cbranch_vccnz .LBB0_153
	v_sub_f32_e32 v41, v41, v36
	v_sub_f32_e32 v40, v40, v36
	v_sub_f32_e32 v43, v43, v36
	v_sub_f32_e32 v42, v42, v36
	v_pk_mul_f32 v[48:49], v[38:39], v[40:41]
	v_mov_b32_e32 v40, v38
	v_mov_b32_e32 v41, v38
	v_pk_mul_f32 v[50:51], v[40:41], v[42:43]
	v_pk_fma_f32 v[42:43], v[50:51], v[174:175], v[214:215]
	v_pk_fma_f32 v[40:41], v[48:49], v[172:173], v[212:213]
.LBB0_153:
	v_pk_mul_f32 v[42:43], v[42:43], s[28:29] op_sel_hi:[1,0]
	v_pk_mul_f32 v[40:41], v[40:41], s[28:29] op_sel_hi:[1,0]
	v_pk_fma_f32 v[22:23], v[22:23], 0.5, v[42:43] op_sel_hi:[1,0,1]
	v_pk_fma_f32 v[20:21], v[20:21], 0.5, v[40:41] op_sel_hi:[1,0,1]
	v_cvt_pk_bf16_f32 v41, v22, v23
	v_cvt_pk_bf16_f32 v40, v20, v21
	global_store_dwordx2 v[34:35], v[40:41], off offset:256
	s_and_b64 vcc, exec, s[6:7]
	s_waitcnt vmcnt(3)
	v_lshlrev_b32_e32 v40, 16, v224
	v_and_b32_e32 v41, 0xffff0000, v224
	v_lshlrev_b32_e32 v42, 16, v225
	v_and_b32_e32 v43, 0xffff0000, v225
	s_cbranch_vccnz .LBB0_155
	v_sub_f32_e32 v43, v43, v36
	v_sub_f32_e32 v42, v42, v36
	v_sub_f32_e32 v37, v41, v36
	v_sub_f32_e32 v36, v40, v36
	v_pk_mul_f32 v[44:45], v[38:39], v[36:37]
	v_mov_b32_e32 v39, v38
	v_pk_mul_f32 v[46:47], v[38:39], v[42:43]
	v_pk_fma_f32 v[42:43], v[46:47], v[178:179], v[218:219]
	v_pk_fma_f32 v[40:41], v[44:45], v[176:177], v[216:217]

; __device__ __forceinline__ unsigned pk2(float lo, float hi) { const f32x2_t v = {lo, hi}; const bf16x2_t b = __builtin_convertvector(v, bf16x2_t); return __builtin_bit_cast(unsigned, b); }
; __device__ __forceinline__ float bflo(unsigned w) { return __uint_as_float(w << 16); }
; __device__ __forceinline__ float bfhi(unsigned w) { return __uint_as_float(w & 0xffff0000u); }
;     __device__ __forceinline__ void operator()(const f32x4 (&acc)[2][2][4][2], const pg8::Unit& u, int wr, int wc, int fr, int fq) const {
;     ...
;                 const int row = row0 + ai * 128 + m * 16; float mu, rstd; row_stats(stats_prev, row, mu, rstd);
;                 float s = 0.f, q = 0.f;
; #pragma unroll
;                 for (int bj = 0; bj < 2; ++bj)
; #pragma unroll
;                     for (int n = 0; n < 2; ++n) {
;                         const int col = col0 + bj * 128 + n * 16;
;                         const u32x2 rb = *(const u32x2*)(YB + (size_t)row * D_ + col);
;                         f32x4 r = (f32x4){bflo(rb.x), bfhi(rb.x), bflo(rb.y), bfhi(rb.y)};
;                         if (stats_prev) { const f32x4 g4 = *(const f32x4*)(lng + col), b4 = *(const f32x4*)(lnb + col); r = (r - mu) * rstd * g4 + b4; }
;                         const f32x4 y = r * ALPHA_ + acc[ai][bj][m][n] * coef;
;                         if (Yout) *(f32x4*)(Yout + (size_t)row * D_ + col) = y;
;                         else { u32x2 w; w.x = pk2(y[0], y[1]); w.y = pk2(y[2], y[3]); *(u32x2*)(YB + (size_t)row * D_ + col) = w; }
;                         s += (y[0] + y[1]) + (y[2] + y[3]); q += (y[0] * y[0] + y[1] * y[1]) + (y[2] * y[2] + y[3] * y[3]);
;                     }
.LBB0_160:
	s_waitcnt lgkmcnt(0)
	v_lshlrev_b64 v[18:19], 11, v[16:17]
	v_lshl_add_u64 v[18:19], s[16:17], 0, v[18:19]
	v_lshl_add_u64 v[18:19], v[140:141], 1, v[18:19]
	global_load_dwordx2 v[26:27], v[18:19], off
	global_load_dwordx2 v[220:221], v[18:19], off offset:32
	global_load_dwordx2 v[222:223], v[18:19], off offset:256
	global_load_dwordx2 v[224:225], v[18:19], off offset:288
	v_mov_b32_e32 v23, v22
	s_and_b64 vcc, exec, s[6:7]
	s_waitcnt vmcnt(3)
	v_lshlrev_b32_e32 v24, 16, v26
	v_and_b32_e32 v25, 0xffff0000, v26
	v_lshlrev_b32_e32 v26, 16, v27
	v_and_b32_e32 v27, 0xffff0000, v27
	s_cbranch_vccnz .LBB0_162
	v_sub_f32_e32 v25, v25, v20
	v_sub_f32_e32 v24, v24, v20
	v_sub_f32_e32 v27, v27, v20
	v_sub_f32_e32 v26, v26, v20
	v_pk_mul_f32 v[32:33], v[22:23], v[24:25]
	v_mov_b32_e32 v24, v22
	v_mov_b32_e32 v25, v22
	v_pk_mul_f32 v[34:35], v[24:25], v[26:27]
	v_pk_fma_f32 v[26:27], v[34:35], v[166:167], v[206:207]
	v_pk_fma_f32 v[24:25], v[32:33], v[164:165], v[204:205]
.LBB0_162:
	s_mov_b32 s28, 0x3fb504f3
	v_pk_mul_f32 v[26:27], v[26:27], s[28:29] op_sel_hi:[1,0]
	v_pk_mul_f32 v[24:25], v[24:25], s[28:29] op_sel_hi:[1,0]
	v_pk_fma_f32 v[14:15], v[14:15], 0.5, v[26:27] op_sel_hi:[1,0,1]
	v_pk_fma_f32 v[12:13], v[12:13], 0.5, v[24:25] op_sel_hi:[1,0,1]
	v_cvt_pk_bf16_f32 v25, v14, v15
	v_cvt_pk_bf16_f32 v24, v12, v13
	global_store_dwordx2 v[18:19], v[24:25], off
	s_and_b64 vcc, exec, s[6:7]
	s_waitcnt vmcnt(3)
	v_lshlrev_b32_e32 v24, 16, v220
	v_and_b32_e32 v25, 0xffff0000, v220
	v_lshlrev_b32_e32 v26, 16, v221
	v_and_b32_e32 v27, 0xffff0000, v221
	s_cbranch_vccnz .LBB0_164
	v_sub_f32_e32 v25, v25, v20
	v_sub_f32_e32 v24, v24, v20
	v_sub_f32_e32 v27, v27, v20
	v_sub_f32_e32 v26, v26, v20
	v_pk_mul_f32 v[32:33], v[22:23], v[24:25]
	v_mov_b32_e32 v24, v22
	v_mov_b32_e32 v25, v22
	v_pk_mul_f32 v[34:35], v[24:25], v[26:27]
	v_pk_fma_f32 v[26:27], v[34:35], v[170:171], v[210:211]
	v_pk_fma_f32 v[24:25], v[32:33], v[168:169], v[208:209]
.LBB0_164:
	v_pk_mul_f32 v[26:27], v[26:27], s[28:29] op_sel_hi:[1,0]
	v_pk_mul_f32 v[24:25], v[24:25], s[28:29] op_sel_hi:[1,0]
	v_pk_fma_f32 v[10:11], v[10:11], 0.5, v[26:27] op_sel_hi:[1,0,1]
	v_pk_fma_f32 v[8:9], v[8:9], 0.5, v[24:25] op_sel_hi:[1,0,1]
	v_cvt_pk_bf16_f32 v25, v10, v11
	v_cvt_pk_bf16_f32 v24, v8, v9
	global_store_dwordx2 v[18:19], v[24:25], off offset:32
	s_and_b64 vcc, exec, s[6:7]
	s_waitcnt vmcnt(3)
	v_lshlrev_b32_e32 v24, 16, v222
	v_and_b32_e32 v25, 0xffff0000, v222
	v_lshlrev_b32_e32 v26, 16, v223
	v_and_b32_e32 v27, 0xffff0000, v223
	s_cbranch_vccnz .LBB0_166
	v_sub_f32_e32 v25, v25, v20
	v_sub_f32_e32 v24, v24, v20
	v_sub_f32_e32 v27, v27, v20
	v_sub_f32_e32 v26, v26, v20
	v_pk_mul_f32 v[32:33], v[22:23], v[24:25]
	v_mov_b32_e32 v24, v22
	v_mov_b32_e32 v25, v22
	v_pk_mul_f32 v[34:35], v[24:25], v[26:27]
	v_pk_fma_f32 v[26:27], v[34:35], v[174:175], v[214:215]
	v_pk_fma_f32 v[24:25], v[32:33], v[172:173], v[212:213]
.LBB0_166:
	v_pk_mul_f32 v[26:27], v[26:27], s[28:29] op_sel_hi:[1,0]
	v_pk_mul_f32 v[24:25], v[24:25], s[28:29] op_sel_hi:[1,0]
	v_pk_fma_f32 v[6:7], v[6:7], 0.5, v[26:27] op_sel_hi:[1,0,1]
	v_pk_fma_f32 v[4:5], v[4:5], 0.5, v[24:25] op_sel_hi:[1,0,1]
	v_cvt_pk_bf16_f32 v25, v6, v7
	v_cvt_pk_bf16_f32 v24, v4, v5
	global_store_dwordx2 v[18:19], v[24:25], off offset:256
	s_and_b64 vcc, exec, s[6:7]
	s_waitcnt vmcnt(3)
	v_lshlrev_b32_e32 v24, 16, v224
	v_and_b32_e32 v25, 0xffff0000, v224
	v_lshlrev_b32_e32 v26, 16, v225
	v_and_b32_e32 v27, 0xffff0000, v225
	s_cbranch_vccnz .LBB0_168
	v_sub_f32_e32 v27, v27, v20
	v_sub_f32_e32 v26, v26, v20
	v_sub_f32_e32 v21, v25, v20
	v_sub_f32_e32 v20, v24, v20
	v_pk_mul_f32 v[28:29], v[22:23], v[20:21]
	v_mov_b32_e32 v23, v22
	v_pk_mul_f32 v[30:31], v[22:23], v[26:27]
	v_pk_fma_f32 v[26:27], v[30:31], v[178:179], v[218:219]
	v_pk_fma_f32 v[24:25], v[28:29], v[176:177], v[216:217]

; __device__ __forceinline__ unsigned pk2(float lo, float hi) { const f32x2_t v = {lo, hi}; const bf16x2_t b = __builtin_convertvector(v, bf16x2_t); return __builtin_bit_cast(unsigned, b); }
; __device__ __forceinline__ float bflo(unsigned w) { return __uint_as_float(w << 16); }
; __device__ __forceinline__ float bfhi(unsigned w) { return __uint_as_float(w & 0xffff0000u); }
;     __device__ __forceinline__ void operator()(const f32x4 (&acc)[2][2][4][2], const pg8::Unit& u, int wr, int wc, int fr, int fq) const {
;     ...
;                 const int row = row0 + ai * 128 + m * 16; float mu, rstd; row_stats(stats_prev, row, mu, rstd);
;                 float s = 0.f, q = 0.f;
; #pragma unroll
;                 for (int bj = 0; bj < 2; ++bj)
; #pragma unroll
;                     for (int n = 0; n < 2; ++n) {
;                         const int col = col0 + bj * 128 + n * 16;
;                         const u32x2 rb = *(const u32x2*)(YB + (size_t)row * D_ + col);
;                         f32x4 r = (f32x4){bflo(rb.x), bfhi(rb.x), bflo(rb.y), bfhi(rb.y)};
;                         if (stats_prev) { const f32x4 g4 = *(const f32x4*)(lng + col), b4 = *(const f32x4*)(lnb + col); r = (r - mu) * rstd * g4 + b4; }
;                         const f32x4 y = r * ALPHA_ + acc[ai][bj][m][n] * coef;
;                         if (Yout) *(f32x4*)(Yout + (size_t)row * D_ + col) = y;
;                         else { u32x2 w; w.x = pk2(y[0], y[1]); w.y = pk2(y[2], y[3]); *(u32x2*)(YB + (size_t)row * D_ + col) = w; }
;                         s += (y[0] + y[1]) + (y[2] + y[3]); q += (y[0] * y[0] + y[1] * y[1]) + (y[2] * y[2] + y[3] * y[3]);
;                     }
.LBB0_238:
	v_lshl_or_b32 v140, s26, 8, v154
	v_lshlrev_b64 v[134:135], 11, v[138:139]
	v_lshl_add_u64 v[134:135], s[10:11], 0, v[134:135]
	v_ashrrev_i32_e32 v141, 31, v140
	v_lshl_add_u64 v[142:143], v[140:141], 1, v[134:135]
	global_load_dwordx2 v[136:137], v[142:143], off
	global_load_dwordx2 v[220:221], v[142:143], off offset:32
	global_load_dwordx2 v[222:223], v[142:143], off offset:256
	global_load_dwordx2 v[224:225], v[142:143], off offset:288
	v_lshlrev_b64 v[156:157], 2, v[140:141]
	v_readlane_b32 s56, v254, 36
	v_mov_b32_e32 v147, v146
	s_and_b64 vcc, exec, s[6:7]
	v_lshl_add_u64 v[134:135], s[12:13], 0, v[156:157]
	v_readlane_b32 s57, v254, 37
	s_waitcnt vmcnt(3)
	v_lshlrev_b32_e32 v148, 16, v136
	v_and_b32_e32 v149, 0xffff0000, v136
	v_lshlrev_b32_e32 v150, 16, v137
	v_and_b32_e32 v151, 0xffff0000, v137
	v_lshl_add_u64 v[136:137], s[14:15], 0, v[156:157]
	s_cbranch_vccnz .LBB0_240
	v_sub_f32_e32 v149, v149, v144
	v_sub_f32_e32 v148, v148, v144
	v_sub_f32_e32 v151, v151, v144
	v_sub_f32_e32 v150, v150, v144
	v_pk_mul_f32 v[160:161], v[146:147], v[148:149]
	v_mov_b32_e32 v148, v146
	v_mov_b32_e32 v149, v146
	v_pk_mul_f32 v[162:163], v[148:149], v[150:151]
	global_load_dwordx4 v[164:167], v[134:135], off
	global_load_dwordx4 v[204:207], v[136:137], off
	global_load_dwordx4 v[168:171], v[134:135], off offset:64
	global_load_dwordx4 v[208:211], v[136:137], off offset:64
	global_load_dwordx4 v[172:175], v[134:135], off offset:512
	global_load_dwordx4 v[212:215], v[136:137], off offset:512
	global_load_dwordx4 v[176:179], v[134:135], off offset:576
	global_load_dwordx4 v[216:219], v[136:137], off offset:576
	s_waitcnt vmcnt(0)
	v_pk_fma_f32 v[150:151], v[162:163], v[166:167], v[206:207]
	v_pk_fma_f32 v[148:149], v[160:161], v[164:165], v[204:205]
.LBB0_240:
	s_mov_b32 s28, 0x3fb504f3
	v_pk_fma_f32 v[126:127], v[150:151], s[28:29], v[126:127] op_sel_hi:[1,0,1]
	v_pk_fma_f32 v[124:125], v[148:149], s[28:29], v[124:125] op_sel_hi:[1,0,1]
	v_cvt_pk_bf16_f32 v149, v126, v127
	v_cvt_pk_bf16_f32 v148, v124, v125
	global_store_dwordx2 v[142:143], v[148:149], off
	s_and_b64 vcc, exec, s[6:7]
	s_waitcnt vmcnt(3)
	v_lshlrev_b32_e32 v148, 16, v220
	v_and_b32_e32 v149, 0xffff0000, v220
	v_lshlrev_b32_e32 v150, 16, v221
	v_and_b32_e32 v151, 0xffff0000, v221
	s_cbranch_vccnz .LBB0_242
	v_sub_f32_e32 v149, v149, v144
	v_sub_f32_e32 v148, v148, v144
	v_sub_f32_e32 v151, v151, v144
	v_sub_f32_e32 v150, v150, v144
	v_pk_mul_f32 v[160:161], v[146:147], v[148:149]
	v_mov_b32_e32 v148, v146
	v_mov_b32_e32 v149, v146
	v_pk_mul_f32 v[162:163], v[148:149], v[150:151]
	v_pk_fma_f32 v[150:151], v[162:163], v[170:171], v[210:211]
	v_pk_fma_f32 v[148:149], v[160:161], v[168:169], v[208:209]
.LBB0_242:
	v_pk_fma_f32 v[122:123], v[150:151], s[28:29], v[122:123] op_sel_hi:[1,0,1]
	v_pk_fma_f32 v[120:121], v[148:149], s[28:29], v[120:121] op_sel_hi:[1,0,1]
	v_cvt_pk_bf16_f32 v149, v122, v123
	v_cvt_pk_bf16_f32 v148, v120, v121
	global_store_dwordx2 v[142:143], v[148:149], off offset:32
	s_and_b64 vcc, exec, s[6:7]
	s_waitcnt vmcnt(3)
	v_lshlrev_b32_e32 v148, 16, v222
	v_and_b32_e32 v149, 0xffff0000, v222
	v_lshlrev_b32_e32 v150, 16, v223
	v_and_b32_e32 v151, 0xffff0000, v223
	s_cbranch_vccnz .LBB0_244
	v_sub_f32_e32 v149, v149, v144
	v_sub_f32_e32 v148, v148, v144
	v_sub_f32_e32 v151, v151, v144
	v_sub_f32_e32 v150, v150, v144
	v_pk_mul_f32 v[160:161], v[146:147], v[148:149]
	v_mov_b32_e32 v148, v146
	v_mov_b32_e32 v149, v146
	v_pk_mul_f32 v[162:163], v[148:149], v[150:151]
	v_pk_fma_f32 v[150:151], v[162:163], v[174:175], v[214:215]
	v_pk_fma_f32 v[148:149], v[160:161], v[172:173], v[212:213]
.LBB0_244:
	v_pk_fma_f32 v[118:119], v[150:151], s[28:29], v[118:119] op_sel_hi:[1,0,1]
	v_pk_fma_f32 v[116:117], v[148:149], s[28:29], v[116:117] op_sel_hi:[1,0,1]
	v_cvt_pk_bf16_f32 v149, v118, v119
	v_cvt_pk_bf16_f32 v148, v116, v117
	global_store_dwordx2 v[142:143], v[148:149], off offset:256
	s_and_b64 vcc, exec, s[6:7]
	s_waitcnt vmcnt(3)
	v_lshlrev_b32_e32 v148, 16, v224
	v_and_b32_e32 v149, 0xffff0000, v224
	v_lshlrev_b32_e32 v150, 16, v225
	v_and_b32_e32 v151, 0xffff0000, v225
	s_cbranch_vccnz .LBB0_246
	v_sub_f32_e32 v151, v151, v144
	v_sub_f32_e32 v150, v150, v144
	v_sub_f32_e32 v145, v149, v144
	v_sub_f32_e32 v144, v148, v144
	v_pk_mul_f32 v[156:157], v[146:147], v[144:145]
	v_mov_b32_e32 v147, v146
	v_pk_mul_f32 v[158:159], v[146:147], v[150:151]
	v_pk_fma_f32 v[150:151], v[158:159], v[178:179], v[218:219]
	v_pk_fma_f32 v[148:149], v[156:157], v[176:177], v[216:217]

; __device__ __forceinline__ unsigned pk2(float lo, float hi) { const f32x2_t v = {lo, hi}; const bf16x2_t b = __builtin_convertvector(v, bf16x2_t); return __builtin_bit_cast(unsigned, b); }
; __device__ __forceinline__ float bflo(unsigned w) { return __uint_as_float(w << 16); }
; __device__ __forceinline__ float bfhi(unsigned w) { return __uint_as_float(w & 0xffff0000u); }
;     __device__ __forceinline__ void operator()(const f32x4 (&acc)[2][2][4][2], const pg8::Unit& u, int wr, int wc, int fr, int fq) const {
;     ...
;                 const int row = row0 + ai * 128 + m * 16; float mu, rstd; row_stats(stats_prev, row, mu, rstd);
;                 float s = 0.f, q = 0.f;
; #pragma unroll
;                 for (int bj = 0; bj < 2; ++bj)
; #pragma unroll
;                     for (int n = 0; n < 2; ++n) {
;                         const int col = col0 + bj * 128 + n * 16;
;                         const u32x2 rb = *(const u32x2*)(YB + (size_t)row * D_ + col);
;                         f32x4 r = (f32x4){bflo(rb.x), bfhi(rb.x), bflo(rb.y), bfhi(rb.y)};
;                         if (stats_prev) { const f32x4 g4 = *(const f32x4*)(lng + col), b4 = *(const f32x4*)(lnb + col); r = (r - mu) * rstd * g4 + b4; }
;                         const f32x4 y = r * ALPHA_ + acc[ai][bj][m][n] * coef;
;                         if (Yout) *(f32x4*)(Yout + (size_t)row * D_ + col) = y;
;                         else { u32x2 w; w.x = pk2(y[0], y[1]); w.y = pk2(y[2], y[3]); *(u32x2*)(YB + (size_t)row * D_ + col) = w; }
;                         s += (y[0] + y[1]) + (y[2] + y[3]); q += (y[0] * y[0] + y[1] * y[1]) + (y[2] * y[2] + y[3] * y[3]);
;                     }
.LBB0_251:
	s_waitcnt lgkmcnt(0)
	v_lshlrev_b64 v[114:115], 11, v[112:113]
	v_lshl_add_u64 v[114:115], s[10:11], 0, v[114:115]
	v_lshl_add_u64 v[114:115], v[140:141], 1, v[114:115]
	global_load_dwordx2 v[122:123], v[114:115], off
	global_load_dwordx2 v[220:221], v[114:115], off offset:32
	global_load_dwordx2 v[222:223], v[114:115], off offset:256
	global_load_dwordx2 v[224:225], v[114:115], off offset:288
	v_mov_b32_e32 v119, v118
	s_and_b64 vcc, exec, s[6:7]
	s_waitcnt vmcnt(3)
	v_lshlrev_b32_e32 v120, 16, v122
	v_and_b32_e32 v121, 0xffff0000, v122
	v_lshlrev_b32_e32 v122, 16, v123
	v_and_b32_e32 v123, 0xffff0000, v123
	s_cbranch_vccnz .LBB0_253
	v_sub_f32_e32 v121, v121, v116
	v_sub_f32_e32 v120, v120, v116
	v_sub_f32_e32 v123, v123, v116
	v_sub_f32_e32 v122, v122, v116
	v_pk_mul_f32 v[126:127], v[118:119], v[120:121]
	v_mov_b32_e32 v120, v118
	v_mov_b32_e32 v121, v118
	v_pk_mul_f32 v[146:147], v[120:121], v[122:123]
	v_pk_fma_f32 v[122:123], v[146:147], v[166:167], v[206:207]
	v_pk_fma_f32 v[120:121], v[126:127], v[164:165], v[204:205]
.LBB0_253:
	s_mov_b32 s28, 0x3fb504f3
	v_pk_fma_f32 v[110:111], v[122:123], s[28:29], v[110:111] op_sel_hi:[1,0,1]
	v_pk_fma_f32 v[108:109], v[120:121], s[28:29], v[108:109] op_sel_hi:[1,0,1]
	v_cvt_pk_bf16_f32 v121, v110, v111
	v_cvt_pk_bf16_f32 v120, v108, v109
	global_store_dwordx2 v[114:115], v[120:121], off
	s_and_b64 vcc, exec, s[6:7]
	s_waitcnt vmcnt(3)
	v_lshlrev_b32_e32 v120, 16, v220
	v_and_b32_e32 v121, 0xffff0000, v220
	v_lshlrev_b32_e32 v122, 16, v221
	v_and_b32_e32 v123, 0xffff0000, v221
	s_cbranch_vccnz .LBB0_255
	v_sub_f32_e32 v121, v121, v116
	v_sub_f32_e32 v120, v120, v116
	v_sub_f32_e32 v123, v123, v116
	v_sub_f32_e32 v122, v122, v116
	v_pk_mul_f32 v[126:127], v[118:119], v[120:121]
	v_mov_b32_e32 v120, v118
	v_mov_b32_e32 v121, v118
	v_pk_mul_f32 v[146:147], v[120:121], v[122:123]
	v_pk_fma_f32 v[122:123], v[146:147], v[170:171], v[210:211]
	v_pk_fma_f32 v[120:121], v[126:127], v[168:169], v[208:209]
.LBB0_255:
	v_pk_fma_f32 v[106:107], v[122:123], s[28:29], v[106:107] op_sel_hi:[1,0,1]
	v_pk_fma_f32 v[104:105], v[120:121], s[28:29], v[104:105] op_sel_hi:[1,0,1]
	v_cvt_pk_bf16_f32 v121, v106, v107
	v_cvt_pk_bf16_f32 v120, v104, v105
	global_store_dwordx2 v[114:115], v[120:121], off offset:32
	s_and_b64 vcc, exec, s[6:7]
	s_waitcnt vmcnt(3)
	v_lshlrev_b32_e32 v120, 16, v222
	v_and_b32_e32 v121, 0xffff0000, v222
	v_lshlrev_b32_e32 v122, 16, v223
	v_and_b32_e32 v123, 0xffff0000, v223
	s_cbranch_vccnz .LBB0_257
	v_sub_f32_e32 v121, v121, v116
	v_sub_f32_e32 v120, v120, v116
	v_sub_f32_e32 v123, v123, v116
	v_sub_f32_e32 v122, v122, v116
	v_pk_mul_f32 v[126:127], v[118:119], v[120:121]
	v_mov_b32_e32 v120, v118
	v_mov_b32_e32 v121, v118
	v_pk_mul_f32 v[146:147], v[120:121], v[122:123]
	v_pk_fma_f32 v[122:123], v[146:147], v[174:175], v[214:215]
	v_pk_fma_f32 v[120:121], v[126:127], v[172:173], v[212:213]
.LBB0_257:
	v_pk_fma_f32 v[102:103], v[122:123], s[28:29], v[102:103] op_sel_hi:[1,0,1]
	v_pk_fma_f32 v[100:101], v[120:121], s[28:29], v[100:101] op_sel_hi:[1,0,1]
	v_cvt_pk_bf16_f32 v121, v102, v103
	v_cvt_pk_bf16_f32 v120, v100, v101
	global_store_dwordx2 v[114:115], v[120:121], off offset:256
	s_and_b64 vcc, exec, s[6:7]
	s_waitcnt vmcnt(3)
	v_lshlrev_b32_e32 v120, 16, v224
	v_and_b32_e32 v121, 0xffff0000, v224
	v_lshlrev_b32_e32 v122, 16, v225
	v_and_b32_e32 v123, 0xffff0000, v225
	s_cbranch_vccnz .LBB0_259
	v_sub_f32_e32 v123, v123, v116
	v_sub_f32_e32 v122, v122, v116
	v_sub_f32_e32 v117, v121, v116
	v_sub_f32_e32 v116, v120, v116
	v_pk_mul_f32 v[126:127], v[118:119], v[116:117]
	v_mov_b32_e32 v119, v118
	v_pk_mul_f32 v[142:143], v[118:119], v[122:123]
	v_pk_fma_f32 v[122:123], v[142:143], v[178:179], v[218:219]
	v_pk_fma_f32 v[120:121], v[126:127], v[176:177], v[216:217]

; __device__ __forceinline__ unsigned pk2(float lo, float hi) { const f32x2_t v = {lo, hi}; const bf16x2_t b = __builtin_convertvector(v, bf16x2_t); return __builtin_bit_cast(unsigned, b); }
; __device__ __forceinline__ float bflo(unsigned w) { return __uint_as_float(w << 16); }
; __device__ __forceinline__ float bfhi(unsigned w) { return __uint_as_float(w & 0xffff0000u); }
;     __device__ __forceinline__ void operator()(const f32x4 (&acc)[2][2][4][2], const pg8::Unit& u, int wr, int wc, int fr, int fq) const {
;     ...
;                 const int row = row0 + ai * 128 + m * 16; float mu, rstd; row_stats(stats_prev, row, mu, rstd);
;                 float s = 0.f, q = 0.f;
; #pragma unroll
;                 for (int bj = 0; bj < 2; ++bj)
; #pragma unroll
;                     for (int n = 0; n < 2; ++n) {
;                         const int col = col0 + bj * 128 + n * 16;
;                         const u32x2 rb = *(const u32x2*)(YB + (size_t)row * D_ + col);
;                         f32x4 r = (f32x4){bflo(rb.x), bfhi(rb.x), bflo(rb.y), bfhi(rb.y)};
;                         if (stats_prev) { const f32x4 g4 = *(const f32x4*)(lng + col), b4 = *(const f32x4*)(lnb + col); r = (r - mu) * rstd * g4 + b4; }
;                         const f32x4 y = r * ALPHA_ + acc[ai][bj][m][n] * coef;
;                         if (Yout) *(f32x4*)(Yout + (size_t)row * D_ + col) = y;
;                         else { u32x2 w; w.x = pk2(y[0], y[1]); w.y = pk2(y[2], y[3]); *(u32x2*)(YB + (size_t)row * D_ + col) = w; }
;                         s += (y[0] + y[1]) + (y[2] + y[3]); q += (y[0] * y[0] + y[1] * y[1]) + (y[2] * y[2] + y[3] * y[3]);
;                     }
.LBB0_264:
	s_waitcnt lgkmcnt(0)
	v_lshlrev_b64 v[98:99], 11, v[96:97]
	v_lshl_add_u64 v[98:99], s[10:11], 0, v[98:99]
	v_lshl_add_u64 v[98:99], v[140:141], 1, v[98:99]
	global_load_dwordx2 v[106:107], v[98:99], off
	global_load_dwordx2 v[220:221], v[98:99], off offset:32
	global_load_dwordx2 v[222:223], v[98:99], off offset:256
	global_load_dwordx2 v[224:225], v[98:99], off offset:288
	v_mov_b32_e32 v103, v102
	s_and_b64 vcc, exec, s[6:7]
	s_waitcnt vmcnt(3)
	v_lshlrev_b32_e32 v104, 16, v106
	v_and_b32_e32 v105, 0xffff0000, v106
	v_lshlrev_b32_e32 v106, 16, v107
	v_and_b32_e32 v107, 0xffff0000, v107
	s_cbranch_vccnz .LBB0_266
	v_sub_f32_e32 v105, v105, v100
	v_sub_f32_e32 v104, v104, v100
	v_sub_f32_e32 v107, v107, v100
	v_sub_f32_e32 v106, v106, v100
	v_pk_mul_f32 v[112:113], v[102:103], v[104:105]
	v_mov_b32_e32 v104, v102
	v_mov_b32_e32 v105, v102
	v_pk_mul_f32 v[114:115], v[104:105], v[106:107]
	v_pk_fma_f32 v[106:107], v[114:115], v[166:167], v[206:207]
	v_pk_fma_f32 v[104:105], v[112:113], v[164:165], v[204:205]
.LBB0_266:
	s_mov_b32 s28, 0x3fb504f3
	v_pk_fma_f32 v[94:95], v[106:107], s[28:29], v[94:95] op_sel_hi:[1,0,1]
	v_pk_fma_f32 v[92:93], v[104:105], s[28:29], v[92:93] op_sel_hi:[1,0,1]
	v_cvt_pk_bf16_f32 v105, v94, v95
	v_cvt_pk_bf16_f32 v104, v92, v93
	global_store_dwordx2 v[98:99], v[104:105], off
	s_and_b64 vcc, exec, s[6:7]
	s_waitcnt vmcnt(3)
	v_lshlrev_b32_e32 v104, 16, v220
	v_and_b32_e32 v105, 0xffff0000, v220
	v_lshlrev_b32_e32 v106, 16, v221
	v_and_b32_e32 v107, 0xffff0000, v221
	s_cbranch_vccnz .LBB0_268
	v_sub_f32_e32 v105, v105, v100
	v_sub_f32_e32 v104, v104, v100
	v_sub_f32_e32 v107, v107, v100
	v_sub_f32_e32 v106, v106, v100
	v_pk_mul_f32 v[112:113], v[102:103], v[104:105]
	v_mov_b32_e32 v104, v102
	v_mov_b32_e32 v105, v102
	v_pk_mul_f32 v[114:115], v[104:105], v[106:107]
	v_pk_fma_f32 v[106:107], v[114:115], v[170:171], v[210:211]
	v_pk_fma_f32 v[104:105], v[112:113], v[168:169], v[208:209]
.LBB0_268:
	v_pk_fma_f32 v[90:91], v[106:107], s[28:29], v[90:91] op_sel_hi:[1,0,1]
	v_pk_fma_f32 v[88:89], v[104:105], s[28:29], v[88:89] op_sel_hi:[1,0,1]
	v_cvt_pk_bf16_f32 v105, v90, v91
	v_cvt_pk_bf16_f32 v104, v88, v89
	global_store_dwordx2 v[98:99], v[104:105], off offset:32
	s_and_b64 vcc, exec, s[6:7]
	s_waitcnt vmcnt(3)
	v_lshlrev_b32_e32 v104, 16, v222
	v_and_b32_e32 v105, 0xffff0000, v222
	v_lshlrev_b32_e32 v106, 16, v223
	v_and_b32_e32 v107, 0xffff0000, v223
	s_cbranch_vccnz .LBB0_270
	v_sub_f32_e32 v105, v105, v100
	v_sub_f32_e32 v104, v104, v100
	v_sub_f32_e32 v107, v107, v100
	v_sub_f32_e32 v106, v106, v100
	v_pk_mul_f32 v[112:113], v[102:103], v[104:105]
	v_mov_b32_e32 v104, v102
	v_mov_b32_e32 v105, v102
	v_pk_mul_f32 v[114:115], v[104:105], v[106:107]
	v_pk_fma_f32 v[106:107], v[114:115], v[174:175], v[214:215]
	v_pk_fma_f32 v[104:105], v[112:113], v[172:173], v[212:213]
.LBB0_270:
	v_pk_fma_f32 v[86:87], v[106:107], s[28:29], v[86:87] op_sel_hi:[1,0,1]
	v_pk_fma_f32 v[84:85], v[104:105], s[28:29], v[84:85] op_sel_hi:[1,0,1]
	v_cvt_pk_bf16_f32 v105, v86, v87
	v_cvt_pk_bf16_f32 v104, v84, v85
	global_store_dwordx2 v[98:99], v[104:105], off offset:256
	s_and_b64 vcc, exec, s[6:7]
	s_waitcnt vmcnt(3)
	v_lshlrev_b32_e32 v104, 16, v224
	v_and_b32_e32 v105, 0xffff0000, v224
	v_lshlrev_b32_e32 v106, 16, v225
	v_and_b32_e32 v107, 0xffff0000, v225
	s_cbranch_vccnz .LBB0_272
	v_sub_f32_e32 v107, v107, v100
	v_sub_f32_e32 v106, v106, v100
	v_sub_f32_e32 v101, v105, v100
	v_sub_f32_e32 v100, v104, v100
	v_pk_mul_f32 v[108:109], v[102:103], v[100:101]
	v_mov_b32_e32 v103, v102
	v_pk_mul_f32 v[110:111], v[102:103], v[106:107]
	v_pk_fma_f32 v[106:107], v[110:111], v[178:179], v[218:219]
	v_pk_fma_f32 v[104:105], v[108:109], v[176:177], v[216:217]

; __device__ __forceinline__ unsigned pk2(float lo, float hi) { const f32x2_t v = {lo, hi}; const bf16x2_t b = __builtin_convertvector(v, bf16x2_t); return __builtin_bit_cast(unsigned, b); }
; __device__ __forceinline__ float bflo(unsigned w) { return __uint_as_float(w << 16); }
; __device__ __forceinline__ float bfhi(unsigned w) { return __uint_as_float(w & 0xffff0000u); }
;     __device__ __forceinline__ void operator()(const f32x4 (&acc)[2][2][4][2], const pg8::Unit& u, int wr, int wc, int fr, int fq) const {
;     ...
;                 const int row = row0 + ai * 128 + m * 16; float mu, rstd; row_stats(stats_prev, row, mu, rstd);
;                 float s = 0.f, q = 0.f;
; #pragma unroll
;                 for (int bj = 0; bj < 2; ++bj)
; #pragma unroll
;                     for (int n = 0; n < 2; ++n) {
;                         const int col = col0 + bj * 128 + n * 16;
;                         const u32x2 rb = *(const u32x2*)(YB + (size_t)row * D_ + col);
;                         f32x4 r = (f32x4){bflo(rb.x), bfhi(rb.x), bflo(rb.y), bfhi(rb.y)};
;                         if (stats_prev) { const f32x4 g4 = *(const f32x4*)(lng + col), b4 = *(const f32x4*)(lnb + col); r = (r - mu) * rstd * g4 + b4; }
;                         const f32x4 y = r * ALPHA_ + acc[ai][bj][m][n] * coef;
;                         if (Yout) *(f32x4*)(Yout + (size_t)row * D_ + col) = y;
;                         else { u32x2 w; w.x = pk2(y[0], y[1]); w.y = pk2(y[2], y[3]); *(u32x2*)(YB + (size_t)row * D_ + col) = w; }
;                         s += (y[0] + y[1]) + (y[2] + y[3]); q += (y[0] * y[0] + y[1] * y[1]) + (y[2] * y[2] + y[3] * y[3]);
;                     }
.LBB0_277:
	s_waitcnt lgkmcnt(0)
	v_lshlrev_b64 v[82:83], 11, v[80:81]
	v_lshl_add_u64 v[82:83], s[10:11], 0, v[82:83]
	v_lshl_add_u64 v[82:83], v[140:141], 1, v[82:83]
	global_load_dwordx2 v[90:91], v[82:83], off
	global_load_dwordx2 v[220:221], v[82:83], off offset:32
	global_load_dwordx2 v[222:223], v[82:83], off offset:256
	global_load_dwordx2 v[224:225], v[82:83], off offset:288
	v_mov_b32_e32 v87, v86
	s_and_b64 vcc, exec, s[6:7]
	s_waitcnt vmcnt(3)
	v_lshlrev_b32_e32 v88, 16, v90
	v_and_b32_e32 v89, 0xffff0000, v90
	v_lshlrev_b32_e32 v90, 16, v91
	v_and_b32_e32 v91, 0xffff0000, v91
	s_cbranch_vccnz .LBB0_279
	v_sub_f32_e32 v89, v89, v84
	v_sub_f32_e32 v88, v88, v84
	v_sub_f32_e32 v91, v91, v84
	v_sub_f32_e32 v90, v90, v84
	v_pk_mul_f32 v[96:97], v[86:87], v[88:89]
	v_mov_b32_e32 v88, v86
	v_mov_b32_e32 v89, v86
	v_pk_mul_f32 v[98:99], v[88:89], v[90:91]
	v_pk_fma_f32 v[90:91], v[98:99], v[166:167], v[206:207]
	v_pk_fma_f32 v[88:89], v[96:97], v[164:165], v[204:205]
.LBB0_279:
	s_mov_b32 s28, 0x3fb504f3
	v_pk_fma_f32 v[78:79], v[90:91], s[28:29], v[78:79] op_sel_hi:[1,0,1]
	v_pk_fma_f32 v[76:77], v[88:89], s[28:29], v[76:77] op_sel_hi:[1,0,1]
	v_cvt_pk_bf16_f32 v89, v78, v79
	v_cvt_pk_bf16_f32 v88, v76, v77
	global_store_dwordx2 v[82:83], v[88:89], off
	s_and_b64 vcc, exec, s[6:7]
	s_waitcnt vmcnt(3)
	v_lshlrev_b32_e32 v88, 16, v220
	v_and_b32_e32 v89, 0xffff0000, v220
	v_lshlrev_b32_e32 v90, 16, v221
	v_and_b32_e32 v91, 0xffff0000, v221
	s_cbranch_vccnz .LBB0_281
	v_sub_f32_e32 v89, v89, v84
	v_sub_f32_e32 v88, v88, v84
	v_sub_f32_e32 v91, v91, v84
	v_sub_f32_e32 v90, v90, v84
	v_pk_mul_f32 v[96:97], v[86:87], v[88:89]
	v_mov_b32_e32 v88, v86
	v_mov_b32_e32 v89, v86
	v_pk_mul_f32 v[98:99], v[88:89], v[90:91]
	v_pk_fma_f32 v[90:91], v[98:99], v[170:171], v[210:211]
	v_pk_fma_f32 v[88:89], v[96:97], v[168:169], v[208:209]
.LBB0_281:
	v_pk_fma_f32 v[74:75], v[90:91], s[28:29], v[74:75] op_sel_hi:[1,0,1]
	v_pk_fma_f32 v[72:73], v[88:89], s[28:29], v[72:73] op_sel_hi:[1,0,1]
	v_cvt_pk_bf16_f32 v89, v74, v75
	v_cvt_pk_bf16_f32 v88, v72, v73
	global_store_dwordx2 v[82:83], v[88:89], off offset:32
	s_and_b64 vcc, exec, s[6:7]
	s_waitcnt vmcnt(3)
	v_lshlrev_b32_e32 v88, 16, v222
	v_and_b32_e32 v89, 0xffff0000, v222
	v_lshlrev_b32_e32 v90, 16, v223
	v_and_b32_e32 v91, 0xffff0000, v223
	s_cbranch_vccnz .LBB0_283
	v_sub_f32_e32 v89, v89, v84
	v_sub_f32_e32 v88, v88, v84
	v_sub_f32_e32 v91, v91, v84
	v_sub_f32_e32 v90, v90, v84
	v_pk_mul_f32 v[96:97], v[86:87], v[88:89]
	v_mov_b32_e32 v88, v86
	v_mov_b32_e32 v89, v86
	v_pk_mul_f32 v[98:99], v[88:89], v[90:91]
	v_pk_fma_f32 v[90:91], v[98:99], v[174:175], v[214:215]
	v_pk_fma_f32 v[88:89], v[96:97], v[172:173], v[212:213]
.LBB0_283:
	v_pk_fma_f32 v[70:71], v[90:91], s[28:29], v[70:71] op_sel_hi:[1,0,1]
	v_pk_fma_f32 v[68:69], v[88:89], s[28:29], v[68:69] op_sel_hi:[1,0,1]
	v_cvt_pk_bf16_f32 v89, v70, v71
	v_cvt_pk_bf16_f32 v88, v68, v69
	global_store_dwordx2 v[82:83], v[88:89], off offset:256
	s_and_b64 vcc, exec, s[6:7]
	s_waitcnt vmcnt(3)
	v_lshlrev_b32_e32 v88, 16, v224
	v_and_b32_e32 v89, 0xffff0000, v224
	v_lshlrev_b32_e32 v90, 16, v225
	v_and_b32_e32 v91, 0xffff0000, v225
	s_cbranch_vccnz .LBB0_285
	v_sub_f32_e32 v91, v91, v84
	v_sub_f32_e32 v90, v90, v84
	v_sub_f32_e32 v85, v89, v84
	v_sub_f32_e32 v84, v88, v84
	v_pk_mul_f32 v[92:93], v[86:87], v[84:85]
	v_mov_b32_e32 v87, v86
	v_pk_mul_f32 v[94:95], v[86:87], v[90:91]
	v_pk_fma_f32 v[90:91], v[94:95], v[178:179], v[218:219]
	v_pk_fma_f32 v[88:89], v[92:93], v[176:177], v[216:217]

; __device__ __forceinline__ unsigned pk2(float lo, float hi) { const f32x2_t v = {lo, hi}; const bf16x2_t b = __builtin_convertvector(v, bf16x2_t); return __builtin_bit_cast(unsigned, b); }
; __device__ __forceinline__ float bflo(unsigned w) { return __uint_as_float(w << 16); }
; __device__ __forceinline__ float bfhi(unsigned w) { return __uint_as_float(w & 0xffff0000u); }
;     __device__ __forceinline__ void operator()(const f32x4 (&acc)[2][2][4][2], const pg8::Unit& u, int wr, int wc, int fr, int fq) const {
;     ...
;                 const int row = row0 + ai * 128 + m * 16; float mu, rstd; row_stats(stats_prev, row, mu, rstd);
;                 float s = 0.f, q = 0.f;
; #pragma unroll
;                 for (int bj = 0; bj < 2; ++bj)
; #pragma unroll
;                     for (int n = 0; n < 2; ++n) {
;                         const int col = col0 + bj * 128 + n * 16;
;                         const u32x2 rb = *(const u32x2*)(YB + (size_t)row * D_ + col);
;                         f32x4 r = (f32x4){bflo(rb.x), bfhi(rb.x), bflo(rb.y), bfhi(rb.y)};
;                         if (stats_prev) { const f32x4 g4 = *(const f32x4*)(lng + col), b4 = *(const f32x4*)(lnb + col); r = (r - mu) * rstd * g4 + b4; }
;                         const f32x4 y = r * ALPHA_ + acc[ai][bj][m][n] * coef;
;                         if (Yout) *(f32x4*)(Yout + (size_t)row * D_ + col) = y;
;                         else { u32x2 w; w.x = pk2(y[0], y[1]); w.y = pk2(y[2], y[3]); *(u32x2*)(YB + (size_t)row * D_ + col) = w; }
;                         s += (y[0] + y[1]) + (y[2] + y[3]); q += (y[0] * y[0] + y[1] * y[1]) + (y[2] * y[2] + y[3] * y[3]);
;                     }
.LBB0_290:
	s_waitcnt lgkmcnt(0)
	v_lshlrev_b64 v[66:67], 11, v[64:65]
	v_lshl_add_u64 v[66:67], s[10:11], 0, v[66:67]
	v_lshl_add_u64 v[66:67], v[140:141], 1, v[66:67]
	global_load_dwordx2 v[74:75], v[66:67], off
	global_load_dwordx2 v[220:221], v[66:67], off offset:32
	global_load_dwordx2 v[222:223], v[66:67], off offset:256
	global_load_dwordx2 v[224:225], v[66:67], off offset:288
	v_mov_b32_e32 v71, v70
	s_and_b64 vcc, exec, s[6:7]
	s_waitcnt vmcnt(3)
	v_lshlrev_b32_e32 v72, 16, v74
	v_and_b32_e32 v73, 0xffff0000, v74
	v_lshlrev_b32_e32 v74, 16, v75
	v_and_b32_e32 v75, 0xffff0000, v75
	s_cbranch_vccnz .LBB0_292
	v_sub_f32_e32 v73, v73, v68
	v_sub_f32_e32 v72, v72, v68
	v_sub_f32_e32 v75, v75, v68
	v_sub_f32_e32 v74, v74, v68
	v_pk_mul_f32 v[80:81], v[70:71], v[72:73]
	v_mov_b32_e32 v72, v70
	v_mov_b32_e32 v73, v70
	v_pk_mul_f32 v[82:83], v[72:73], v[74:75]
	v_pk_fma_f32 v[74:75], v[82:83], v[166:167], v[206:207]
	v_pk_fma_f32 v[72:73], v[80:81], v[164:165], v[204:205]
.LBB0_292:
	s_mov_b32 s28, 0x3fb504f3
	v_pk_fma_f32 v[62:63], v[74:75], s[28:29], v[62:63] op_sel_hi:[1,0,1]
	v_pk_fma_f32 v[60:61], v[72:73], s[28:29], v[60:61] op_sel_hi:[1,0,1]
	v_cvt_pk_bf16_f32 v73, v62, v63
	v_cvt_pk_bf16_f32 v72, v60, v61
	global_store_dwordx2 v[66:67], v[72:73], off
	s_and_b64 vcc, exec, s[6:7]
	s_waitcnt vmcnt(3)
	v_lshlrev_b32_e32 v72, 16, v220
	v_and_b32_e32 v73, 0xffff0000, v220
	v_lshlrev_b32_e32 v74, 16, v221
	v_and_b32_e32 v75, 0xffff0000, v221
	s_cbranch_vccnz .LBB0_294
	v_sub_f32_e32 v73, v73, v68
	v_sub_f32_e32 v72, v72, v68
	v_sub_f32_e32 v75, v75, v68
	v_sub_f32_e32 v74, v74, v68
	v_pk_mul_f32 v[80:81], v[70:71], v[72:73]
	v_mov_b32_e32 v72, v70
	v_mov_b32_e32 v73, v70
	v_pk_mul_f32 v[82:83], v[72:73], v[74:75]
	v_pk_fma_f32 v[74:75], v[82:83], v[170:171], v[210:211]
	v_pk_fma_f32 v[72:73], v[80:81], v[168:169], v[208:209]
.LBB0_294:
	v_pk_fma_f32 v[58:59], v[74:75], s[28:29], v[58:59] op_sel_hi:[1,0,1]
	v_pk_fma_f32 v[56:57], v[72:73], s[28:29], v[56:57] op_sel_hi:[1,0,1]
	v_cvt_pk_bf16_f32 v73, v58, v59
	v_cvt_pk_bf16_f32 v72, v56, v57
	global_store_dwordx2 v[66:67], v[72:73], off offset:32
	s_and_b64 vcc, exec, s[6:7]
	s_waitcnt vmcnt(3)
	v_lshlrev_b32_e32 v72, 16, v222
	v_and_b32_e32 v73, 0xffff0000, v222
	v_lshlrev_b32_e32 v74, 16, v223
	v_and_b32_e32 v75, 0xffff0000, v223
	s_cbranch_vccnz .LBB0_296
	v_sub_f32_e32 v73, v73, v68
	v_sub_f32_e32 v72, v72, v68
	v_sub_f32_e32 v75, v75, v68
	v_sub_f32_e32 v74, v74, v68
	v_pk_mul_f32 v[80:81], v[70:71], v[72:73]
	v_mov_b32_e32 v72, v70
	v_mov_b32_e32 v73, v70
	v_pk_mul_f32 v[82:83], v[72:73], v[74:75]
	v_pk_fma_f32 v[74:75], v[82:83], v[174:175], v[214:215]
	v_pk_fma_f32 v[72:73], v[80:81], v[172:173], v[212:213]
.LBB0_296:
	v_pk_fma_f32 v[54:55], v[74:75], s[28:29], v[54:55] op_sel_hi:[1,0,1]
	v_pk_fma_f32 v[52:53], v[72:73], s[28:29], v[52:53] op_sel_hi:[1,0,1]
	v_cvt_pk_bf16_f32 v73, v54, v55
	v_cvt_pk_bf16_f32 v72, v52, v53
	global_store_dwordx2 v[66:67], v[72:73], off offset:256
	s_and_b64 vcc, exec, s[6:7]
	s_waitcnt vmcnt(3)
	v_lshlrev_b32_e32 v72, 16, v224
	v_and_b32_e32 v73, 0xffff0000, v224
	v_lshlrev_b32_e32 v74, 16, v225
	v_and_b32_e32 v75, 0xffff0000, v225
	s_cbranch_vccnz .LBB0_298
	v_sub_f32_e32 v75, v75, v68
	v_sub_f32_e32 v74, v74, v68
	v_sub_f32_e32 v69, v73, v68
	v_sub_f32_e32 v68, v72, v68
	v_pk_mul_f32 v[76:77], v[70:71], v[68:69]
	v_mov_b32_e32 v71, v70
	v_pk_mul_f32 v[78:79], v[70:71], v[74:75]
	v_pk_fma_f32 v[74:75], v[78:79], v[178:179], v[218:219]
	v_pk_fma_f32 v[72:73], v[76:77], v[176:177], v[216:217]

; __device__ __forceinline__ unsigned pk2(float lo, float hi) { const f32x2_t v = {lo, hi}; const bf16x2_t b = __builtin_convertvector(v, bf16x2_t); return __builtin_bit_cast(unsigned, b); }
; __device__ __forceinline__ float bflo(unsigned w) { return __uint_as_float(w << 16); }
; __device__ __forceinline__ float bfhi(unsigned w) { return __uint_as_float(w & 0xffff0000u); }
;     __device__ __forceinline__ void operator()(const f32x4 (&acc)[2][2][4][2], const pg8::Unit& u, int wr, int wc, int fr, int fq) const {
;     ...
;                 const int row = row0 + ai * 128 + m * 16; float mu, rstd; row_stats(stats_prev, row, mu, rstd);
;                 float s = 0.f, q = 0.f;
; #pragma unroll
;                 for (int bj = 0; bj < 2; ++bj)
; #pragma unroll
;                     for (int n = 0; n < 2; ++n) {
;                         const int col = col0 + bj * 128 + n * 16;
;                         const u32x2 rb = *(const u32x2*)(YB + (size_t)row * D_ + col);
;                         f32x4 r = (f32x4){bflo(rb.x), bfhi(rb.x), bflo(rb.y), bfhi(rb.y)};
;                         if (stats_prev) { const f32x4 g4 = *(const f32x4*)(lng + col), b4 = *(const f32x4*)(lnb + col); r = (r - mu) * rstd * g4 + b4; }
;                         const f32x4 y = r * ALPHA_ + acc[ai][bj][m][n] * coef;
;                         if (Yout) *(f32x4*)(Yout + (size_t)row * D_ + col) = y;
;                         else { u32x2 w; w.x = pk2(y[0], y[1]); w.y = pk2(y[2], y[3]); *(u32x2*)(YB + (size_t)row * D_ + col) = w; }
;                         s += (y[0] + y[1]) + (y[2] + y[3]); q += (y[0] * y[0] + y[1] * y[1]) + (y[2] * y[2] + y[3] * y[3]);
;                     }
.LBB0_303:
	s_waitcnt lgkmcnt(0)
	v_lshlrev_b64 v[50:51], 11, v[48:49]
	v_lshl_add_u64 v[50:51], s[10:11], 0, v[50:51]
	v_lshl_add_u64 v[50:51], v[140:141], 1, v[50:51]
	global_load_dwordx2 v[58:59], v[50:51], off
	global_load_dwordx2 v[220:221], v[50:51], off offset:32
	global_load_dwordx2 v[222:223], v[50:51], off offset:256
	global_load_dwordx2 v[224:225], v[50:51], off offset:288
	v_mov_b32_e32 v55, v54
	s_and_b64 vcc, exec, s[6:7]
	s_waitcnt vmcnt(3)
	v_lshlrev_b32_e32 v56, 16, v58
	v_and_b32_e32 v57, 0xffff0000, v58
	v_lshlrev_b32_e32 v58, 16, v59
	v_and_b32_e32 v59, 0xffff0000, v59
	s_cbranch_vccnz .LBB0_305
	v_sub_f32_e32 v57, v57, v52
	v_sub_f32_e32 v56, v56, v52
	v_sub_f32_e32 v59, v59, v52
	v_sub_f32_e32 v58, v58, v52
	v_pk_mul_f32 v[64:65], v[54:55], v[56:57]
	v_mov_b32_e32 v56, v54
	v_mov_b32_e32 v57, v54
	v_pk_mul_f32 v[66:67], v[56:57], v[58:59]
	v_pk_fma_f32 v[58:59], v[66:67], v[166:167], v[206:207]
	v_pk_fma_f32 v[56:57], v[64:65], v[164:165], v[204:205]
.LBB0_305:
	s_mov_b32 s28, 0x3fb504f3
	v_pk_fma_f32 v[46:47], v[58:59], s[28:29], v[46:47] op_sel_hi:[1,0,1]
	v_pk_fma_f32 v[44:45], v[56:57], s[28:29], v[44:45] op_sel_hi:[1,0,1]
	v_cvt_pk_bf16_f32 v57, v46, v47
	v_cvt_pk_bf16_f32 v56, v44, v45
	global_store_dwordx2 v[50:51], v[56:57], off
	s_and_b64 vcc, exec, s[6:7]
	s_waitcnt vmcnt(3)
	v_lshlrev_b32_e32 v56, 16, v220
	v_and_b32_e32 v57, 0xffff0000, v220
	v_lshlrev_b32_e32 v58, 16, v221
	v_and_b32_e32 v59, 0xffff0000, v221
	s_cbranch_vccnz .LBB0_307
	v_sub_f32_e32 v57, v57, v52
	v_sub_f32_e32 v56, v56, v52
	v_sub_f32_e32 v59, v59, v52
	v_sub_f32_e32 v58, v58, v52
	v_pk_mul_f32 v[64:65], v[54:55], v[56:57]
	v_mov_b32_e32 v56, v54
	v_mov_b32_e32 v57, v54
	v_pk_mul_f32 v[66:67], v[56:57], v[58:59]
	v_pk_fma_f32 v[58:59], v[66:67], v[170:171], v[210:211]
	v_pk_fma_f32 v[56:57], v[64:65], v[168:169], v[208:209]
.LBB0_307:
	v_pk_fma_f32 v[42:43], v[58:59], s[28:29], v[42:43] op_sel_hi:[1,0,1]
	v_pk_fma_f32 v[40:41], v[56:57], s[28:29], v[40:41] op_sel_hi:[1,0,1]
	v_cvt_pk_bf16_f32 v57, v42, v43
	v_cvt_pk_bf16_f32 v56, v40, v41
	global_store_dwordx2 v[50:51], v[56:57], off offset:32
	s_and_b64 vcc, exec, s[6:7]
	s_waitcnt vmcnt(3)
	v_lshlrev_b32_e32 v56, 16, v222
	v_and_b32_e32 v57, 0xffff0000, v222
	v_lshlrev_b32_e32 v58, 16, v223
	v_and_b32_e32 v59, 0xffff0000, v223
	s_cbranch_vccnz .LBB0_309
	v_sub_f32_e32 v57, v57, v52
	v_sub_f32_e32 v56, v56, v52
	v_sub_f32_e32 v59, v59, v52
	v_sub_f32_e32 v58, v58, v52
	v_pk_mul_f32 v[64:65], v[54:55], v[56:57]
	v_mov_b32_e32 v56, v54
	v_mov_b32_e32 v57, v54
	v_pk_mul_f32 v[66:67], v[56:57], v[58:59]
	v_pk_fma_f32 v[58:59], v[66:67], v[174:175], v[214:215]
	v_pk_fma_f32 v[56:57], v[64:65], v[172:173], v[212:213]
.LBB0_309:
	v_pk_fma_f32 v[38:39], v[58:59], s[28:29], v[38:39] op_sel_hi:[1,0,1]
	v_pk_fma_f32 v[36:37], v[56:57], s[28:29], v[36:37] op_sel_hi:[1,0,1]
	v_cvt_pk_bf16_f32 v57, v38, v39
	v_cvt_pk_bf16_f32 v56, v36, v37
	global_store_dwordx2 v[50:51], v[56:57], off offset:256
	s_and_b64 vcc, exec, s[6:7]
	s_waitcnt vmcnt(3)
	v_lshlrev_b32_e32 v56, 16, v224
	v_and_b32_e32 v57, 0xffff0000, v224
	v_lshlrev_b32_e32 v58, 16, v225
	v_and_b32_e32 v59, 0xffff0000, v225
	s_cbranch_vccnz .LBB0_311
	v_sub_f32_e32 v59, v59, v52
	v_sub_f32_e32 v58, v58, v52
	v_sub_f32_e32 v53, v57, v52
	v_sub_f32_e32 v52, v56, v52
	v_pk_mul_f32 v[60:61], v[54:55], v[52:53]
	v_mov_b32_e32 v55, v54
	v_pk_mul_f32 v[62:63], v[54:55], v[58:59]
	v_pk_fma_f32 v[58:59], v[62:63], v[178:179], v[218:219]
	v_pk_fma_f32 v[56:57], v[60:61], v[176:177], v[216:217]

; __device__ __forceinline__ unsigned pk2(float lo, float hi) { const f32x2_t v = {lo, hi}; const bf16x2_t b = __builtin_convertvector(v, bf16x2_t); return __builtin_bit_cast(unsigned, b); }
; __device__ __forceinline__ float bflo(unsigned w) { return __uint_as_float(w << 16); }
; __device__ __forceinline__ float bfhi(unsigned w) { return __uint_as_float(w & 0xffff0000u); }
;     __device__ __forceinline__ void operator()(const f32x4 (&acc)[2][2][4][2], const pg8::Unit& u, int wr, int wc, int fr, int fq) const {
;     ...
;                 const int row = row0 + ai * 128 + m * 16; float mu, rstd; row_stats(stats_prev, row, mu, rstd);
;                 float s = 0.f, q = 0.f;
; #pragma unroll
;                 for (int bj = 0; bj < 2; ++bj)
; #pragma unroll
;                     for (int n = 0; n < 2; ++n) {
;                         const int col = col0 + bj * 128 + n * 16;
;                         const u32x2 rb = *(const u32x2*)(YB + (size_t)row * D_ + col);
;                         f32x4 r = (f32x4){bflo(rb.x), bfhi(rb.x), bflo(rb.y), bfhi(rb.y)};
;                         if (stats_prev) { const f32x4 g4 = *(const f32x4*)(lng + col), b4 = *(const f32x4*)(lnb + col); r = (r - mu) * rstd * g4 + b4; }
;                         const f32x4 y = r * ALPHA_ + acc[ai][bj][m][n] * coef;
;                         if (Yout) *(f32x4*)(Yout + (size_t)row * D_ + col) = y;
;                         else { u32x2 w; w.x = pk2(y[0], y[1]); w.y = pk2(y[2], y[3]); *(u32x2*)(YB + (size_t)row * D_ + col) = w; }
;                         s += (y[0] + y[1]) + (y[2] + y[3]); q += (y[0] * y[0] + y[1] * y[1]) + (y[2] * y[2] + y[3] * y[3]);
;                     }
.LBB0_316:
	s_waitcnt lgkmcnt(0)
	v_lshlrev_b64 v[34:35], 11, v[32:33]
	v_lshl_add_u64 v[34:35], s[10:11], 0, v[34:35]
	v_lshl_add_u64 v[34:35], v[140:141], 1, v[34:35]
	global_load_dwordx2 v[42:43], v[34:35], off
	global_load_dwordx2 v[220:221], v[34:35], off offset:32
	global_load_dwordx2 v[222:223], v[34:35], off offset:256
	global_load_dwordx2 v[224:225], v[34:35], off offset:288
	v_mov_b32_e32 v39, v38
	s_and_b64 vcc, exec, s[6:7]
	s_waitcnt vmcnt(3)
	v_lshlrev_b32_e32 v40, 16, v42
	v_and_b32_e32 v41, 0xffff0000, v42
	v_lshlrev_b32_e32 v42, 16, v43
	v_and_b32_e32 v43, 0xffff0000, v43
	s_cbranch_vccnz .LBB0_318
	v_sub_f32_e32 v41, v41, v36
	v_sub_f32_e32 v40, v40, v36
	v_sub_f32_e32 v43, v43, v36
	v_sub_f32_e32 v42, v42, v36
	v_pk_mul_f32 v[48:49], v[38:39], v[40:41]
	v_mov_b32_e32 v40, v38
	v_mov_b32_e32 v41, v38
	v_pk_mul_f32 v[50:51], v[40:41], v[42:43]
	v_pk_fma_f32 v[42:43], v[50:51], v[166:167], v[206:207]
	v_pk_fma_f32 v[40:41], v[48:49], v[164:165], v[204:205]
.LBB0_318:
	s_mov_b32 s28, 0x3fb504f3
	v_pk_fma_f32 v[30:31], v[42:43], s[28:29], v[30:31] op_sel_hi:[1,0,1]
	v_pk_fma_f32 v[28:29], v[40:41], s[28:29], v[28:29] op_sel_hi:[1,0,1]
	v_cvt_pk_bf16_f32 v41, v30, v31
	v_cvt_pk_bf16_f32 v40, v28, v29
	global_store_dwordx2 v[34:35], v[40:41], off
	s_and_b64 vcc, exec, s[6:7]
	s_waitcnt vmcnt(3)
	v_lshlrev_b32_e32 v40, 16, v220
	v_and_b32_e32 v41, 0xffff0000, v220
	v_lshlrev_b32_e32 v42, 16, v221
	v_and_b32_e32 v43, 0xffff0000, v221
	s_cbranch_vccnz .LBB0_320
	v_sub_f32_e32 v41, v41, v36
	v_sub_f32_e32 v40, v40, v36
	v_sub_f32_e32 v43, v43, v36
	v_sub_f32_e32 v42, v42, v36
	v_pk_mul_f32 v[48:49], v[38:39], v[40:41]
	v_mov_b32_e32 v40, v38
	v_mov_b32_e32 v41, v38
	v_pk_mul_f32 v[50:51], v[40:41], v[42:43]
	v_pk_fma_f32 v[42:43], v[50:51], v[170:171], v[210:211]
	v_pk_fma_f32 v[40:41], v[48:49], v[168:169], v[208:209]
.LBB0_320:
	v_pk_fma_f32 v[26:27], v[42:43], s[28:29], v[26:27] op_sel_hi:[1,0,1]
	v_pk_fma_f32 v[24:25], v[40:41], s[28:29], v[24:25] op_sel_hi:[1,0,1]
	v_cvt_pk_bf16_f32 v41, v26, v27
	v_cvt_pk_bf16_f32 v40, v24, v25
	global_store_dwordx2 v[34:35], v[40:41], off offset:32
	s_and_b64 vcc, exec, s[6:7]
	s_waitcnt vmcnt(3)
	v_lshlrev_b32_e32 v40, 16, v222
	v_and_b32_e32 v41, 0xffff0000, v222
	v_lshlrev_b32_e32 v42, 16, v223
	v_and_b32_e32 v43, 0xffff0000, v223
	s_cbranch_vccnz .LBB0_322
	v_sub_f32_e32 v41, v41, v36
	v_sub_f32_e32 v40, v40, v36
	v_sub_f32_e32 v43, v43, v36
	v_sub_f32_e32 v42, v42, v36
	v_pk_mul_f32 v[48:49], v[38:39], v[40:41]
	v_mov_b32_e32 v40, v38
	v_mov_b32_e32 v41, v38
	v_pk_mul_f32 v[50:51], v[40:41], v[42:43]
	v_pk_fma_f32 v[42:43], v[50:51], v[174:175], v[214:215]
	v_pk_fma_f32 v[40:41], v[48:49], v[172:173], v[212:213]
.LBB0_322:
	v_pk_fma_f32 v[22:23], v[42:43], s[28:29], v[22:23] op_sel_hi:[1,0,1]
	v_pk_fma_f32 v[20:21], v[40:41], s[28:29], v[20:21] op_sel_hi:[1,0,1]
	v_cvt_pk_bf16_f32 v41, v22, v23
	v_cvt_pk_bf16_f32 v40, v20, v21
	global_store_dwordx2 v[34:35], v[40:41], off offset:256
	s_and_b64 vcc, exec, s[6:7]
	s_waitcnt vmcnt(3)
	v_lshlrev_b32_e32 v40, 16, v224
	v_and_b32_e32 v41, 0xffff0000, v224
	v_lshlrev_b32_e32 v42, 16, v225
	v_and_b32_e32 v43, 0xffff0000, v225
	s_cbranch_vccnz .LBB0_324
	v_sub_f32_e32 v43, v43, v36
	v_sub_f32_e32 v42, v42, v36
	v_sub_f32_e32 v37, v41, v36
	v_sub_f32_e32 v36, v40, v36
	v_pk_mul_f32 v[44:45], v[38:39], v[36:37]
	v_mov_b32_e32 v39, v38
	v_pk_mul_f32 v[46:47], v[38:39], v[42:43]
	v_pk_fma_f32 v[42:43], v[46:47], v[178:179], v[218:219]
	v_pk_fma_f32 v[40:41], v[44:45], v[176:177], v[216:217]

; __device__ __forceinline__ unsigned pk2(float lo, float hi) { const f32x2_t v = {lo, hi}; const bf16x2_t b = __builtin_convertvector(v, bf16x2_t); return __builtin_bit_cast(unsigned, b); }
; __device__ __forceinline__ float bflo(unsigned w) { return __uint_as_float(w << 16); }
; __device__ __forceinline__ float bfhi(unsigned w) { return __uint_as_float(w & 0xffff0000u); }
;     __device__ __forceinline__ void operator()(const f32x4 (&acc)[2][2][4][2], const pg8::Unit& u, int wr, int wc, int fr, int fq) const {
;     ...
;                 const int row = row0 + ai * 128 + m * 16; float mu, rstd; row_stats(stats_prev, row, mu, rstd);
;                 float s = 0.f, q = 0.f;
; #pragma unroll
;                 for (int bj = 0; bj < 2; ++bj)
; #pragma unroll
;                     for (int n = 0; n < 2; ++n) {
;                         const int col = col0 + bj * 128 + n * 16;
;                         const u32x2 rb = *(const u32x2*)(YB + (size_t)row * D_ + col);
;                         f32x4 r = (f32x4){bflo(rb.x), bfhi(rb.x), bflo(rb.y), bfhi(rb.y)};
;                         if (stats_prev) { const f32x4 g4 = *(const f32x4*)(lng + col), b4 = *(const f32x4*)(lnb + col); r = (r - mu) * rstd * g4 + b4; }
;                         const f32x4 y = r * ALPHA_ + acc[ai][bj][m][n] * coef;
;                         if (Yout) *(f32x4*)(Yout + (size_t)row * D_ + col) = y;
;                         else { u32x2 w; w.x = pk2(y[0], y[1]); w.y = pk2(y[2], y[3]); *(u32x2*)(YB + (size_t)row * D_ + col) = w; }
;                         s += (y[0] + y[1]) + (y[2] + y[3]); q += (y[0] * y[0] + y[1] * y[1]) + (y[2] * y[2] + y[3] * y[3]);
;                     }
.LBB0_329:
	s_waitcnt lgkmcnt(0)
	v_lshlrev_b64 v[18:19], 11, v[16:17]
	v_lshl_add_u64 v[18:19], s[10:11], 0, v[18:19]
	v_lshl_add_u64 v[18:19], v[140:141], 1, v[18:19]
	global_load_dwordx2 v[26:27], v[18:19], off
	global_load_dwordx2 v[220:221], v[18:19], off offset:32
	global_load_dwordx2 v[222:223], v[18:19], off offset:256
	global_load_dwordx2 v[224:225], v[18:19], off offset:288
	v_mov_b32_e32 v23, v22
	s_and_b64 vcc, exec, s[6:7]
	s_waitcnt vmcnt(3)
	v_lshlrev_b32_e32 v24, 16, v26
	v_and_b32_e32 v25, 0xffff0000, v26
	v_lshlrev_b32_e32 v26, 16, v27
	v_and_b32_e32 v27, 0xffff0000, v27
	s_cbranch_vccnz .LBB0_331
	v_sub_f32_e32 v25, v25, v20
	v_sub_f32_e32 v24, v24, v20
	v_sub_f32_e32 v27, v27, v20
	v_sub_f32_e32 v26, v26, v20
	v_pk_mul_f32 v[32:33], v[22:23], v[24:25]
	v_mov_b32_e32 v24, v22
	v_mov_b32_e32 v25, v22
	v_pk_mul_f32 v[34:35], v[24:25], v[26:27]
	v_pk_fma_f32 v[26:27], v[34:35], v[166:167], v[206:207]
	v_pk_fma_f32 v[24:25], v[32:33], v[164:165], v[204:205]
.LBB0_331:
	s_mov_b32 s28, 0x3fb504f3
	v_pk_fma_f32 v[14:15], v[26:27], s[28:29], v[14:15] op_sel_hi:[1,0,1]
	v_pk_fma_f32 v[12:13], v[24:25], s[28:29], v[12:13] op_sel_hi:[1,0,1]
	v_cvt_pk_bf16_f32 v25, v14, v15
	v_cvt_pk_bf16_f32 v24, v12, v13
	global_store_dwordx2 v[18:19], v[24:25], off
	s_and_b64 vcc, exec, s[6:7]
	s_waitcnt vmcnt(3)
	v_lshlrev_b32_e32 v24, 16, v220
	v_and_b32_e32 v25, 0xffff0000, v220
	v_lshlrev_b32_e32 v26, 16, v221
	v_and_b32_e32 v27, 0xffff0000, v221
	s_cbranch_vccnz .LBB0_333
	v_sub_f32_e32 v25, v25, v20
	v_sub_f32_e32 v24, v24, v20
	v_sub_f32_e32 v27, v27, v20
	v_sub_f32_e32 v26, v26, v20
	v_pk_mul_f32 v[32:33], v[22:23], v[24:25]
	v_mov_b32_e32 v24, v22
	v_mov_b32_e32 v25, v22
	v_pk_mul_f32 v[34:35], v[24:25], v[26:27]
	v_pk_fma_f32 v[26:27], v[34:35], v[170:171], v[210:211]
	v_pk_fma_f32 v[24:25], v[32:33], v[168:169], v[208:209]
.LBB0_333:
	v_pk_fma_f32 v[10:11], v[26:27], s[28:29], v[10:11] op_sel_hi:[1,0,1]
	v_pk_fma_f32 v[8:9], v[24:25], s[28:29], v[8:9] op_sel_hi:[1,0,1]
	v_cvt_pk_bf16_f32 v25, v10, v11
	v_cvt_pk_bf16_f32 v24, v8, v9
	global_store_dwordx2 v[18:19], v[24:25], off offset:32
	s_and_b64 vcc, exec, s[6:7]
	s_waitcnt vmcnt(3)
	v_lshlrev_b32_e32 v24, 16, v222
	v_and_b32_e32 v25, 0xffff0000, v222
	v_lshlrev_b32_e32 v26, 16, v223
	v_and_b32_e32 v27, 0xffff0000, v223
	s_cbranch_vccnz .LBB0_335
	v_sub_f32_e32 v25, v25, v20
	v_sub_f32_e32 v24, v24, v20
	v_sub_f32_e32 v27, v27, v20
	v_sub_f32_e32 v26, v26, v20
	v_pk_mul_f32 v[32:33], v[22:23], v[24:25]
	v_mov_b32_e32 v24, v22
	v_mov_b32_e32 v25, v22
	v_pk_mul_f32 v[34:35], v[24:25], v[26:27]
	v_pk_fma_f32 v[26:27], v[34:35], v[174:175], v[214:215]
	v_pk_fma_f32 v[24:25], v[32:33], v[172:173], v[212:213]
.LBB0_335:
	v_pk_fma_f32 v[6:7], v[26:27], s[28:29], v[6:7] op_sel_hi:[1,0,1]
	v_pk_fma_f32 v[4:5], v[24:25], s[28:29], v[4:5] op_sel_hi:[1,0,1]
	v_cvt_pk_bf16_f32 v25, v6, v7
	v_cvt_pk_bf16_f32 v24, v4, v5
	global_store_dwordx2 v[18:19], v[24:25], off offset:256
	s_and_b64 vcc, exec, s[6:7]
	s_waitcnt vmcnt(3)
	v_lshlrev_b32_e32 v24, 16, v224
	v_and_b32_e32 v25, 0xffff0000, v224
	v_lshlrev_b32_e32 v26, 16, v225
	v_and_b32_e32 v27, 0xffff0000, v225
	s_cbranch_vccnz .LBB0_337
	v_sub_f32_e32 v27, v27, v20
	v_sub_f32_e32 v26, v26, v20
	v_sub_f32_e32 v21, v25, v20
	v_sub_f32_e32 v20, v24, v20
	v_pk_mul_f32 v[28:29], v[22:23], v[20:21]
	v_mov_b32_e32 v23, v22
	v_pk_mul_f32 v[30:31], v[22:23], v[26:27]
	v_pk_fma_f32 v[26:27], v[30:31], v[178:179], v[218:219]
	v_pk_fma_f32 v[24:25], v[28:29], v[176:177], v[216:217]

; #define LAS __attribute__((address_space(3)))
; __device__ __forceinline__ void phase_dnprep(ArgsRef a, const Tb tb, int l, LAS unsigned char* lds) {
;     ...
;         if (tid < 256) {
;             const int col = tid;
;             float acc[64];
; #pragma unroll
;             for (int i = 0; i < 64; ++i) acc[i] = rhs[i * 256 + col];
; #pragma unroll
;             for (int jp = 0; jp < 16; ++jp) {
;                 const int r0 = 4 * jp;
;                 const f32x4 d1 = *(LAS const f32x4*)(Lm + (r0 + 1) * 64 + r0), d2 = *(LAS const f32x4*)(Lm + (r0 + 2) * 64 + r0), d3 = *(LAS const f32x4*)(Lm + (r0 + 3) * 64 + r0);
;                 const float x0 = acc[r0];
;                 const float x1 = acc[r0 + 1] - d1[0] * x0;
;                 const float x2 = (acc[r0 + 2] - d2[0] * x0) - d2[1] * x1;
;                 const float x3 = ((acc[r0 + 3] - d3[0] * x0) - d3[1] * x1) - d3[2] * x2;
;                 rhs[(r0 + 0) * 256 + col] = x0; rhs[(r0 + 1) * 256 + col] = x1; rhs[(r0 + 2) * 256 + col] = x2; rhs[(r0 + 3) * 256 + col] = x3;
; #pragma unroll
;                 for (int i = r0 + 4; i < 64; ++i) {
;                     const f32x4 l4 = *(LAS const f32x4*)(Lm + i * 64 + r0);
;                     acc[i] = (((acc[i] - l4[0] * x0) - l4[1] * x1) - l4[2] * x2) - l4[3] * x3;
;                 }
;             }
;         }
.LBB0_1182:
	s_or_b64 exec, exec, s[16:17]
	s_waitcnt lgkmcnt(0)
	s_barrier
	s_and_saveexec_b64 s[74:75], s[46:47]
	s_cbranch_execz .LBB0_1024
	ds_read2st64_b32 v[34:35], v91 offset0:0 offset1:4
	ds_read2st64_b32 v[36:37], v91 offset0:8 offset1:12
	ds_read2st64_b32 v[38:39], v91 offset0:16 offset1:20
	ds_read2st64_b32 v[40:41], v91 offset0:24 offset1:28
	ds_read2st64_b32 v[42:43], v91 offset0:32 offset1:36
	ds_read2st64_b32 v[44:45], v91 offset0:40 offset1:44
	ds_read2st64_b32 v[46:47], v91 offset0:48 offset1:52
	ds_read2st64_b32 v[48:49], v91 offset0:56 offset1:60
	ds_read2st64_b32 v[50:51], v91 offset0:64 offset1:68
	ds_read2st64_b32 v[52:53], v91 offset0:72 offset1:76
	ds_read2st64_b32 v[54:55], v91 offset0:80 offset1:84
	ds_read2st64_b32 v[56:57], v91 offset0:88 offset1:92
	ds_read2st64_b32 v[58:59], v91 offset0:96 offset1:100
	ds_read2st64_b32 v[60:61], v91 offset0:104 offset1:108
	ds_read2st64_b32 v[62:63], v91 offset0:112 offset1:116
	ds_read2st64_b32 v[64:65], v91 offset0:120 offset1:124
	ds_read2st64_b32 v[66:67], v91 offset0:128 offset1:132
	ds_read2st64_b32 v[68:69], v91 offset0:136 offset1:140
	ds_read2st64_b32 v[70:71], v91 offset0:144 offset1:148
	ds_read2st64_b32 v[72:73], v91 offset0:152 offset1:156
	ds_read2st64_b32 v[74:75], v91 offset0:160 offset1:164
	ds_read2st64_b32 v[76:77], v91 offset0:168 offset1:172
	ds_read2st64_b32 v[116:117], v91 offset0:176 offset1:180
	ds_read2st64_b32 v[118:119], v91 offset0:184 offset1:188
	ds_read2st64_b32 v[120:121], v91 offset0:192 offset1:196
	ds_read2st64_b32 v[122:123], v91 offset0:200 offset1:204
	ds_read2st64_b32 v[124:125], v91 offset0:208 offset1:212
	ds_read2st64_b32 v[126:127], v91 offset0:216 offset1:220
	ds_read2st64_b32 v[128:129], v91 offset0:224 offset1:228
	ds_read2st64_b32 v[130:131], v91 offset0:232 offset1:236
	ds_read2st64_b32 v[132:133], v91 offset0:240 offset1:244
	ds_read2st64_b32 v[134:135], v91 offset0:248 offset1:252
	ds_read_b128 v[144:147], v181 offset:256
	ds_read_b128 v[148:151], v181 offset:512
	ds_read_b128 v[152:155], v181 offset:768
	ds_read_b128 v[156:159], v181 offset:1024
	ds_read_b128 v[160:163], v181 offset:1280
	ds_read_b128 v[164:167], v181 offset:1536
	ds_read_b128 v[168:171], v181 offset:1792
	ds_read_b128 v[172:175], v181 offset:2048
	ds_read_b128 v[176:179], v181 offset:2304
	ds_read_b128 v[204:207], v181 offset:2560
	ds_read_b128 v[208:211], v181 offset:2816
	ds_read_b128 v[212:215], v181 offset:3072
	s_waitcnt lgkmcnt(9)
	v_fma_f32 v35, -v34, v144, v35
	v_fma_f32 v36, -v34, v148, v36
	v_fma_f32 v37, -v34, v152, v37
	v_fma_f32 v36, -v149, v35, v36
	v_fma_f32 v37, -v153, v35, v37
	v_fma_f32 v37, -v154, v36, v37
	ds_write_b32 v91, v34 offset:0
	ds_write_b32 v91, v35 offset:1024
	ds_write_b32 v91, v36 offset:2048
	ds_write_b32 v91, v37 offset:3072
	ds_read_b128 v[144:147], v181 offset:3328
	ds_read_b128 v[148:151], v181 offset:3584
	ds_read_b128 v[152:155], v181 offset:3840
	s_waitcnt lgkmcnt(14)
	v_fma_f32 v38, -v34, v156, v38
	v_fma_f32 v39, -v34, v160, v39
	v_fma_f32 v38, -v35, v157, v38
	v_fma_f32 v39, -v35, v161, v39
	v_fma_f32 v38, -v36, v158, v38
	v_fma_f32 v39, -v36, v162, v39
	v_fma_f32 v38, -v37, v159, v38
	v_fma_f32 v39, -v37, v163, v39
	ds_read_b128 v[156:159], v181 offset:4096
	ds_read_b128 v[160:163], v181 offset:4352
	s_waitcnt lgkmcnt(14)
	v_fma_f32 v40, -v34, v164, v40
	v_fma_f32 v41, -v34, v168, v41
	v_fma_f32 v40, -v35, v165, v40
	v_fma_f32 v41, -v35, v169, v41
	v_fma_f32 v40, -v36, v166, v40
	v_fma_f32 v41, -v36, v170, v41
	v_fma_f32 v40, -v37, v167, v40
	v_fma_f32 v41, -v37, v171, v41
	ds_read_b128 v[164:167], v181 offset:4608
	ds_read_b128 v[168:171], v181 offset:4864
	s_waitcnt lgkmcnt(14)
	v_fma_f32 v42, -v34, v172, v42
	v_fma_f32 v43, -v34, v176, v43
	v_fma_f32 v42, -v35, v173, v42
	v_fma_f32 v43, -v35, v177, v43
	v_fma_f32 v42, -v36, v174, v42
	v_fma_f32 v43, -v36, v178, v43
	v_fma_f32 v42, -v37, v175, v42
	v_fma_f32 v43, -v37, v179, v43
	ds_read_b128 v[172:175], v181 offset:5120
	ds_read_b128 v[176:179], v181 offset:5376
	s_waitcnt lgkmcnt(14)
	v_fma_f32 v44, -v34, v204, v44
	v_fma_f32 v45, -v34, v208, v45
	v_fma_f32 v44, -v35, v205, v44
	v_fma_f32 v45, -v35, v209, v45
	v_fma_f32 v44, -v36, v206, v44
	v_fma_f32 v45, -v36, v210, v45
	v_fma_f32 v44, -v37, v207, v44
	v_fma_f32 v45, -v37, v211, v45
	ds_read_b128 v[204:207], v181 offset:5632
	ds_read_b128 v[208:211], v181 offset:5888
	s_waitcnt lgkmcnt(10)
	v_fma_f32 v46, -v34, v212, v46
	v_fma_f32 v47, -v34, v144, v47
	v_fma_f32 v46, -v35, v213, v46
	v_fma_f32 v47, -v35, v145, v47
	v_fma_f32 v46, -v36, v214, v46
	v_fma_f32 v47, -v36, v146, v47
	v_fma_f32 v46, -v37, v215, v46
	v_fma_f32 v47, -v37, v147, v47
	ds_read_b128 v[212:215], v181 offset:6144
	ds_read_b128 v[144:147], v181 offset:6400
	s_waitcnt lgkmcnt(10)
	v_fma_f32 v48, -v34, v148, v48
	v_fma_f32 v49, -v34, v152, v49
	v_fma_f32 v48, -v35, v149, v48
	v_fma_f32 v49, -v35, v153, v49
	v_fma_f32 v48, -v36, v150, v48
	v_fma_f32 v49, -v36, v154, v49
	v_fma_f32 v48, -v37, v151, v48
	v_fma_f32 v49, -v37, v155, v49
	ds_read_b128 v[148:151], v181 offset:6656
	ds_read_b128 v[152:155], v181 offset:6912
	s_waitcnt lgkmcnt(10)
	v_fma_f32 v50, -v34, v156, v50
	v_fma_f32 v51, -v34, v160, v51
	v_fma_f32 v50, -v35, v157, v50
	v_fma_f32 v51, -v35, v161, v51
	v_fma_f32 v50, -v36, v158, v50
	v_fma_f32 v51, -v36, v162, v51
	v_fma_f32 v50, -v37, v159, v50
	v_fma_f32 v51, -v37, v163, v51
	ds_read_b128 v[156:159], v181 offset:7168
	ds_read_b128 v[160:163], v181 offset:7424
	s_waitcnt lgkmcnt(10)
; #define LAS __attribute__((address_space(3)))
; __device__ __forceinline__ void phase_dnprep(ArgsRef a, const Tb tb, int l, LAS unsigned char* lds) {
;     ...
;             for (int jp = 0; jp < 16; ++jp) {
;                 const int r0 = 4 * jp;
;                 const f32x4 d1 = *(LAS const f32x4*)(Lm + (r0 + 1) * 64 + r0), d2 = *(LAS const f32x4*)(Lm + (r0 + 2) * 64 + r0), d3 = *(LAS const f32x4*)(Lm + (r0 + 3) * 64 + r0);
;                 const float x0 = acc[r0];
;                 const float x1 = acc[r0 + 1] - d1[0] * x0;
;                 const float x2 = (acc[r0 + 2] - d2[0] * x0) - d2[1] * x1;
;                 const float x3 = ((acc[r0 + 3] - d3[0] * x0) - d3[1] * x1) - d3[2] * x2;
;                 rhs[(r0 + 0) * 256 + col] = x0; rhs[(r0 + 1) * 256 + col] = x1; rhs[(r0 + 2) * 256 + col] = x2; rhs[(r0 + 3) * 256 + col] = x3;
; #pragma unroll
;                 for (int i = r0 + 4; i < 64; ++i) {
;                     const f32x4 l4 = *(LAS const f32x4*)(Lm + i * 64 + r0);
;                     acc[i] = (((acc[i] - l4[0] * x0) - l4[1] * x1) - l4[2] * x2) - l4[3] * x3;
;                 }
	v_fma_f32 v52, -v34, v164, v52
	v_fma_f32 v53, -v34, v168, v53
	v_fma_f32 v52, -v35, v165, v52
	v_fma_f32 v53, -v35, v169, v53
	v_fma_f32 v52, -v36, v166, v52
	v_fma_f32 v53, -v36, v170, v53
	v_fma_f32 v52, -v37, v167, v52
	v_fma_f32 v53, -v37, v171, v53
	ds_read_b128 v[164:167], v181 offset:7680
	ds_read_b128 v[168:171], v181 offset:7936
	s_waitcnt lgkmcnt(10)
	v_fma_f32 v54, -v34, v172, v54
	v_fma_f32 v55, -v34, v176, v55
	v_fma_f32 v54, -v35, v173, v54
	v_fma_f32 v55, -v35, v177, v55
	v_fma_f32 v54, -v36, v174, v54
	v_fma_f32 v55, -v36, v178, v55
	v_fma_f32 v54, -v37, v175, v54
	v_fma_f32 v55, -v37, v179, v55
	ds_read_b128 v[172:175], v181 offset:8192
	ds_read_b128 v[176:179], v181 offset:8448
	s_waitcnt lgkmcnt(10)
	v_fma_f32 v56, -v34, v204, v56
	v_fma_f32 v57, -v34, v208, v57
	v_fma_f32 v56, -v35, v205, v56
	v_fma_f32 v57, -v35, v209, v57
	v_fma_f32 v56, -v36, v206, v56
	v_fma_f32 v57, -v36, v210, v57
	v_fma_f32 v56, -v37, v207, v56
	v_fma_f32 v57, -v37, v211, v57
	ds_read_b128 v[204:207], v181 offset:8704
	ds_read_b128 v[208:211], v181 offset:8960
	s_waitcnt lgkmcnt(10)
	v_fma_f32 v58, -v34, v212, v58
	v_fma_f32 v59, -v34, v144, v59
	v_fma_f32 v58, -v35, v213, v58
	v_fma_f32 v59, -v35, v145, v59
	v_fma_f32 v58, -v36, v214, v58
	v_fma_f32 v59, -v36, v146, v59
	v_fma_f32 v58, -v37, v215, v58
	v_fma_f32 v59, -v37, v147, v59
	ds_read_b128 v[212:215], v181 offset:9216
	ds_read_b128 v[144:147], v181 offset:9472
	s_waitcnt lgkmcnt(10)
	v_fma_f32 v60, -v34, v148, v60
	v_fma_f32 v61, -v34, v152, v61
	v_fma_f32 v60, -v35, v149, v60
	v_fma_f32 v61, -v35, v153, v61
	v_fma_f32 v60, -v36, v150, v60
	v_fma_f32 v61, -v36, v154, v61
	v_fma_f32 v60, -v37, v151, v60
	v_fma_f32 v61, -v37, v155, v61
	ds_read_b128 v[148:151], v181 offset:9728
	ds_read_b128 v[152:155], v181 offset:9984
	s_waitcnt lgkmcnt(10)
	v_fma_f32 v62, -v34, v156, v62
	v_fma_f32 v63, -v34, v160, v63
	v_fma_f32 v62, -v35, v157, v62
	v_fma_f32 v63, -v35, v161, v63
	v_fma_f32 v62, -v36, v158, v62
	v_fma_f32 v63, -v36, v162, v63
	v_fma_f32 v62, -v37, v159, v62
	v_fma_f32 v63, -v37, v163, v63
	ds_read_b128 v[156:159], v181 offset:10240
	ds_read_b128 v[160:163], v181 offset:10496
	s_waitcnt lgkmcnt(10)
	v_fma_f32 v64, -v34, v164, v64
	v_fma_f32 v65, -v34, v168, v65
	v_fma_f32 v64, -v35, v165, v64
	v_fma_f32 v65, -v35, v169, v65
	v_fma_f32 v64, -v36, v166, v64
	v_fma_f32 v65, -v36, v170, v65
	v_fma_f32 v64, -v37, v167, v64
	v_fma_f32 v65, -v37, v171, v65
	ds_read_b128 v[164:167], v181 offset:10752
	ds_read_b128 v[168:171], v181 offset:11008
	s_waitcnt lgkmcnt(10)
	v_fma_f32 v66, -v34, v172, v66
	v_fma_f32 v67, -v34, v176, v67
	v_fma_f32 v66, -v35, v173, v66
	v_fma_f32 v67, -v35, v177, v67
	v_fma_f32 v66, -v36, v174, v66
	v_fma_f32 v67, -v36, v178, v67
	v_fma_f32 v66, -v37, v175, v66
	v_fma_f32 v67, -v37, v179, v67
	ds_read_b128 v[172:175], v181 offset:11264
	ds_read_b128 v[176:179], v181 offset:11520
	s_waitcnt lgkmcnt(10)
	v_fma_f32 v68, -v34, v204, v68
	v_fma_f32 v69, -v34, v208, v69
	v_fma_f32 v68, -v35, v205, v68
	v_fma_f32 v69, -v35, v209, v69
	v_fma_f32 v68, -v36, v206, v68
	v_fma_f32 v69, -v36, v210, v69
	v_fma_f32 v68, -v37, v207, v68
	v_fma_f32 v69, -v37, v211, v69
	ds_read_b128 v[204:207], v181 offset:11776
	ds_read_b128 v[208:211], v181 offset:12032
	s_waitcnt lgkmcnt(10)
	v_fma_f32 v70, -v34, v212, v70
	v_fma_f32 v71, -v34, v144, v71
	v_fma_f32 v70, -v35, v213, v70
	v_fma_f32 v71, -v35, v145, v71
	v_fma_f32 v70, -v36, v214, v70
	v_fma_f32 v71, -v36, v146, v71
	v_fma_f32 v70, -v37, v215, v70
	v_fma_f32 v71, -v37, v147, v71
	ds_read_b128 v[212:215], v181 offset:12288
	ds_read_b128 v[144:147], v181 offset:12544
	s_waitcnt lgkmcnt(10)
	v_fma_f32 v72, -v34, v148, v72
	v_fma_f32 v73, -v34, v152, v73
	v_fma_f32 v72, -v35, v149, v72
	v_fma_f32 v73, -v35, v153, v73
	v_fma_f32 v72, -v36, v150, v72
	v_fma_f32 v73, -v36, v154, v73
	v_fma_f32 v72, -v37, v151, v72
	v_fma_f32 v73, -v37, v155, v73
	ds_read_b128 v[148:151], v181 offset:12800
	ds_read_b128 v[152:155], v181 offset:13056
	s_waitcnt lgkmcnt(10)
	v_fma_f32 v74, -v34, v156, v74
	v_fma_f32 v75, -v34, v160, v75
	v_fma_f32 v74, -v35, v157, v74
	v_fma_f32 v75, -v35, v161, v75
	v_fma_f32 v74, -v36, v158, v74
	v_fma_f32 v75, -v36, v162, v75
	v_fma_f32 v74, -v37, v159, v74
	v_fma_f32 v75, -v37, v163, v75
	ds_read_b128 v[156:159], v181 offset:13312
	ds_read_b128 v[160:163], v181 offset:13568
	s_waitcnt lgkmcnt(10)
	v_fma_f32 v76, -v34, v164, v76
	v_fma_f32 v77, -v34, v168, v77
	v_fma_f32 v76, -v35, v165, v76
	v_fma_f32 v77, -v35, v169, v77
	v_fma_f32 v76, -v36, v166, v76
	v_fma_f32 v77, -v36, v170, v77
	v_fma_f32 v76, -v37, v167, v76
	v_fma_f32 v77, -v37, v171, v77
	ds_read_b128 v[164:167], v181 offset:13824
	ds_read_b128 v[168:171], v181 offset:14080
	s_waitcnt lgkmcnt(10)
	v_fma_f32 v116, -v34, v172, v116
	v_fma_f32 v117, -v34, v176, v117
	v_fma_f32 v116, -v35, v173, v116
	v_fma_f32 v117, -v35, v177, v117
	v_fma_f32 v116, -v36, v174, v116
	v_fma_f32 v117, -v36, v178, v117
	v_fma_f32 v116, -v37, v175, v116
	v_fma_f32 v117, -v37, v179, v117
	ds_read_b128 v[172:175], v181 offset:14336
	ds_read_b128 v[176:179], v181 offset:14592
	s_waitcnt lgkmcnt(10)
	v_fma_f32 v118, -v34, v204, v118
	v_fma_f32 v119, -v34, v208, v119
	v_fma_f32 v118, -v35, v205, v118
	v_fma_f32 v119, -v35, v209, v119
	v_fma_f32 v118, -v36, v206, v118
	v_fma_f32 v119, -v36, v210, v119
	v_fma_f32 v118, -v37, v207, v118
	v_fma_f32 v119, -v37, v211, v119
	ds_read_b128 v[204:207], v181 offset:14848
	ds_read_b128 v[208:211], v181 offset:15104
	s_waitcnt lgkmcnt(10)
; #define LAS __attribute__((address_space(3)))
; __device__ __forceinline__ void phase_dnprep(ArgsRef a, const Tb tb, int l, LAS unsigned char* lds) {
;     ...
;             for (int jp = 0; jp < 16; ++jp) {
;                 const int r0 = 4 * jp;
;                 const f32x4 d1 = *(LAS const f32x4*)(Lm + (r0 + 1) * 64 + r0), d2 = *(LAS const f32x4*)(Lm + (r0 + 2) * 64 + r0), d3 = *(LAS const f32x4*)(Lm + (r0 + 3) * 64 + r0);
;                 const float x0 = acc[r0];
;                 const float x1 = acc[r0 + 1] - d1[0] * x0;
;                 const float x2 = (acc[r0 + 2] - d2[0] * x0) - d2[1] * x1;
;                 const float x3 = ((acc[r0 + 3] - d3[0] * x0) - d3[1] * x1) - d3[2] * x2;
;                 rhs[(r0 + 0) * 256 + col] = x0; rhs[(r0 + 1) * 256 + col] = x1; rhs[(r0 + 2) * 256 + col] = x2; rhs[(r0 + 3) * 256 + col] = x3;
; #pragma unroll
;                 for (int i = r0 + 4; i < 64; ++i) {
;                     const f32x4 l4 = *(LAS const f32x4*)(Lm + i * 64 + r0);
;                     acc[i] = (((acc[i] - l4[0] * x0) - l4[1] * x1) - l4[2] * x2) - l4[3] * x3;
;                 }
	v_fma_f32 v120, -v34, v212, v120
	v_fma_f32 v121, -v34, v144, v121
	v_fma_f32 v120, -v35, v213, v120
	v_fma_f32 v121, -v35, v145, v121
	v_fma_f32 v120, -v36, v214, v120
	v_fma_f32 v121, -v36, v146, v121
	v_fma_f32 v120, -v37, v215, v120
	v_fma_f32 v121, -v37, v147, v121
	ds_read_b128 v[212:215], v181 offset:15360
	ds_read_b128 v[144:147], v181 offset:15616
	s_waitcnt lgkmcnt(10)
	v_fma_f32 v122, -v34, v148, v122
	v_fma_f32 v123, -v34, v152, v123
	v_fma_f32 v122, -v35, v149, v122
	v_fma_f32 v123, -v35, v153, v123
	v_fma_f32 v122, -v36, v150, v122
	v_fma_f32 v123, -v36, v154, v123
	v_fma_f32 v122, -v37, v151, v122
	v_fma_f32 v123, -v37, v155, v123
	ds_read_b128 v[148:151], v181 offset:15872
	ds_read_b128 v[152:155], v181 offset:16128
	s_waitcnt lgkmcnt(10)
	v_fma_f32 v124, -v34, v156, v124
	v_fma_f32 v125, -v34, v160, v125
	v_fma_f32 v124, -v35, v157, v124
	v_fma_f32 v125, -v35, v161, v125
	v_fma_f32 v124, -v36, v158, v124
	v_fma_f32 v125, -v36, v162, v125
	v_fma_f32 v124, -v37, v159, v124
	v_fma_f32 v125, -v37, v163, v125
	ds_read_b128 v[156:159], v181 offset:1296
	ds_read_b128 v[160:163], v181 offset:1552
	s_waitcnt lgkmcnt(10)
	v_fma_f32 v126, -v34, v164, v126
	v_fma_f32 v127, -v34, v168, v127
	v_fma_f32 v126, -v35, v165, v126
	v_fma_f32 v127, -v35, v169, v127
	v_fma_f32 v126, -v36, v166, v126
	v_fma_f32 v127, -v36, v170, v127
	v_fma_f32 v126, -v37, v167, v126
	v_fma_f32 v127, -v37, v171, v127
	ds_read_b128 v[164:167], v181 offset:1808
	ds_read_b128 v[168:171], v181 offset:2064
	s_waitcnt lgkmcnt(10)
	v_fma_f32 v128, -v34, v172, v128
	v_fma_f32 v129, -v34, v176, v129
	v_fma_f32 v128, -v35, v173, v128
	v_fma_f32 v129, -v35, v177, v129
	v_fma_f32 v128, -v36, v174, v128
	v_fma_f32 v129, -v36, v178, v129
	v_fma_f32 v128, -v37, v175, v128
	v_fma_f32 v129, -v37, v179, v129
	ds_read_b128 v[172:175], v181 offset:2320
	ds_read_b128 v[176:179], v181 offset:2576
	s_waitcnt lgkmcnt(10)
	v_fma_f32 v130, -v34, v204, v130
	v_fma_f32 v131, -v34, v208, v131
	v_fma_f32 v130, -v35, v205, v130
	v_fma_f32 v131, -v35, v209, v131
	v_fma_f32 v130, -v36, v206, v130
	v_fma_f32 v131, -v36, v210, v131
	v_fma_f32 v130, -v37, v207, v130
	v_fma_f32 v131, -v37, v211, v131
	ds_read_b128 v[204:207], v181 offset:2832
	ds_read_b128 v[208:211], v181 offset:3088
	s_waitcnt lgkmcnt(10)
	v_fma_f32 v132, -v34, v212, v132
	v_fma_f32 v133, -v34, v144, v133
	v_fma_f32 v132, -v35, v213, v132
	v_fma_f32 v133, -v35, v145, v133
	v_fma_f32 v132, -v36, v214, v132
	v_fma_f32 v133, -v36, v146, v133
	v_fma_f32 v132, -v37, v215, v132
	v_fma_f32 v133, -v37, v147, v133
	ds_read_b128 v[212:215], v181 offset:3344
	ds_read_b128 v[144:147], v181 offset:3600
	s_waitcnt lgkmcnt(10)
	v_fma_f32 v134, -v34, v148, v134
	v_fma_f32 v135, -v34, v152, v135
	v_fma_f32 v134, -v35, v149, v134
	v_fma_f32 v135, -v35, v153, v135
	v_fma_f32 v134, -v36, v150, v134
	v_fma_f32 v135, -v36, v154, v135
	v_fma_f32 v134, -v37, v151, v134
	v_fma_f32 v135, -v37, v155, v135
	ds_read_b128 v[148:151], v181 offset:3856
	ds_read_b128 v[152:155], v181 offset:4112
	s_waitcnt lgkmcnt(9)
	v_fma_f32 v39, -v38, v156, v39
	v_fma_f32 v40, -v38, v160, v40
	v_fma_f32 v41, -v38, v164, v41
	v_fma_f32 v40, -v161, v39, v40
	v_fma_f32 v41, -v165, v39, v41
	v_fma_f32 v41, -v166, v40, v41
	ds_write_b32 v91, v38 offset:4096
	ds_write_b32 v91, v39 offset:5120
	ds_write_b32 v91, v40 offset:6144
	ds_write_b32 v91, v41 offset:7168
	ds_read_b128 v[156:159], v181 offset:4368
	ds_read_b128 v[160:163], v181 offset:4624
	ds_read_b128 v[164:167], v181 offset:4880
	s_waitcnt lgkmcnt(14)
	v_fma_f32 v42, -v38, v168, v42
	v_fma_f32 v43, -v38, v172, v43
	v_fma_f32 v42, -v39, v169, v42
	v_fma_f32 v43, -v39, v173, v43
	v_fma_f32 v42, -v40, v170, v42
	v_fma_f32 v43, -v40, v174, v43
	v_fma_f32 v42, -v41, v171, v42
	v_fma_f32 v43, -v41, v175, v43
	ds_read_b128 v[168:171], v181 offset:5136
	ds_read_b128 v[172:175], v181 offset:5392
	s_waitcnt lgkmcnt(14)
	v_fma_f32 v44, -v38, v176, v44
	v_fma_f32 v45, -v38, v204, v45
	v_fma_f32 v44, -v39, v177, v44
	v_fma_f32 v45, -v39, v205, v45
	v_fma_f32 v44, -v40, v178, v44
	v_fma_f32 v45, -v40, v206, v45
	v_fma_f32 v44, -v41, v179, v44
	v_fma_f32 v45, -v41, v207, v45
	ds_read_b128 v[176:179], v181 offset:5648
	ds_read_b128 v[204:207], v181 offset:5904
	s_waitcnt lgkmcnt(14)
	v_fma_f32 v46, -v38, v208, v46
	v_fma_f32 v47, -v38, v212, v47
	v_fma_f32 v46, -v39, v209, v46
	v_fma_f32 v47, -v39, v213, v47
	v_fma_f32 v46, -v40, v210, v46
	v_fma_f32 v47, -v40, v214, v47
	v_fma_f32 v46, -v41, v211, v46
	v_fma_f32 v47, -v41, v215, v47
	ds_read_b128 v[208:211], v181 offset:6160
	ds_read_b128 v[212:215], v181 offset:6416
	s_waitcnt lgkmcnt(14)
	v_fma_f32 v48, -v38, v144, v48
	v_fma_f32 v49, -v38, v148, v49
	v_fma_f32 v48, -v39, v145, v48
	v_fma_f32 v49, -v39, v149, v49
	v_fma_f32 v48, -v40, v146, v48
	v_fma_f32 v49, -v40, v150, v49
	v_fma_f32 v48, -v41, v147, v48
	v_fma_f32 v49, -v41, v151, v49
	ds_read_b128 v[144:147], v181 offset:6672
	ds_read_b128 v[148:151], v181 offset:6928
	s_waitcnt lgkmcnt(10)
	v_fma_f32 v50, -v38, v152, v50
	v_fma_f32 v51, -v38, v156, v51
	v_fma_f32 v50, -v39, v153, v50
	v_fma_f32 v51, -v39, v157, v51
	v_fma_f32 v50, -v40, v154, v50
	v_fma_f32 v51, -v40, v158, v51
	v_fma_f32 v50, -v41, v155, v50
	v_fma_f32 v51, -v41, v159, v51
	ds_read_b128 v[152:155], v181 offset:7184
	ds_read_b128 v[156:159], v181 offset:7440
	s_waitcnt lgkmcnt(10)
	v_fma_f32 v52, -v38, v160, v52
	v_fma_f32 v53, -v38, v164, v53
	v_fma_f32 v52, -v39, v161, v52
	v_fma_f32 v53, -v39, v165, v53
	v_fma_f32 v52, -v40, v162, v52
	v_fma_f32 v53, -v40, v166, v53
	v_fma_f32 v52, -v41, v163, v52
	v_fma_f32 v53, -v41, v167, v53
	ds_read_b128 v[160:163], v181 offset:7696
	ds_read_b128 v[164:167], v181 offset:7952
	s_waitcnt lgkmcnt(10)
; #define LAS __attribute__((address_space(3)))
; __device__ __forceinline__ void phase_dnprep(ArgsRef a, const Tb tb, int l, LAS unsigned char* lds) {
;     ...
;             for (int jp = 0; jp < 16; ++jp) {
;                 const int r0 = 4 * jp;
;                 const f32x4 d1 = *(LAS const f32x4*)(Lm + (r0 + 1) * 64 + r0), d2 = *(LAS const f32x4*)(Lm + (r0 + 2) * 64 + r0), d3 = *(LAS const f32x4*)(Lm + (r0 + 3) * 64 + r0);
;                 const float x0 = acc[r0];
;                 const float x1 = acc[r0 + 1] - d1[0] * x0;
;                 const float x2 = (acc[r0 + 2] - d2[0] * x0) - d2[1] * x1;
;                 const float x3 = ((acc[r0 + 3] - d3[0] * x0) - d3[1] * x1) - d3[2] * x2;
;                 rhs[(r0 + 0) * 256 + col] = x0; rhs[(r0 + 1) * 256 + col] = x1; rhs[(r0 + 2) * 256 + col] = x2; rhs[(r0 + 3) * 256 + col] = x3;
; #pragma unroll
;                 for (int i = r0 + 4; i < 64; ++i) {
;                     const f32x4 l4 = *(LAS const f32x4*)(Lm + i * 64 + r0);
;                     acc[i] = (((acc[i] - l4[0] * x0) - l4[1] * x1) - l4[2] * x2) - l4[3] * x3;
;                 }
	v_fma_f32 v54, -v38, v168, v54
	v_fma_f32 v55, -v38, v172, v55
	v_fma_f32 v54, -v39, v169, v54
	v_fma_f32 v55, -v39, v173, v55
	v_fma_f32 v54, -v40, v170, v54
	v_fma_f32 v55, -v40, v174, v55
	v_fma_f32 v54, -v41, v171, v54
	v_fma_f32 v55, -v41, v175, v55
	ds_read_b128 v[168:171], v181 offset:8208
	ds_read_b128 v[172:175], v181 offset:8464
	s_waitcnt lgkmcnt(10)
	v_fma_f32 v56, -v38, v176, v56
	v_fma_f32 v57, -v38, v204, v57
	v_fma_f32 v56, -v39, v177, v56
	v_fma_f32 v57, -v39, v205, v57
	v_fma_f32 v56, -v40, v178, v56
	v_fma_f32 v57, -v40, v206, v57
	v_fma_f32 v56, -v41, v179, v56
	v_fma_f32 v57, -v41, v207, v57
	ds_read_b128 v[176:179], v181 offset:8720
	ds_read_b128 v[204:207], v181 offset:8976
	s_waitcnt lgkmcnt(10)
	v_fma_f32 v58, -v38, v208, v58
	v_fma_f32 v59, -v38, v212, v59
	v_fma_f32 v58, -v39, v209, v58
	v_fma_f32 v59, -v39, v213, v59
	v_fma_f32 v58, -v40, v210, v58
	v_fma_f32 v59, -v40, v214, v59
	v_fma_f32 v58, -v41, v211, v58
	v_fma_f32 v59, -v41, v215, v59
	ds_read_b128 v[208:211], v181 offset:9232
	ds_read_b128 v[212:215], v181 offset:9488
	s_waitcnt lgkmcnt(10)
	v_fma_f32 v60, -v38, v144, v60
	v_fma_f32 v61, -v38, v148, v61
	v_fma_f32 v60, -v39, v145, v60
	v_fma_f32 v61, -v39, v149, v61
	v_fma_f32 v60, -v40, v146, v60
	v_fma_f32 v61, -v40, v150, v61
	v_fma_f32 v60, -v41, v147, v60
	v_fma_f32 v61, -v41, v151, v61
	ds_read_b128 v[144:147], v181 offset:9744
	ds_read_b128 v[148:151], v181 offset:10000
	s_waitcnt lgkmcnt(10)
	v_fma_f32 v62, -v38, v152, v62
	v_fma_f32 v63, -v38, v156, v63
	v_fma_f32 v62, -v39, v153, v62
	v_fma_f32 v63, -v39, v157, v63
	v_fma_f32 v62, -v40, v154, v62
	v_fma_f32 v63, -v40, v158, v63
	v_fma_f32 v62, -v41, v155, v62
	v_fma_f32 v63, -v41, v159, v63
	ds_read_b128 v[152:155], v181 offset:10256
	ds_read_b128 v[156:159], v181 offset:10512
	s_waitcnt lgkmcnt(10)
	v_fma_f32 v64, -v38, v160, v64
	v_fma_f32 v65, -v38, v164, v65
	v_fma_f32 v64, -v39, v161, v64
	v_fma_f32 v65, -v39, v165, v65
	v_fma_f32 v64, -v40, v162, v64
	v_fma_f32 v65, -v40, v166, v65
	v_fma_f32 v64, -v41, v163, v64
	v_fma_f32 v65, -v41, v167, v65
	ds_read_b128 v[160:163], v181 offset:10768
	ds_read_b128 v[164:167], v181 offset:11024
	s_waitcnt lgkmcnt(10)
	v_fma_f32 v66, -v38, v168, v66
	v_fma_f32 v67, -v38, v172, v67
	v_fma_f32 v66, -v39, v169, v66
	v_fma_f32 v67, -v39, v173, v67
	v_fma_f32 v66, -v40, v170, v66
	v_fma_f32 v67, -v40, v174, v67
	v_fma_f32 v66, -v41, v171, v66
	v_fma_f32 v67, -v41, v175, v67
	ds_read_b128 v[168:171], v181 offset:11280
	ds_read_b128 v[172:175], v181 offset:11536
	s_waitcnt lgkmcnt(10)
	v_fma_f32 v68, -v38, v176, v68
	v_fma_f32 v69, -v38, v204, v69
	v_fma_f32 v68, -v39, v177, v68
	v_fma_f32 v69, -v39, v205, v69
	v_fma_f32 v68, -v40, v178, v68
	v_fma_f32 v69, -v40, v206, v69
	v_fma_f32 v68, -v41, v179, v68
	v_fma_f32 v69, -v41, v207, v69
	ds_read_b128 v[176:179], v181 offset:11792
	ds_read_b128 v[204:207], v181 offset:12048
	s_waitcnt lgkmcnt(10)
	v_fma_f32 v70, -v38, v208, v70
	v_fma_f32 v71, -v38, v212, v71
	v_fma_f32 v70, -v39, v209, v70
	v_fma_f32 v71, -v39, v213, v71
	v_fma_f32 v70, -v40, v210, v70
	v_fma_f32 v71, -v40, v214, v71
	v_fma_f32 v70, -v41, v211, v70
	v_fma_f32 v71, -v41, v215, v71
	ds_read_b128 v[208:211], v181 offset:12304
	ds_read_b128 v[212:215], v181 offset:12560
	s_waitcnt lgkmcnt(10)
	v_fma_f32 v72, -v38, v144, v72
	v_fma_f32 v73, -v38, v148, v73
	v_fma_f32 v72, -v39, v145, v72
	v_fma_f32 v73, -v39, v149, v73
	v_fma_f32 v72, -v40, v146, v72
	v_fma_f32 v73, -v40, v150, v73
	v_fma_f32 v72, -v41, v147, v72
	v_fma_f32 v73, -v41, v151, v73
	ds_read_b128 v[144:147], v181 offset:12816
	ds_read_b128 v[148:151], v181 offset:13072
	s_waitcnt lgkmcnt(10)
	v_fma_f32 v74, -v38, v152, v74
	v_fma_f32 v75, -v38, v156, v75
	v_fma_f32 v74, -v39, v153, v74
	v_fma_f32 v75, -v39, v157, v75
	v_fma_f32 v74, -v40, v154, v74
	v_fma_f32 v75, -v40, v158, v75
	v_fma_f32 v74, -v41, v155, v74
	v_fma_f32 v75, -v41, v159, v75
	ds_read_b128 v[152:155], v181 offset:13328
	ds_read_b128 v[156:159], v181 offset:13584
	s_waitcnt lgkmcnt(10)
	v_fma_f32 v76, -v38, v160, v76
	v_fma_f32 v77, -v38, v164, v77
	v_fma_f32 v76, -v39, v161, v76
	v_fma_f32 v77, -v39, v165, v77
	v_fma_f32 v76, -v40, v162, v76
	v_fma_f32 v77, -v40, v166, v77
	v_fma_f32 v76, -v41, v163, v76
	v_fma_f32 v77, -v41, v167, v77
	ds_read_b128 v[160:163], v181 offset:13840
	ds_read_b128 v[164:167], v181 offset:14096
	s_waitcnt lgkmcnt(10)
	v_fma_f32 v116, -v38, v168, v116
	v_fma_f32 v117, -v38, v172, v117
	v_fma_f32 v116, -v39, v169, v116
	v_fma_f32 v117, -v39, v173, v117
	v_fma_f32 v116, -v40, v170, v116
	v_fma_f32 v117, -v40, v174, v117
	v_fma_f32 v116, -v41, v171, v116
	v_fma_f32 v117, -v41, v175, v117
	ds_read_b128 v[168:171], v181 offset:14352
	ds_read_b128 v[172:175], v181 offset:14608
	s_waitcnt lgkmcnt(10)
	v_fma_f32 v118, -v38, v176, v118
	v_fma_f32 v119, -v38, v204, v119
	v_fma_f32 v118, -v39, v177, v118
	v_fma_f32 v119, -v39, v205, v119
	v_fma_f32 v118, -v40, v178, v118
	v_fma_f32 v119, -v40, v206, v119
	v_fma_f32 v118, -v41, v179, v118
	v_fma_f32 v119, -v41, v207, v119
	ds_read_b128 v[176:179], v181 offset:14864
	ds_read_b128 v[204:207], v181 offset:15120
	s_waitcnt lgkmcnt(10)
	v_fma_f32 v120, -v38, v208, v120
	v_fma_f32 v121, -v38, v212, v121
	v_fma_f32 v120, -v39, v209, v120
	v_fma_f32 v121, -v39, v213, v121
	v_fma_f32 v120, -v40, v210, v120
	v_fma_f32 v121, -v40, v214, v121
	v_fma_f32 v120, -v41, v211, v120
	v_fma_f32 v121, -v41, v215, v121
	ds_read_b128 v[208:211], v181 offset:15376
	ds_read_b128 v[212:215], v181 offset:15632
	s_waitcnt lgkmcnt(10)
; #define LAS __attribute__((address_space(3)))
; __device__ __forceinline__ void phase_dnprep(ArgsRef a, const Tb tb, int l, LAS unsigned char* lds) {
;     ...
;             for (int jp = 0; jp < 16; ++jp) {
;                 const int r0 = 4 * jp;
;                 const f32x4 d1 = *(LAS const f32x4*)(Lm + (r0 + 1) * 64 + r0), d2 = *(LAS const f32x4*)(Lm + (r0 + 2) * 64 + r0), d3 = *(LAS const f32x4*)(Lm + (r0 + 3) * 64 + r0);
;                 const float x0 = acc[r0];
;                 const float x1 = acc[r0 + 1] - d1[0] * x0;
;                 const float x2 = (acc[r0 + 2] - d2[0] * x0) - d2[1] * x1;
;                 const float x3 = ((acc[r0 + 3] - d3[0] * x0) - d3[1] * x1) - d3[2] * x2;
;                 rhs[(r0 + 0) * 256 + col] = x0; rhs[(r0 + 1) * 256 + col] = x1; rhs[(r0 + 2) * 256 + col] = x2; rhs[(r0 + 3) * 256 + col] = x3;
; #pragma unroll
;                 for (int i = r0 + 4; i < 64; ++i) {
;                     const f32x4 l4 = *(LAS const f32x4*)(Lm + i * 64 + r0);
;                     acc[i] = (((acc[i] - l4[0] * x0) - l4[1] * x1) - l4[2] * x2) - l4[3] * x3;
;                 }
	v_fma_f32 v122, -v38, v144, v122
	v_fma_f32 v123, -v38, v148, v123
	v_fma_f32 v122, -v39, v145, v122
	v_fma_f32 v123, -v39, v149, v123
	v_fma_f32 v122, -v40, v146, v122
	v_fma_f32 v123, -v40, v150, v123
	v_fma_f32 v122, -v41, v147, v122
	v_fma_f32 v123, -v41, v151, v123
	ds_read_b128 v[144:147], v181 offset:15888
	ds_read_b128 v[148:151], v181 offset:16144
	s_waitcnt lgkmcnt(10)
	v_fma_f32 v124, -v38, v152, v124
	v_fma_f32 v125, -v38, v156, v125
	v_fma_f32 v124, -v39, v153, v124
	v_fma_f32 v125, -v39, v157, v125
	v_fma_f32 v124, -v40, v154, v124
	v_fma_f32 v125, -v40, v158, v125
	v_fma_f32 v124, -v41, v155, v124
	v_fma_f32 v125, -v41, v159, v125
	ds_read_b128 v[152:155], v181 offset:2336
	ds_read_b128 v[156:159], v181 offset:2592
	s_waitcnt lgkmcnt(10)
	v_fma_f32 v126, -v38, v160, v126
	v_fma_f32 v127, -v38, v164, v127
	v_fma_f32 v126, -v39, v161, v126
	v_fma_f32 v127, -v39, v165, v127
	v_fma_f32 v126, -v40, v162, v126
	v_fma_f32 v127, -v40, v166, v127
	v_fma_f32 v126, -v41, v163, v126
	v_fma_f32 v127, -v41, v167, v127
	ds_read_b128 v[160:163], v181 offset:2848
	ds_read_b128 v[164:167], v181 offset:3104
	s_waitcnt lgkmcnt(10)
	v_fma_f32 v128, -v38, v168, v128
	v_fma_f32 v129, -v38, v172, v129
	v_fma_f32 v128, -v39, v169, v128
	v_fma_f32 v129, -v39, v173, v129
	v_fma_f32 v128, -v40, v170, v128
	v_fma_f32 v129, -v40, v174, v129
	v_fma_f32 v128, -v41, v171, v128
	v_fma_f32 v129, -v41, v175, v129
	ds_read_b128 v[168:171], v181 offset:3360
	ds_read_b128 v[172:175], v181 offset:3616
	s_waitcnt lgkmcnt(10)
	v_fma_f32 v130, -v38, v176, v130
	v_fma_f32 v131, -v38, v204, v131
	v_fma_f32 v130, -v39, v177, v130
	v_fma_f32 v131, -v39, v205, v131
	v_fma_f32 v130, -v40, v178, v130
	v_fma_f32 v131, -v40, v206, v131
	v_fma_f32 v130, -v41, v179, v130
	v_fma_f32 v131, -v41, v207, v131
	ds_read_b128 v[176:179], v181 offset:3872
	ds_read_b128 v[204:207], v181 offset:4128
	s_waitcnt lgkmcnt(10)
	v_fma_f32 v132, -v38, v208, v132
	v_fma_f32 v133, -v38, v212, v133
	v_fma_f32 v132, -v39, v209, v132
	v_fma_f32 v133, -v39, v213, v133
	v_fma_f32 v132, -v40, v210, v132
	v_fma_f32 v133, -v40, v214, v133
	v_fma_f32 v132, -v41, v211, v132
	v_fma_f32 v133, -v41, v215, v133
	ds_read_b128 v[208:211], v181 offset:4384
	ds_read_b128 v[212:215], v181 offset:4640
	s_waitcnt lgkmcnt(10)
	v_fma_f32 v134, -v38, v144, v134
	v_fma_f32 v135, -v38, v148, v135
	v_fma_f32 v134, -v39, v145, v134
	v_fma_f32 v135, -v39, v149, v135
	v_fma_f32 v134, -v40, v146, v134
	v_fma_f32 v135, -v40, v150, v135
	v_fma_f32 v134, -v41, v147, v134
	v_fma_f32 v135, -v41, v151, v135
	ds_read_b128 v[144:147], v181 offset:4896
	ds_read_b128 v[148:151], v181 offset:5152
	s_waitcnt lgkmcnt(9)
	v_fma_f32 v43, -v42, v152, v43
	v_fma_f32 v44, -v42, v156, v44
	v_fma_f32 v45, -v42, v160, v45
	v_fma_f32 v44, -v157, v43, v44
	v_fma_f32 v45, -v161, v43, v45
	v_fma_f32 v45, -v162, v44, v45
	ds_write_b32 v91, v42 offset:8192
	ds_write_b32 v91, v43 offset:9216
	ds_write_b32 v91, v44 offset:10240
	ds_write_b32 v91, v45 offset:11264
	ds_read_b128 v[152:155], v181 offset:5408
	ds_read_b128 v[156:159], v181 offset:5664
	ds_read_b128 v[160:163], v181 offset:5920
	s_waitcnt lgkmcnt(14)
	v_fma_f32 v46, -v42, v164, v46
	v_fma_f32 v47, -v42, v168, v47
	v_fma_f32 v46, -v43, v165, v46
	v_fma_f32 v47, -v43, v169, v47
	v_fma_f32 v46, -v44, v166, v46
	v_fma_f32 v47, -v44, v170, v47
	v_fma_f32 v46, -v45, v167, v46
	v_fma_f32 v47, -v45, v171, v47
	ds_read_b128 v[164:167], v181 offset:6176
	ds_read_b128 v[168:171], v181 offset:6432
	s_waitcnt lgkmcnt(14)
	v_fma_f32 v48, -v42, v172, v48
	v_fma_f32 v49, -v42, v176, v49
	v_fma_f32 v48, -v43, v173, v48
	v_fma_f32 v49, -v43, v177, v49
	v_fma_f32 v48, -v44, v174, v48
	v_fma_f32 v49, -v44, v178, v49
	v_fma_f32 v48, -v45, v175, v48
	v_fma_f32 v49, -v45, v179, v49
	ds_read_b128 v[172:175], v181 offset:6688
	ds_read_b128 v[176:179], v181 offset:6944
	s_waitcnt lgkmcnt(14)
	v_fma_f32 v50, -v42, v204, v50
	v_fma_f32 v51, -v42, v208, v51
	v_fma_f32 v50, -v43, v205, v50
	v_fma_f32 v51, -v43, v209, v51
	v_fma_f32 v50, -v44, v206, v50
	v_fma_f32 v51, -v44, v210, v51
	v_fma_f32 v50, -v45, v207, v50
	v_fma_f32 v51, -v45, v211, v51
	ds_read_b128 v[204:207], v181 offset:7200
	ds_read_b128 v[208:211], v181 offset:7456
	s_waitcnt lgkmcnt(14)
	v_fma_f32 v52, -v42, v212, v52
	v_fma_f32 v53, -v42, v144, v53
	v_fma_f32 v52, -v43, v213, v52
	v_fma_f32 v53, -v43, v145, v53
	v_fma_f32 v52, -v44, v214, v52
	v_fma_f32 v53, -v44, v146, v53
	v_fma_f32 v52, -v45, v215, v52
	v_fma_f32 v53, -v45, v147, v53
	ds_read_b128 v[212:215], v181 offset:7712
	ds_read_b128 v[144:147], v181 offset:7968
	s_waitcnt lgkmcnt(10)
	v_fma_f32 v54, -v42, v148, v54
	v_fma_f32 v55, -v42, v152, v55
	v_fma_f32 v54, -v43, v149, v54
	v_fma_f32 v55, -v43, v153, v55
	v_fma_f32 v54, -v44, v150, v54
	v_fma_f32 v55, -v44, v154, v55
	v_fma_f32 v54, -v45, v151, v54
	v_fma_f32 v55, -v45, v155, v55
	ds_read_b128 v[148:151], v181 offset:8224
	ds_read_b128 v[152:155], v181 offset:8480
	s_waitcnt lgkmcnt(10)
	v_fma_f32 v56, -v42, v156, v56
	v_fma_f32 v57, -v42, v160, v57
	v_fma_f32 v56, -v43, v157, v56
	v_fma_f32 v57, -v43, v161, v57
	v_fma_f32 v56, -v44, v158, v56
	v_fma_f32 v57, -v44, v162, v57
	v_fma_f32 v56, -v45, v159, v56
	v_fma_f32 v57, -v45, v163, v57
	ds_read_b128 v[156:159], v181 offset:8736
	ds_read_b128 v[160:163], v181 offset:8992
	s_waitcnt lgkmcnt(10)
	v_fma_f32 v58, -v42, v164, v58
	v_fma_f32 v59, -v42, v168, v59
	v_fma_f32 v58, -v43, v165, v58
	v_fma_f32 v59, -v43, v169, v59
	v_fma_f32 v58, -v44, v166, v58
	v_fma_f32 v59, -v44, v170, v59
	v_fma_f32 v58, -v45, v167, v58
	v_fma_f32 v59, -v45, v171, v59
	ds_read_b128 v[164:167], v181 offset:9248
	ds_read_b128 v[168:171], v181 offset:9504
	s_waitcnt lgkmcnt(10)
; #define LAS __attribute__((address_space(3)))
; __device__ __forceinline__ void phase_dnprep(ArgsRef a, const Tb tb, int l, LAS unsigned char* lds) {
;     ...
;             for (int jp = 0; jp < 16; ++jp) {
;                 const int r0 = 4 * jp;
;                 const f32x4 d1 = *(LAS const f32x4*)(Lm + (r0 + 1) * 64 + r0), d2 = *(LAS const f32x4*)(Lm + (r0 + 2) * 64 + r0), d3 = *(LAS const f32x4*)(Lm + (r0 + 3) * 64 + r0);
;                 const float x0 = acc[r0];
;                 const float x1 = acc[r0 + 1] - d1[0] * x0;
;                 const float x2 = (acc[r0 + 2] - d2[0] * x0) - d2[1] * x1;
;                 const float x3 = ((acc[r0 + 3] - d3[0] * x0) - d3[1] * x1) - d3[2] * x2;
;                 rhs[(r0 + 0) * 256 + col] = x0; rhs[(r0 + 1) * 256 + col] = x1; rhs[(r0 + 2) * 256 + col] = x2; rhs[(r0 + 3) * 256 + col] = x3;
; #pragma unroll
;                 for (int i = r0 + 4; i < 64; ++i) {
;                     const f32x4 l4 = *(LAS const f32x4*)(Lm + i * 64 + r0);
;                     acc[i] = (((acc[i] - l4[0] * x0) - l4[1] * x1) - l4[2] * x2) - l4[3] * x3;
;                 }
	v_fma_f32 v60, -v42, v172, v60
	v_fma_f32 v61, -v42, v176, v61
	v_fma_f32 v60, -v43, v173, v60
	v_fma_f32 v61, -v43, v177, v61
	v_fma_f32 v60, -v44, v174, v60
	v_fma_f32 v61, -v44, v178, v61
	v_fma_f32 v60, -v45, v175, v60
	v_fma_f32 v61, -v45, v179, v61
	ds_read_b128 v[172:175], v181 offset:9760
	ds_read_b128 v[176:179], v181 offset:10016
	s_waitcnt lgkmcnt(10)
	v_fma_f32 v62, -v42, v204, v62
	v_fma_f32 v63, -v42, v208, v63
	v_fma_f32 v62, -v43, v205, v62
	v_fma_f32 v63, -v43, v209, v63
	v_fma_f32 v62, -v44, v206, v62
	v_fma_f32 v63, -v44, v210, v63
	v_fma_f32 v62, -v45, v207, v62
	v_fma_f32 v63, -v45, v211, v63
	ds_read_b128 v[204:207], v181 offset:10272
	ds_read_b128 v[208:211], v181 offset:10528
	s_waitcnt lgkmcnt(10)
	v_fma_f32 v64, -v42, v212, v64
	v_fma_f32 v65, -v42, v144, v65
	v_fma_f32 v64, -v43, v213, v64
	v_fma_f32 v65, -v43, v145, v65
	v_fma_f32 v64, -v44, v214, v64
	v_fma_f32 v65, -v44, v146, v65
	v_fma_f32 v64, -v45, v215, v64
	v_fma_f32 v65, -v45, v147, v65
	ds_read_b128 v[212:215], v181 offset:10784
	ds_read_b128 v[144:147], v181 offset:11040
	s_waitcnt lgkmcnt(10)
	v_fma_f32 v66, -v42, v148, v66
	v_fma_f32 v67, -v42, v152, v67
	v_fma_f32 v66, -v43, v149, v66
	v_fma_f32 v67, -v43, v153, v67
	v_fma_f32 v66, -v44, v150, v66
	v_fma_f32 v67, -v44, v154, v67
	v_fma_f32 v66, -v45, v151, v66
	v_fma_f32 v67, -v45, v155, v67
	ds_read_b128 v[148:151], v181 offset:11296
	ds_read_b128 v[152:155], v181 offset:11552
	s_waitcnt lgkmcnt(10)
	v_fma_f32 v68, -v42, v156, v68
	v_fma_f32 v69, -v42, v160, v69
	v_fma_f32 v68, -v43, v157, v68
	v_fma_f32 v69, -v43, v161, v69
	v_fma_f32 v68, -v44, v158, v68
	v_fma_f32 v69, -v44, v162, v69
	v_fma_f32 v68, -v45, v159, v68
	v_fma_f32 v69, -v45, v163, v69
	ds_read_b128 v[156:159], v181 offset:11808
	ds_read_b128 v[160:163], v181 offset:12064
	s_waitcnt lgkmcnt(10)
	v_fma_f32 v70, -v42, v164, v70
	v_fma_f32 v71, -v42, v168, v71
	v_fma_f32 v70, -v43, v165, v70
	v_fma_f32 v71, -v43, v169, v71
	v_fma_f32 v70, -v44, v166, v70
	v_fma_f32 v71, -v44, v170, v71
	v_fma_f32 v70, -v45, v167, v70
	v_fma_f32 v71, -v45, v171, v71
	ds_read_b128 v[164:167], v181 offset:12320
	ds_read_b128 v[168:171], v181 offset:12576
	s_waitcnt lgkmcnt(10)
	v_fma_f32 v72, -v42, v172, v72
	v_fma_f32 v73, -v42, v176, v73
	v_fma_f32 v72, -v43, v173, v72
	v_fma_f32 v73, -v43, v177, v73
	v_fma_f32 v72, -v44, v174, v72
	v_fma_f32 v73, -v44, v178, v73
	v_fma_f32 v72, -v45, v175, v72
	v_fma_f32 v73, -v45, v179, v73
	ds_read_b128 v[172:175], v181 offset:12832
	ds_read_b128 v[176:179], v181 offset:13088
	s_waitcnt lgkmcnt(10)
	v_fma_f32 v74, -v42, v204, v74
	v_fma_f32 v75, -v42, v208, v75
	v_fma_f32 v74, -v43, v205, v74
	v_fma_f32 v75, -v43, v209, v75
	v_fma_f32 v74, -v44, v206, v74
	v_fma_f32 v75, -v44, v210, v75
	v_fma_f32 v74, -v45, v207, v74
	v_fma_f32 v75, -v45, v211, v75
	ds_read_b128 v[204:207], v181 offset:13344
	ds_read_b128 v[208:211], v181 offset:13600
	s_waitcnt lgkmcnt(10)
	v_fma_f32 v76, -v42, v212, v76
	v_fma_f32 v77, -v42, v144, v77
	v_fma_f32 v76, -v43, v213, v76
	v_fma_f32 v77, -v43, v145, v77
	v_fma_f32 v76, -v44, v214, v76
	v_fma_f32 v77, -v44, v146, v77
	v_fma_f32 v76, -v45, v215, v76
	v_fma_f32 v77, -v45, v147, v77
	ds_read_b128 v[212:215], v181 offset:13856
	ds_read_b128 v[144:147], v181 offset:14112
	s_waitcnt lgkmcnt(10)
	v_fma_f32 v116, -v42, v148, v116
	v_fma_f32 v117, -v42, v152, v117
	v_fma_f32 v116, -v43, v149, v116
	v_fma_f32 v117, -v43, v153, v117
	v_fma_f32 v116, -v44, v150, v116
	v_fma_f32 v117, -v44, v154, v117
	v_fma_f32 v116, -v45, v151, v116
	v_fma_f32 v117, -v45, v155, v117
	ds_read_b128 v[148:151], v181 offset:14368
	ds_read_b128 v[152:155], v181 offset:14624
	s_waitcnt lgkmcnt(10)
	v_fma_f32 v118, -v42, v156, v118
	v_fma_f32 v119, -v42, v160, v119
	v_fma_f32 v118, -v43, v157, v118
	v_fma_f32 v119, -v43, v161, v119
	v_fma_f32 v118, -v44, v158, v118
	v_fma_f32 v119, -v44, v162, v119
	v_fma_f32 v118, -v45, v159, v118
	v_fma_f32 v119, -v45, v163, v119
	ds_read_b128 v[156:159], v181 offset:14880
	ds_read_b128 v[160:163], v181 offset:15136
	s_waitcnt lgkmcnt(10)
	v_fma_f32 v120, -v42, v164, v120
	v_fma_f32 v121, -v42, v168, v121
	v_fma_f32 v120, -v43, v165, v120
	v_fma_f32 v121, -v43, v169, v121
	v_fma_f32 v120, -v44, v166, v120
	v_fma_f32 v121, -v44, v170, v121
	v_fma_f32 v120, -v45, v167, v120
	v_fma_f32 v121, -v45, v171, v121
	ds_read_b128 v[164:167], v181 offset:15392
	ds_read_b128 v[168:171], v181 offset:15648
	s_waitcnt lgkmcnt(10)
	v_fma_f32 v122, -v42, v172, v122
	v_fma_f32 v123, -v42, v176, v123
	v_fma_f32 v122, -v43, v173, v122
	v_fma_f32 v123, -v43, v177, v123
	v_fma_f32 v122, -v44, v174, v122
	v_fma_f32 v123, -v44, v178, v123
	v_fma_f32 v122, -v45, v175, v122
	v_fma_f32 v123, -v45, v179, v123
	ds_read_b128 v[172:175], v181 offset:15904
	ds_read_b128 v[176:179], v181 offset:16160
	s_waitcnt lgkmcnt(10)
	v_fma_f32 v124, -v42, v204, v124
	v_fma_f32 v125, -v42, v208, v125
	v_fma_f32 v124, -v43, v205, v124
	v_fma_f32 v125, -v43, v209, v125
	v_fma_f32 v124, -v44, v206, v124
	v_fma_f32 v125, -v44, v210, v125
	v_fma_f32 v124, -v45, v207, v124
	v_fma_f32 v125, -v45, v211, v125
	ds_read_b128 v[204:207], v181 offset:3376
	ds_read_b128 v[208:211], v181 offset:3632
	s_waitcnt lgkmcnt(10)
	v_fma_f32 v126, -v42, v212, v126
	v_fma_f32 v127, -v42, v144, v127
	v_fma_f32 v126, -v43, v213, v126
	v_fma_f32 v127, -v43, v145, v127
	v_fma_f32 v126, -v44, v214, v126
	v_fma_f32 v127, -v44, v146, v127
	v_fma_f32 v126, -v45, v215, v126
	v_fma_f32 v127, -v45, v147, v127
	ds_read_b128 v[212:215], v181 offset:3888
	ds_read_b128 v[144:147], v181 offset:4144
	s_waitcnt lgkmcnt(10)
; #define LAS __attribute__((address_space(3)))
; __device__ __forceinline__ void phase_dnprep(ArgsRef a, const Tb tb, int l, LAS unsigned char* lds) {
;     ...
;             for (int jp = 0; jp < 16; ++jp) {
;                 const int r0 = 4 * jp;
;                 const f32x4 d1 = *(LAS const f32x4*)(Lm + (r0 + 1) * 64 + r0), d2 = *(LAS const f32x4*)(Lm + (r0 + 2) * 64 + r0), d3 = *(LAS const f32x4*)(Lm + (r0 + 3) * 64 + r0);
;                 const float x0 = acc[r0];
;                 const float x1 = acc[r0 + 1] - d1[0] * x0;
;                 const float x2 = (acc[r0 + 2] - d2[0] * x0) - d2[1] * x1;
;                 const float x3 = ((acc[r0 + 3] - d3[0] * x0) - d3[1] * x1) - d3[2] * x2;
;                 rhs[(r0 + 0) * 256 + col] = x0; rhs[(r0 + 1) * 256 + col] = x1; rhs[(r0 + 2) * 256 + col] = x2; rhs[(r0 + 3) * 256 + col] = x3;
; #pragma unroll
;                 for (int i = r0 + 4; i < 64; ++i) {
;                     const f32x4 l4 = *(LAS const f32x4*)(Lm + i * 64 + r0);
;                     acc[i] = (((acc[i] - l4[0] * x0) - l4[1] * x1) - l4[2] * x2) - l4[3] * x3;
;                 }
	v_fma_f32 v128, -v42, v148, v128
	v_fma_f32 v129, -v42, v152, v129
	v_fma_f32 v128, -v43, v149, v128
	v_fma_f32 v129, -v43, v153, v129
	v_fma_f32 v128, -v44, v150, v128
	v_fma_f32 v129, -v44, v154, v129
	v_fma_f32 v128, -v45, v151, v128
	v_fma_f32 v129, -v45, v155, v129
	ds_read_b128 v[148:151], v181 offset:4400
	ds_read_b128 v[152:155], v181 offset:4656
	s_waitcnt lgkmcnt(10)
	v_fma_f32 v130, -v42, v156, v130
	v_fma_f32 v131, -v42, v160, v131
	v_fma_f32 v130, -v43, v157, v130
	v_fma_f32 v131, -v43, v161, v131
	v_fma_f32 v130, -v44, v158, v130
	v_fma_f32 v131, -v44, v162, v131
	v_fma_f32 v130, -v45, v159, v130
	v_fma_f32 v131, -v45, v163, v131
	ds_read_b128 v[156:159], v181 offset:4912
	ds_read_b128 v[160:163], v181 offset:5168
	s_waitcnt lgkmcnt(10)
	v_fma_f32 v132, -v42, v164, v132
	v_fma_f32 v133, -v42, v168, v133
	v_fma_f32 v132, -v43, v165, v132
	v_fma_f32 v133, -v43, v169, v133
	v_fma_f32 v132, -v44, v166, v132
	v_fma_f32 v133, -v44, v170, v133
	v_fma_f32 v132, -v45, v167, v132
	v_fma_f32 v133, -v45, v171, v133
	ds_read_b128 v[164:167], v181 offset:5424
	ds_read_b128 v[168:171], v181 offset:5680
	s_waitcnt lgkmcnt(10)
	v_fma_f32 v134, -v42, v172, v134
	v_fma_f32 v135, -v42, v176, v135
	v_fma_f32 v134, -v43, v173, v134
	v_fma_f32 v135, -v43, v177, v135
	v_fma_f32 v134, -v44, v174, v134
	v_fma_f32 v135, -v44, v178, v135
	v_fma_f32 v134, -v45, v175, v134
	v_fma_f32 v135, -v45, v179, v135
	ds_read_b128 v[172:175], v181 offset:5936
	ds_read_b128 v[176:179], v181 offset:6192
	s_waitcnt lgkmcnt(9)
	v_fma_f32 v47, -v46, v204, v47
	v_fma_f32 v48, -v46, v208, v48
	v_fma_f32 v49, -v46, v212, v49
	v_fma_f32 v48, -v209, v47, v48
	v_fma_f32 v49, -v213, v47, v49
	v_fma_f32 v49, -v214, v48, v49
	ds_write_b32 v91, v46 offset:12288
	ds_write_b32 v91, v47 offset:13312
	ds_write_b32 v91, v48 offset:14336
	ds_write_b32 v91, v49 offset:15360
	ds_read_b128 v[204:207], v181 offset:6448
	ds_read_b128 v[208:211], v181 offset:6704
	ds_read_b128 v[212:215], v181 offset:6960
	s_waitcnt lgkmcnt(14)
	v_fma_f32 v50, -v46, v144, v50
	v_fma_f32 v51, -v46, v148, v51
	v_fma_f32 v50, -v47, v145, v50
	v_fma_f32 v51, -v47, v149, v51
	v_fma_f32 v50, -v48, v146, v50
	v_fma_f32 v51, -v48, v150, v51
	v_fma_f32 v50, -v49, v147, v50
	v_fma_f32 v51, -v49, v151, v51
	ds_read_b128 v[144:147], v181 offset:7216
	ds_read_b128 v[148:151], v181 offset:7472
	s_waitcnt lgkmcnt(14)
	v_fma_f32 v52, -v46, v152, v52
	v_fma_f32 v53, -v46, v156, v53
	v_fma_f32 v52, -v47, v153, v52
	v_fma_f32 v53, -v47, v157, v53
	v_fma_f32 v52, -v48, v154, v52
	v_fma_f32 v53, -v48, v158, v53
	v_fma_f32 v52, -v49, v155, v52
	v_fma_f32 v53, -v49, v159, v53
	ds_read_b128 v[152:155], v181 offset:7728
	ds_read_b128 v[156:159], v181 offset:7984
	s_waitcnt lgkmcnt(14)
	v_fma_f32 v54, -v46, v160, v54
	v_fma_f32 v55, -v46, v164, v55
	v_fma_f32 v54, -v47, v161, v54
	v_fma_f32 v55, -v47, v165, v55
	v_fma_f32 v54, -v48, v162, v54
	v_fma_f32 v55, -v48, v166, v55
	v_fma_f32 v54, -v49, v163, v54
	v_fma_f32 v55, -v49, v167, v55
	ds_read_b128 v[160:163], v181 offset:8240
	ds_read_b128 v[164:167], v181 offset:8496
	s_waitcnt lgkmcnt(14)
	v_fma_f32 v56, -v46, v168, v56
	v_fma_f32 v57, -v46, v172, v57
	v_fma_f32 v56, -v47, v169, v56
	v_fma_f32 v57, -v47, v173, v57
	v_fma_f32 v56, -v48, v170, v56
	v_fma_f32 v57, -v48, v174, v57
	v_fma_f32 v56, -v49, v171, v56
	v_fma_f32 v57, -v49, v175, v57
	ds_read_b128 v[168:171], v181 offset:8752
	ds_read_b128 v[172:175], v181 offset:9008
	s_waitcnt lgkmcnt(10)
	v_fma_f32 v58, -v46, v176, v58
	v_fma_f32 v59, -v46, v204, v59
	v_fma_f32 v58, -v47, v177, v58
	v_fma_f32 v59, -v47, v205, v59
	v_fma_f32 v58, -v48, v178, v58
	v_fma_f32 v59, -v48, v206, v59
	v_fma_f32 v58, -v49, v179, v58
	v_fma_f32 v59, -v49, v207, v59
	ds_read_b128 v[176:179], v181 offset:9264
	ds_read_b128 v[204:207], v181 offset:9520
	s_waitcnt lgkmcnt(10)
	v_fma_f32 v60, -v46, v208, v60
	v_fma_f32 v61, -v46, v212, v61
	v_fma_f32 v60, -v47, v209, v60
	v_fma_f32 v61, -v47, v213, v61
	v_fma_f32 v60, -v48, v210, v60
	v_fma_f32 v61, -v48, v214, v61
	v_fma_f32 v60, -v49, v211, v60
	v_fma_f32 v61, -v49, v215, v61
	ds_read_b128 v[208:211], v181 offset:9776
	ds_read_b128 v[212:215], v181 offset:10032
	s_waitcnt lgkmcnt(10)
	v_fma_f32 v62, -v46, v144, v62
	v_fma_f32 v63, -v46, v148, v63
	v_fma_f32 v62, -v47, v145, v62
	v_fma_f32 v63, -v47, v149, v63
	v_fma_f32 v62, -v48, v146, v62
	v_fma_f32 v63, -v48, v150, v63
	v_fma_f32 v62, -v49, v147, v62
	v_fma_f32 v63, -v49, v151, v63
	ds_read_b128 v[144:147], v181 offset:10288
	ds_read_b128 v[148:151], v181 offset:10544
	s_waitcnt lgkmcnt(10)
	v_fma_f32 v64, -v46, v152, v64
	v_fma_f32 v65, -v46, v156, v65
	v_fma_f32 v64, -v47, v153, v64
	v_fma_f32 v65, -v47, v157, v65
	v_fma_f32 v64, -v48, v154, v64
	v_fma_f32 v65, -v48, v158, v65
	v_fma_f32 v64, -v49, v155, v64
	v_fma_f32 v65, -v49, v159, v65
	ds_read_b128 v[152:155], v181 offset:10800
	ds_read_b128 v[156:159], v181 offset:11056
	s_waitcnt lgkmcnt(10)
	v_fma_f32 v66, -v46, v160, v66
	v_fma_f32 v67, -v46, v164, v67
	v_fma_f32 v66, -v47, v161, v66
	v_fma_f32 v67, -v47, v165, v67
	v_fma_f32 v66, -v48, v162, v66
	v_fma_f32 v67, -v48, v166, v67
	v_fma_f32 v66, -v49, v163, v66
	v_fma_f32 v67, -v49, v167, v67
	ds_read_b128 v[160:163], v181 offset:11312
	ds_read_b128 v[164:167], v181 offset:11568
	s_waitcnt lgkmcnt(10)
	v_fma_f32 v68, -v46, v168, v68
	v_fma_f32 v69, -v46, v172, v69
	v_fma_f32 v68, -v47, v169, v68
	v_fma_f32 v69, -v47, v173, v69
	v_fma_f32 v68, -v48, v170, v68
	v_fma_f32 v69, -v48, v174, v69
	v_fma_f32 v68, -v49, v171, v68
	v_fma_f32 v69, -v49, v175, v69
	ds_read_b128 v[168:171], v181 offset:11824
	ds_read_b128 v[172:175], v181 offset:12080
	s_waitcnt lgkmcnt(10)
; #define LAS __attribute__((address_space(3)))
; __device__ __forceinline__ void phase_dnprep(ArgsRef a, const Tb tb, int l, LAS unsigned char* lds) {
;     ...
;             for (int jp = 0; jp < 16; ++jp) {
;                 const int r0 = 4 * jp;
;                 const f32x4 d1 = *(LAS const f32x4*)(Lm + (r0 + 1) * 64 + r0), d2 = *(LAS const f32x4*)(Lm + (r0 + 2) * 64 + r0), d3 = *(LAS const f32x4*)(Lm + (r0 + 3) * 64 + r0);
;                 const float x0 = acc[r0];
;                 const float x1 = acc[r0 + 1] - d1[0] * x0;
;                 const float x2 = (acc[r0 + 2] - d2[0] * x0) - d2[1] * x1;
;                 const float x3 = ((acc[r0 + 3] - d3[0] * x0) - d3[1] * x1) - d3[2] * x2;
;                 rhs[(r0 + 0) * 256 + col] = x0; rhs[(r0 + 1) * 256 + col] = x1; rhs[(r0 + 2) * 256 + col] = x2; rhs[(r0 + 3) * 256 + col] = x3;
; #pragma unroll
;                 for (int i = r0 + 4; i < 64; ++i) {
;                     const f32x4 l4 = *(LAS const f32x4*)(Lm + i * 64 + r0);
;                     acc[i] = (((acc[i] - l4[0] * x0) - l4[1] * x1) - l4[2] * x2) - l4[3] * x3;
;                 }
	v_fma_f32 v70, -v46, v176, v70
	v_fma_f32 v71, -v46, v204, v71
	v_fma_f32 v70, -v47, v177, v70
	v_fma_f32 v71, -v47, v205, v71
	v_fma_f32 v70, -v48, v178, v70
	v_fma_f32 v71, -v48, v206, v71
	v_fma_f32 v70, -v49, v179, v70
	v_fma_f32 v71, -v49, v207, v71
	ds_read_b128 v[176:179], v181 offset:12336
	ds_read_b128 v[204:207], v181 offset:12592
	s_waitcnt lgkmcnt(10)
	v_fma_f32 v72, -v46, v208, v72
	v_fma_f32 v73, -v46, v212, v73
	v_fma_f32 v72, -v47, v209, v72
	v_fma_f32 v73, -v47, v213, v73
	v_fma_f32 v72, -v48, v210, v72
	v_fma_f32 v73, -v48, v214, v73
	v_fma_f32 v72, -v49, v211, v72
	v_fma_f32 v73, -v49, v215, v73
	ds_read_b128 v[208:211], v181 offset:12848
	ds_read_b128 v[212:215], v181 offset:13104
	s_waitcnt lgkmcnt(10)
	v_fma_f32 v74, -v46, v144, v74
	v_fma_f32 v75, -v46, v148, v75
	v_fma_f32 v74, -v47, v145, v74
	v_fma_f32 v75, -v47, v149, v75
	v_fma_f32 v74, -v48, v146, v74
	v_fma_f32 v75, -v48, v150, v75
	v_fma_f32 v74, -v49, v147, v74
	v_fma_f32 v75, -v49, v151, v75
	ds_read_b128 v[144:147], v181 offset:13360
	ds_read_b128 v[148:151], v181 offset:13616
	s_waitcnt lgkmcnt(10)
	v_fma_f32 v76, -v46, v152, v76
	v_fma_f32 v77, -v46, v156, v77
	v_fma_f32 v76, -v47, v153, v76
	v_fma_f32 v77, -v47, v157, v77
	v_fma_f32 v76, -v48, v154, v76
	v_fma_f32 v77, -v48, v158, v77
	v_fma_f32 v76, -v49, v155, v76
	v_fma_f32 v77, -v49, v159, v77
	ds_read_b128 v[152:155], v181 offset:13872
	ds_read_b128 v[156:159], v181 offset:14128
	s_waitcnt lgkmcnt(10)
	v_fma_f32 v116, -v46, v160, v116
	v_fma_f32 v117, -v46, v164, v117
	v_fma_f32 v116, -v47, v161, v116
	v_fma_f32 v117, -v47, v165, v117
	v_fma_f32 v116, -v48, v162, v116
	v_fma_f32 v117, -v48, v166, v117
	v_fma_f32 v116, -v49, v163, v116
	v_fma_f32 v117, -v49, v167, v117
	ds_read_b128 v[160:163], v181 offset:14384
	ds_read_b128 v[164:167], v181 offset:14640
	s_waitcnt lgkmcnt(10)
	v_fma_f32 v118, -v46, v168, v118
	v_fma_f32 v119, -v46, v172, v119
	v_fma_f32 v118, -v47, v169, v118
	v_fma_f32 v119, -v47, v173, v119
	v_fma_f32 v118, -v48, v170, v118
	v_fma_f32 v119, -v48, v174, v119
	v_fma_f32 v118, -v49, v171, v118
	v_fma_f32 v119, -v49, v175, v119
	ds_read_b128 v[168:171], v181 offset:14896
	ds_read_b128 v[172:175], v181 offset:15152
	s_waitcnt lgkmcnt(10)
	v_fma_f32 v120, -v46, v176, v120
	v_fma_f32 v121, -v46, v204, v121
	v_fma_f32 v120, -v47, v177, v120
	v_fma_f32 v121, -v47, v205, v121
	v_fma_f32 v120, -v48, v178, v120
	v_fma_f32 v121, -v48, v206, v121
	v_fma_f32 v120, -v49, v179, v120
	v_fma_f32 v121, -v49, v207, v121
	ds_read_b128 v[176:179], v181 offset:15408
	ds_read_b128 v[204:207], v181 offset:15664
	s_waitcnt lgkmcnt(10)
	v_fma_f32 v122, -v46, v208, v122
	v_fma_f32 v123, -v46, v212, v123
	v_fma_f32 v122, -v47, v209, v122
	v_fma_f32 v123, -v47, v213, v123
	v_fma_f32 v122, -v48, v210, v122
	v_fma_f32 v123, -v48, v214, v123
	v_fma_f32 v122, -v49, v211, v122
	v_fma_f32 v123, -v49, v215, v123
	ds_read_b128 v[208:211], v181 offset:15920
	ds_read_b128 v[212:215], v181 offset:16176
	s_waitcnt lgkmcnt(10)
	v_fma_f32 v124, -v46, v144, v124
	v_fma_f32 v125, -v46, v148, v125
	v_fma_f32 v124, -v47, v145, v124
	v_fma_f32 v125, -v47, v149, v125
	v_fma_f32 v124, -v48, v146, v124
	v_fma_f32 v125, -v48, v150, v125
	v_fma_f32 v124, -v49, v147, v124
	v_fma_f32 v125, -v49, v151, v125
	ds_read_b128 v[144:147], v181 offset:4416
	ds_read_b128 v[148:151], v181 offset:4672
	s_waitcnt lgkmcnt(10)
	v_fma_f32 v126, -v46, v152, v126
	v_fma_f32 v127, -v46, v156, v127
	v_fma_f32 v126, -v47, v153, v126
	v_fma_f32 v127, -v47, v157, v127
	v_fma_f32 v126, -v48, v154, v126
	v_fma_f32 v127, -v48, v158, v127
	v_fma_f32 v126, -v49, v155, v126
	v_fma_f32 v127, -v49, v159, v127
	ds_read_b128 v[152:155], v181 offset:4928
	ds_read_b128 v[156:159], v181 offset:5184
	s_waitcnt lgkmcnt(10)
	v_fma_f32 v128, -v46, v160, v128
	v_fma_f32 v129, -v46, v164, v129
	v_fma_f32 v128, -v47, v161, v128
	v_fma_f32 v129, -v47, v165, v129
	v_fma_f32 v128, -v48, v162, v128
	v_fma_f32 v129, -v48, v166, v129
	v_fma_f32 v128, -v49, v163, v128
	v_fma_f32 v129, -v49, v167, v129
	ds_read_b128 v[160:163], v181 offset:5440
	ds_read_b128 v[164:167], v181 offset:5696
	s_waitcnt lgkmcnt(10)
	v_fma_f32 v130, -v46, v168, v130
	v_fma_f32 v131, -v46, v172, v131
	v_fma_f32 v130, -v47, v169, v130
	v_fma_f32 v131, -v47, v173, v131
	v_fma_f32 v130, -v48, v170, v130
	v_fma_f32 v131, -v48, v174, v131
	v_fma_f32 v130, -v49, v171, v130
	v_fma_f32 v131, -v49, v175, v131
	ds_read_b128 v[168:171], v181 offset:5952
	ds_read_b128 v[172:175], v181 offset:6208
	s_waitcnt lgkmcnt(10)
	v_fma_f32 v132, -v46, v176, v132
	v_fma_f32 v133, -v46, v204, v133
	v_fma_f32 v132, -v47, v177, v132
	v_fma_f32 v133, -v47, v205, v133
	v_fma_f32 v132, -v48, v178, v132
	v_fma_f32 v133, -v48, v206, v133
	v_fma_f32 v132, -v49, v179, v132
	v_fma_f32 v133, -v49, v207, v133
	ds_read_b128 v[176:179], v181 offset:6464
	ds_read_b128 v[204:207], v181 offset:6720
	s_waitcnt lgkmcnt(10)
	v_fma_f32 v134, -v46, v208, v134
	v_fma_f32 v135, -v46, v212, v135
	v_fma_f32 v134, -v47, v209, v134
	v_fma_f32 v135, -v47, v213, v135
	v_fma_f32 v134, -v48, v210, v134
	v_fma_f32 v135, -v48, v214, v135
	v_fma_f32 v134, -v49, v211, v134
	v_fma_f32 v135, -v49, v215, v135
	ds_read_b128 v[208:211], v181 offset:6976
	ds_read_b128 v[212:215], v181 offset:7232
	s_waitcnt lgkmcnt(9)
	v_fma_f32 v51, -v50, v144, v51
	v_fma_f32 v52, -v50, v148, v52
	v_fma_f32 v53, -v50, v152, v53
	v_fma_f32 v52, -v149, v51, v52
	v_fma_f32 v53, -v153, v51, v53
	v_fma_f32 v53, -v154, v52, v53
	ds_write_b32 v91, v50 offset:16384
	ds_write_b32 v91, v51 offset:17408
	ds_write_b32 v91, v52 offset:18432
	ds_write_b32 v91, v53 offset:19456
	ds_read_b128 v[144:147], v181 offset:7488
	ds_read_b128 v[148:151], v181 offset:7744
	ds_read_b128 v[152:155], v181 offset:8000
	s_waitcnt lgkmcnt(14)
; #define LAS __attribute__((address_space(3)))
; __device__ __forceinline__ void phase_dnprep(ArgsRef a, const Tb tb, int l, LAS unsigned char* lds) {
;     ...
;             for (int jp = 0; jp < 16; ++jp) {
;                 const int r0 = 4 * jp;
;                 const f32x4 d1 = *(LAS const f32x4*)(Lm + (r0 + 1) * 64 + r0), d2 = *(LAS const f32x4*)(Lm + (r0 + 2) * 64 + r0), d3 = *(LAS const f32x4*)(Lm + (r0 + 3) * 64 + r0);
;                 const float x0 = acc[r0];
;                 const float x1 = acc[r0 + 1] - d1[0] * x0;
;                 const float x2 = (acc[r0 + 2] - d2[0] * x0) - d2[1] * x1;
;                 const float x3 = ((acc[r0 + 3] - d3[0] * x0) - d3[1] * x1) - d3[2] * x2;
;                 rhs[(r0 + 0) * 256 + col] = x0; rhs[(r0 + 1) * 256 + col] = x1; rhs[(r0 + 2) * 256 + col] = x2; rhs[(r0 + 3) * 256 + col] = x3;
; #pragma unroll
;                 for (int i = r0 + 4; i < 64; ++i) {
;                     const f32x4 l4 = *(LAS const f32x4*)(Lm + i * 64 + r0);
;                     acc[i] = (((acc[i] - l4[0] * x0) - l4[1] * x1) - l4[2] * x2) - l4[3] * x3;
;                 }
	v_fma_f32 v54, -v50, v156, v54
	v_fma_f32 v55, -v50, v160, v55
	v_fma_f32 v54, -v51, v157, v54
	v_fma_f32 v55, -v51, v161, v55
	v_fma_f32 v54, -v52, v158, v54
	v_fma_f32 v55, -v52, v162, v55
	v_fma_f32 v54, -v53, v159, v54
	v_fma_f32 v55, -v53, v163, v55
	ds_read_b128 v[156:159], v181 offset:8256
	ds_read_b128 v[160:163], v181 offset:8512
	s_waitcnt lgkmcnt(14)
	v_fma_f32 v56, -v50, v164, v56
	v_fma_f32 v57, -v50, v168, v57
	v_fma_f32 v56, -v51, v165, v56
	v_fma_f32 v57, -v51, v169, v57
	v_fma_f32 v56, -v52, v166, v56
	v_fma_f32 v57, -v52, v170, v57
	v_fma_f32 v56, -v53, v167, v56
	v_fma_f32 v57, -v53, v171, v57
	ds_read_b128 v[164:167], v181 offset:8768
	ds_read_b128 v[168:171], v181 offset:9024
	s_waitcnt lgkmcnt(14)
	v_fma_f32 v58, -v50, v172, v58
	v_fma_f32 v59, -v50, v176, v59
	v_fma_f32 v58, -v51, v173, v58
	v_fma_f32 v59, -v51, v177, v59
	v_fma_f32 v58, -v52, v174, v58
	v_fma_f32 v59, -v52, v178, v59
	v_fma_f32 v58, -v53, v175, v58
	v_fma_f32 v59, -v53, v179, v59
	ds_read_b128 v[172:175], v181 offset:9280
	ds_read_b128 v[176:179], v181 offset:9536
	s_waitcnt lgkmcnt(14)
	v_fma_f32 v60, -v50, v204, v60
	v_fma_f32 v61, -v50, v208, v61
	v_fma_f32 v60, -v51, v205, v60
	v_fma_f32 v61, -v51, v209, v61
	v_fma_f32 v60, -v52, v206, v60
	v_fma_f32 v61, -v52, v210, v61
	v_fma_f32 v60, -v53, v207, v60
	v_fma_f32 v61, -v53, v211, v61
	ds_read_b128 v[204:207], v181 offset:9792
	ds_read_b128 v[208:211], v181 offset:10048
	s_waitcnt lgkmcnt(10)
	v_fma_f32 v62, -v50, v212, v62
	v_fma_f32 v63, -v50, v144, v63
	v_fma_f32 v62, -v51, v213, v62
	v_fma_f32 v63, -v51, v145, v63
	v_fma_f32 v62, -v52, v214, v62
	v_fma_f32 v63, -v52, v146, v63
	v_fma_f32 v62, -v53, v215, v62
	v_fma_f32 v63, -v53, v147, v63
	ds_read_b128 v[212:215], v181 offset:10304
	ds_read_b128 v[144:147], v181 offset:10560
	s_waitcnt lgkmcnt(10)
	v_fma_f32 v64, -v50, v148, v64
	v_fma_f32 v65, -v50, v152, v65
	v_fma_f32 v64, -v51, v149, v64
	v_fma_f32 v65, -v51, v153, v65
	v_fma_f32 v64, -v52, v150, v64
	v_fma_f32 v65, -v52, v154, v65
	v_fma_f32 v64, -v53, v151, v64
	v_fma_f32 v65, -v53, v155, v65
	ds_read_b128 v[148:151], v181 offset:10816
	ds_read_b128 v[152:155], v181 offset:11072
	s_waitcnt lgkmcnt(10)
	v_fma_f32 v66, -v50, v156, v66
	v_fma_f32 v67, -v50, v160, v67
	v_fma_f32 v66, -v51, v157, v66
	v_fma_f32 v67, -v51, v161, v67
	v_fma_f32 v66, -v52, v158, v66
	v_fma_f32 v67, -v52, v162, v67
	v_fma_f32 v66, -v53, v159, v66
	v_fma_f32 v67, -v53, v163, v67
	ds_read_b128 v[156:159], v181 offset:11328
	ds_read_b128 v[160:163], v181 offset:11584
	s_waitcnt lgkmcnt(10)
	v_fma_f32 v68, -v50, v164, v68
	v_fma_f32 v69, -v50, v168, v69
	v_fma_f32 v68, -v51, v165, v68
	v_fma_f32 v69, -v51, v169, v69
	v_fma_f32 v68, -v52, v166, v68
	v_fma_f32 v69, -v52, v170, v69
	v_fma_f32 v68, -v53, v167, v68
	v_fma_f32 v69, -v53, v171, v69
	ds_read_b128 v[164:167], v181 offset:11840
	ds_read_b128 v[168:171], v181 offset:12096
	s_waitcnt lgkmcnt(10)
	v_fma_f32 v70, -v50, v172, v70
	v_fma_f32 v71, -v50, v176, v71
	v_fma_f32 v70, -v51, v173, v70
	v_fma_f32 v71, -v51, v177, v71
	v_fma_f32 v70, -v52, v174, v70
	v_fma_f32 v71, -v52, v178, v71
	v_fma_f32 v70, -v53, v175, v70
	v_fma_f32 v71, -v53, v179, v71
	ds_read_b128 v[172:175], v181 offset:12352
	ds_read_b128 v[176:179], v181 offset:12608
	s_waitcnt lgkmcnt(10)
	v_fma_f32 v72, -v50, v204, v72
	v_fma_f32 v73, -v50, v208, v73
	v_fma_f32 v72, -v51, v205, v72
	v_fma_f32 v73, -v51, v209, v73
	v_fma_f32 v72, -v52, v206, v72
	v_fma_f32 v73, -v52, v210, v73
	v_fma_f32 v72, -v53, v207, v72
	v_fma_f32 v73, -v53, v211, v73
	ds_read_b128 v[204:207], v181 offset:12864
	ds_read_b128 v[208:211], v181 offset:13120
	s_waitcnt lgkmcnt(10)
	v_fma_f32 v74, -v50, v212, v74
	v_fma_f32 v75, -v50, v144, v75
	v_fma_f32 v74, -v51, v213, v74
	v_fma_f32 v75, -v51, v145, v75
	v_fma_f32 v74, -v52, v214, v74
	v_fma_f32 v75, -v52, v146, v75
	v_fma_f32 v74, -v53, v215, v74
	v_fma_f32 v75, -v53, v147, v75
	ds_read_b128 v[212:215], v181 offset:13376
	ds_read_b128 v[144:147], v181 offset:13632
	s_waitcnt lgkmcnt(10)
	v_fma_f32 v76, -v50, v148, v76
	v_fma_f32 v77, -v50, v152, v77
	v_fma_f32 v76, -v51, v149, v76
	v_fma_f32 v77, -v51, v153, v77
	v_fma_f32 v76, -v52, v150, v76
	v_fma_f32 v77, -v52, v154, v77
	v_fma_f32 v76, -v53, v151, v76
	v_fma_f32 v77, -v53, v155, v77
	ds_read_b128 v[148:151], v181 offset:13888
	ds_read_b128 v[152:155], v181 offset:14144
	s_waitcnt lgkmcnt(10)
	v_fma_f32 v116, -v50, v156, v116
	v_fma_f32 v117, -v50, v160, v117
	v_fma_f32 v116, -v51, v157, v116
	v_fma_f32 v117, -v51, v161, v117
	v_fma_f32 v116, -v52, v158, v116
	v_fma_f32 v117, -v52, v162, v117
	v_fma_f32 v116, -v53, v159, v116
	v_fma_f32 v117, -v53, v163, v117
	ds_read_b128 v[156:159], v181 offset:14400
	ds_read_b128 v[160:163], v181 offset:14656
	s_waitcnt lgkmcnt(10)
	v_fma_f32 v118, -v50, v164, v118
	v_fma_f32 v119, -v50, v168, v119
	v_fma_f32 v118, -v51, v165, v118
	v_fma_f32 v119, -v51, v169, v119
	v_fma_f32 v118, -v52, v166, v118
	v_fma_f32 v119, -v52, v170, v119
	v_fma_f32 v118, -v53, v167, v118
	v_fma_f32 v119, -v53, v171, v119
	ds_read_b128 v[164:167], v181 offset:14912
	ds_read_b128 v[168:171], v181 offset:15168
	s_waitcnt lgkmcnt(10)
	v_fma_f32 v120, -v50, v172, v120
	v_fma_f32 v121, -v50, v176, v121
	v_fma_f32 v120, -v51, v173, v120
	v_fma_f32 v121, -v51, v177, v121
	v_fma_f32 v120, -v52, v174, v120
	v_fma_f32 v121, -v52, v178, v121
	v_fma_f32 v120, -v53, v175, v120
	v_fma_f32 v121, -v53, v179, v121
	ds_read_b128 v[172:175], v181 offset:15424
	ds_read_b128 v[176:179], v181 offset:15680
	s_waitcnt lgkmcnt(10)
; #define LAS __attribute__((address_space(3)))
; __device__ __forceinline__ void phase_dnprep(ArgsRef a, const Tb tb, int l, LAS unsigned char* lds) {
;     ...
;             for (int jp = 0; jp < 16; ++jp) {
;                 const int r0 = 4 * jp;
;                 const f32x4 d1 = *(LAS const f32x4*)(Lm + (r0 + 1) * 64 + r0), d2 = *(LAS const f32x4*)(Lm + (r0 + 2) * 64 + r0), d3 = *(LAS const f32x4*)(Lm + (r0 + 3) * 64 + r0);
;                 const float x0 = acc[r0];
;                 const float x1 = acc[r0 + 1] - d1[0] * x0;
;                 const float x2 = (acc[r0 + 2] - d2[0] * x0) - d2[1] * x1;
;                 const float x3 = ((acc[r0 + 3] - d3[0] * x0) - d3[1] * x1) - d3[2] * x2;
;                 rhs[(r0 + 0) * 256 + col] = x0; rhs[(r0 + 1) * 256 + col] = x1; rhs[(r0 + 2) * 256 + col] = x2; rhs[(r0 + 3) * 256 + col] = x3;
; #pragma unroll
;                 for (int i = r0 + 4; i < 64; ++i) {
;                     const f32x4 l4 = *(LAS const f32x4*)(Lm + i * 64 + r0);
;                     acc[i] = (((acc[i] - l4[0] * x0) - l4[1] * x1) - l4[2] * x2) - l4[3] * x3;
;                 }
	v_fma_f32 v122, -v50, v204, v122
	v_fma_f32 v123, -v50, v208, v123
	v_fma_f32 v122, -v51, v205, v122
	v_fma_f32 v123, -v51, v209, v123
	v_fma_f32 v122, -v52, v206, v122
	v_fma_f32 v123, -v52, v210, v123
	v_fma_f32 v122, -v53, v207, v122
	v_fma_f32 v123, -v53, v211, v123
	ds_read_b128 v[204:207], v181 offset:15936
	ds_read_b128 v[208:211], v181 offset:16192
	s_waitcnt lgkmcnt(10)
	v_fma_f32 v124, -v50, v212, v124
	v_fma_f32 v125, -v50, v144, v125
	v_fma_f32 v124, -v51, v213, v124
	v_fma_f32 v125, -v51, v145, v125
	v_fma_f32 v124, -v52, v214, v124
	v_fma_f32 v125, -v52, v146, v125
	v_fma_f32 v124, -v53, v215, v124
	v_fma_f32 v125, -v53, v147, v125
	ds_read_b128 v[212:215], v181 offset:5456
	ds_read_b128 v[144:147], v181 offset:5712
	s_waitcnt lgkmcnt(10)
	v_fma_f32 v126, -v50, v148, v126
	v_fma_f32 v127, -v50, v152, v127
	v_fma_f32 v126, -v51, v149, v126
	v_fma_f32 v127, -v51, v153, v127
	v_fma_f32 v126, -v52, v150, v126
	v_fma_f32 v127, -v52, v154, v127
	v_fma_f32 v126, -v53, v151, v126
	v_fma_f32 v127, -v53, v155, v127
	ds_read_b128 v[148:151], v181 offset:5968
	ds_read_b128 v[152:155], v181 offset:6224
	s_waitcnt lgkmcnt(10)
	v_fma_f32 v128, -v50, v156, v128
	v_fma_f32 v129, -v50, v160, v129
	v_fma_f32 v128, -v51, v157, v128
	v_fma_f32 v129, -v51, v161, v129
	v_fma_f32 v128, -v52, v158, v128
	v_fma_f32 v129, -v52, v162, v129
	v_fma_f32 v128, -v53, v159, v128
	v_fma_f32 v129, -v53, v163, v129
	ds_read_b128 v[156:159], v181 offset:6480
	ds_read_b128 v[160:163], v181 offset:6736
	s_waitcnt lgkmcnt(10)
	v_fma_f32 v130, -v50, v164, v130
	v_fma_f32 v131, -v50, v168, v131
	v_fma_f32 v130, -v51, v165, v130
	v_fma_f32 v131, -v51, v169, v131
	v_fma_f32 v130, -v52, v166, v130
	v_fma_f32 v131, -v52, v170, v131
	v_fma_f32 v130, -v53, v167, v130
	v_fma_f32 v131, -v53, v171, v131
	ds_read_b128 v[164:167], v181 offset:6992
	ds_read_b128 v[168:171], v181 offset:7248
	s_waitcnt lgkmcnt(10)
	v_fma_f32 v132, -v50, v172, v132
	v_fma_f32 v133, -v50, v176, v133
	v_fma_f32 v132, -v51, v173, v132
	v_fma_f32 v133, -v51, v177, v133
	v_fma_f32 v132, -v52, v174, v132
	v_fma_f32 v133, -v52, v178, v133
	v_fma_f32 v132, -v53, v175, v132
	v_fma_f32 v133, -v53, v179, v133
	ds_read_b128 v[172:175], v181 offset:7504
	ds_read_b128 v[176:179], v181 offset:7760
	s_waitcnt lgkmcnt(10)
	v_fma_f32 v134, -v50, v204, v134
	v_fma_f32 v135, -v50, v208, v135
	v_fma_f32 v134, -v51, v205, v134
	v_fma_f32 v135, -v51, v209, v135
	v_fma_f32 v134, -v52, v206, v134
	v_fma_f32 v135, -v52, v210, v135
	v_fma_f32 v134, -v53, v207, v134
	v_fma_f32 v135, -v53, v211, v135
	ds_read_b128 v[204:207], v181 offset:8016
	ds_read_b128 v[208:211], v181 offset:8272
	s_waitcnt lgkmcnt(9)
	v_fma_f32 v55, -v54, v212, v55
	v_fma_f32 v56, -v54, v144, v56
	v_fma_f32 v57, -v54, v148, v57
	v_fma_f32 v56, -v145, v55, v56
	v_fma_f32 v57, -v149, v55, v57
	v_fma_f32 v57, -v150, v56, v57
	ds_write_b32 v91, v54 offset:20480
	ds_write_b32 v91, v55 offset:21504
	ds_write_b32 v91, v56 offset:22528
	ds_write_b32 v91, v57 offset:23552
	ds_read_b128 v[212:215], v181 offset:8528
	ds_read_b128 v[144:147], v181 offset:8784
	ds_read_b128 v[148:151], v181 offset:9040
	s_waitcnt lgkmcnt(14)
	v_fma_f32 v58, -v54, v152, v58
	v_fma_f32 v59, -v54, v156, v59
	v_fma_f32 v58, -v55, v153, v58
	v_fma_f32 v59, -v55, v157, v59
	v_fma_f32 v58, -v56, v154, v58
	v_fma_f32 v59, -v56, v158, v59
	v_fma_f32 v58, -v57, v155, v58
	v_fma_f32 v59, -v57, v159, v59
	ds_read_b128 v[152:155], v181 offset:9296
	ds_read_b128 v[156:159], v181 offset:9552
	s_waitcnt lgkmcnt(14)
	v_fma_f32 v60, -v54, v160, v60
	v_fma_f32 v61, -v54, v164, v61
	v_fma_f32 v60, -v55, v161, v60
	v_fma_f32 v61, -v55, v165, v61
	v_fma_f32 v60, -v56, v162, v60
	v_fma_f32 v61, -v56, v166, v61
	v_fma_f32 v60, -v57, v163, v60
	v_fma_f32 v61, -v57, v167, v61
	ds_read_b128 v[160:163], v181 offset:9808
	ds_read_b128 v[164:167], v181 offset:10064
	s_waitcnt lgkmcnt(14)
	v_fma_f32 v62, -v54, v168, v62
	v_fma_f32 v63, -v54, v172, v63
	v_fma_f32 v62, -v55, v169, v62
	v_fma_f32 v63, -v55, v173, v63
	v_fma_f32 v62, -v56, v170, v62
	v_fma_f32 v63, -v56, v174, v63
	v_fma_f32 v62, -v57, v171, v62
	v_fma_f32 v63, -v57, v175, v63
	ds_read_b128 v[168:171], v181 offset:10320
	ds_read_b128 v[172:175], v181 offset:10576
	s_waitcnt lgkmcnt(14)
	v_fma_f32 v64, -v54, v176, v64
	v_fma_f32 v65, -v54, v204, v65
	v_fma_f32 v64, -v55, v177, v64
	v_fma_f32 v65, -v55, v205, v65
	v_fma_f32 v64, -v56, v178, v64
	v_fma_f32 v65, -v56, v206, v65
	v_fma_f32 v64, -v57, v179, v64
	v_fma_f32 v65, -v57, v207, v65
	ds_read_b128 v[176:179], v181 offset:10832
	ds_read_b128 v[204:207], v181 offset:11088
	s_waitcnt lgkmcnt(10)
	v_fma_f32 v66, -v54, v208, v66
	v_fma_f32 v67, -v54, v212, v67
	v_fma_f32 v66, -v55, v209, v66
	v_fma_f32 v67, -v55, v213, v67
	v_fma_f32 v66, -v56, v210, v66
	v_fma_f32 v67, -v56, v214, v67
	v_fma_f32 v66, -v57, v211, v66
	v_fma_f32 v67, -v57, v215, v67
	ds_read_b128 v[208:211], v181 offset:11344
	ds_read_b128 v[212:215], v181 offset:11600
	s_waitcnt lgkmcnt(10)
	v_fma_f32 v68, -v54, v144, v68
	v_fma_f32 v69, -v54, v148, v69
	v_fma_f32 v68, -v55, v145, v68
	v_fma_f32 v69, -v55, v149, v69
	v_fma_f32 v68, -v56, v146, v68
	v_fma_f32 v69, -v56, v150, v69
	v_fma_f32 v68, -v57, v147, v68
	v_fma_f32 v69, -v57, v151, v69
	ds_read_b128 v[144:147], v181 offset:11856
	ds_read_b128 v[148:151], v181 offset:12112
	s_waitcnt lgkmcnt(10)
	v_fma_f32 v70, -v54, v152, v70
	v_fma_f32 v71, -v54, v156, v71
	v_fma_f32 v70, -v55, v153, v70
	v_fma_f32 v71, -v55, v157, v71
	v_fma_f32 v70, -v56, v154, v70
	v_fma_f32 v71, -v56, v158, v71
	v_fma_f32 v70, -v57, v155, v70
	v_fma_f32 v71, -v57, v159, v71
	ds_read_b128 v[152:155], v181 offset:12368
	ds_read_b128 v[156:159], v181 offset:12624
	s_waitcnt lgkmcnt(10)
; #define LAS __attribute__((address_space(3)))
; __device__ __forceinline__ void phase_dnprep(ArgsRef a, const Tb tb, int l, LAS unsigned char* lds) {
;     ...
;             for (int jp = 0; jp < 16; ++jp) {
;                 const int r0 = 4 * jp;
;                 const f32x4 d1 = *(LAS const f32x4*)(Lm + (r0 + 1) * 64 + r0), d2 = *(LAS const f32x4*)(Lm + (r0 + 2) * 64 + r0), d3 = *(LAS const f32x4*)(Lm + (r0 + 3) * 64 + r0);
;                 const float x0 = acc[r0];
;                 const float x1 = acc[r0 + 1] - d1[0] * x0;
;                 const float x2 = (acc[r0 + 2] - d2[0] * x0) - d2[1] * x1;
;                 const float x3 = ((acc[r0 + 3] - d3[0] * x0) - d3[1] * x1) - d3[2] * x2;
;                 rhs[(r0 + 0) * 256 + col] = x0; rhs[(r0 + 1) * 256 + col] = x1; rhs[(r0 + 2) * 256 + col] = x2; rhs[(r0 + 3) * 256 + col] = x3;
; #pragma unroll
;                 for (int i = r0 + 4; i < 64; ++i) {
;                     const f32x4 l4 = *(LAS const f32x4*)(Lm + i * 64 + r0);
;                     acc[i] = (((acc[i] - l4[0] * x0) - l4[1] * x1) - l4[2] * x2) - l4[3] * x3;
;                 }
	v_fma_f32 v72, -v54, v160, v72
	v_fma_f32 v73, -v54, v164, v73
	v_fma_f32 v72, -v55, v161, v72
	v_fma_f32 v73, -v55, v165, v73
	v_fma_f32 v72, -v56, v162, v72
	v_fma_f32 v73, -v56, v166, v73
	v_fma_f32 v72, -v57, v163, v72
	v_fma_f32 v73, -v57, v167, v73
	ds_read_b128 v[160:163], v181 offset:12880
	ds_read_b128 v[164:167], v181 offset:13136
	s_waitcnt lgkmcnt(10)
	v_fma_f32 v74, -v54, v168, v74
	v_fma_f32 v75, -v54, v172, v75
	v_fma_f32 v74, -v55, v169, v74
	v_fma_f32 v75, -v55, v173, v75
	v_fma_f32 v74, -v56, v170, v74
	v_fma_f32 v75, -v56, v174, v75
	v_fma_f32 v74, -v57, v171, v74
	v_fma_f32 v75, -v57, v175, v75
	ds_read_b128 v[168:171], v181 offset:13392
	ds_read_b128 v[172:175], v181 offset:13648
	s_waitcnt lgkmcnt(10)
	v_fma_f32 v76, -v54, v176, v76
	v_fma_f32 v77, -v54, v204, v77
	v_fma_f32 v76, -v55, v177, v76
	v_fma_f32 v77, -v55, v205, v77
	v_fma_f32 v76, -v56, v178, v76
	v_fma_f32 v77, -v56, v206, v77
	v_fma_f32 v76, -v57, v179, v76
	v_fma_f32 v77, -v57, v207, v77
	ds_read_b128 v[176:179], v181 offset:13904
	ds_read_b128 v[204:207], v181 offset:14160
	s_waitcnt lgkmcnt(10)
	v_fma_f32 v116, -v54, v208, v116
	v_fma_f32 v117, -v54, v212, v117
	v_fma_f32 v116, -v55, v209, v116
	v_fma_f32 v117, -v55, v213, v117
	v_fma_f32 v116, -v56, v210, v116
	v_fma_f32 v117, -v56, v214, v117
	v_fma_f32 v116, -v57, v211, v116
	v_fma_f32 v117, -v57, v215, v117
	ds_read_b128 v[208:211], v181 offset:14416
	ds_read_b128 v[212:215], v181 offset:14672
	s_waitcnt lgkmcnt(10)
	v_fma_f32 v118, -v54, v144, v118
	v_fma_f32 v119, -v54, v148, v119
	v_fma_f32 v118, -v55, v145, v118
	v_fma_f32 v119, -v55, v149, v119
	v_fma_f32 v118, -v56, v146, v118
	v_fma_f32 v119, -v56, v150, v119
	v_fma_f32 v118, -v57, v147, v118
	v_fma_f32 v119, -v57, v151, v119
	ds_read_b128 v[144:147], v181 offset:14928
	ds_read_b128 v[148:151], v181 offset:15184
	s_waitcnt lgkmcnt(10)
	v_fma_f32 v120, -v54, v152, v120
	v_fma_f32 v121, -v54, v156, v121
	v_fma_f32 v120, -v55, v153, v120
	v_fma_f32 v121, -v55, v157, v121
	v_fma_f32 v120, -v56, v154, v120
	v_fma_f32 v121, -v56, v158, v121
	v_fma_f32 v120, -v57, v155, v120
	v_fma_f32 v121, -v57, v159, v121
	ds_read_b128 v[152:155], v181 offset:15440
	ds_read_b128 v[156:159], v181 offset:15696
	s_waitcnt lgkmcnt(10)
	v_fma_f32 v122, -v54, v160, v122
	v_fma_f32 v123, -v54, v164, v123
	v_fma_f32 v122, -v55, v161, v122
	v_fma_f32 v123, -v55, v165, v123
	v_fma_f32 v122, -v56, v162, v122
	v_fma_f32 v123, -v56, v166, v123
	v_fma_f32 v122, -v57, v163, v122
	v_fma_f32 v123, -v57, v167, v123
	ds_read_b128 v[160:163], v181 offset:15952
	ds_read_b128 v[164:167], v181 offset:16208
	s_waitcnt lgkmcnt(10)
	v_fma_f32 v124, -v54, v168, v124
	v_fma_f32 v125, -v54, v172, v125
	v_fma_f32 v124, -v55, v169, v124
	v_fma_f32 v125, -v55, v173, v125
	v_fma_f32 v124, -v56, v170, v124
	v_fma_f32 v125, -v56, v174, v125
	v_fma_f32 v124, -v57, v171, v124
	v_fma_f32 v125, -v57, v175, v125
	ds_read_b128 v[168:171], v181 offset:6496
	ds_read_b128 v[172:175], v181 offset:6752
	s_waitcnt lgkmcnt(10)
	v_fma_f32 v126, -v54, v176, v126
	v_fma_f32 v127, -v54, v204, v127
	v_fma_f32 v126, -v55, v177, v126
	v_fma_f32 v127, -v55, v205, v127
	v_fma_f32 v126, -v56, v178, v126
	v_fma_f32 v127, -v56, v206, v127
	v_fma_f32 v126, -v57, v179, v126
	v_fma_f32 v127, -v57, v207, v127
	ds_read_b128 v[176:179], v181 offset:7008
	ds_read_b128 v[204:207], v181 offset:7264
	s_waitcnt lgkmcnt(10)
	v_fma_f32 v128, -v54, v208, v128
	v_fma_f32 v129, -v54, v212, v129
	v_fma_f32 v128, -v55, v209, v128
	v_fma_f32 v129, -v55, v213, v129
	v_fma_f32 v128, -v56, v210, v128
	v_fma_f32 v129, -v56, v214, v129
	v_fma_f32 v128, -v57, v211, v128
	v_fma_f32 v129, -v57, v215, v129
	ds_read_b128 v[208:211], v181 offset:7520
	ds_read_b128 v[212:215], v181 offset:7776
	s_waitcnt lgkmcnt(10)
	v_fma_f32 v130, -v54, v144, v130
	v_fma_f32 v131, -v54, v148, v131
	v_fma_f32 v130, -v55, v145, v130
	v_fma_f32 v131, -v55, v149, v131
	v_fma_f32 v130, -v56, v146, v130
	v_fma_f32 v131, -v56, v150, v131
	v_fma_f32 v130, -v57, v147, v130
	v_fma_f32 v131, -v57, v151, v131
	ds_read_b128 v[144:147], v181 offset:8032
	ds_read_b128 v[148:151], v181 offset:8288
	s_waitcnt lgkmcnt(10)
	v_fma_f32 v132, -v54, v152, v132
	v_fma_f32 v133, -v54, v156, v133
	v_fma_f32 v132, -v55, v153, v132
	v_fma_f32 v133, -v55, v157, v133
	v_fma_f32 v132, -v56, v154, v132
	v_fma_f32 v133, -v56, v158, v133
	v_fma_f32 v132, -v57, v155, v132
	v_fma_f32 v133, -v57, v159, v133
	ds_read_b128 v[152:155], v181 offset:8544
	ds_read_b128 v[156:159], v181 offset:8800
	s_waitcnt lgkmcnt(10)
	v_fma_f32 v134, -v54, v160, v134
	v_fma_f32 v135, -v54, v164, v135
	v_fma_f32 v134, -v55, v161, v134
	v_fma_f32 v135, -v55, v165, v135
	v_fma_f32 v134, -v56, v162, v134
	v_fma_f32 v135, -v56, v166, v135
	v_fma_f32 v134, -v57, v163, v134
	v_fma_f32 v135, -v57, v167, v135
	ds_read_b128 v[160:163], v181 offset:9056
	ds_read_b128 v[164:167], v181 offset:9312
	s_waitcnt lgkmcnt(9)
	v_fma_f32 v59, -v58, v168, v59
	v_fma_f32 v60, -v58, v172, v60
	v_fma_f32 v61, -v58, v176, v61
	v_fma_f32 v60, -v173, v59, v60
	v_fma_f32 v61, -v177, v59, v61
	v_fma_f32 v61, -v178, v60, v61
	ds_write_b32 v91, v58 offset:24576
	ds_write_b32 v91, v59 offset:25600
	ds_write_b32 v91, v60 offset:26624
	ds_write_b32 v91, v61 offset:27648
	ds_read_b128 v[168:171], v181 offset:9568
	ds_read_b128 v[172:175], v181 offset:9824
	ds_read_b128 v[176:179], v181 offset:10080
	s_waitcnt lgkmcnt(14)
	v_fma_f32 v62, -v58, v204, v62
	v_fma_f32 v63, -v58, v208, v63
	v_fma_f32 v62, -v59, v205, v62
	v_fma_f32 v63, -v59, v209, v63
	v_fma_f32 v62, -v60, v206, v62
	v_fma_f32 v63, -v60, v210, v63
	v_fma_f32 v62, -v61, v207, v62
	v_fma_f32 v63, -v61, v211, v63
	ds_read_b128 v[204:207], v181 offset:10336
	ds_read_b128 v[208:211], v181 offset:10592
	s_waitcnt lgkmcnt(14)
; #define LAS __attribute__((address_space(3)))
; __device__ __forceinline__ void phase_dnprep(ArgsRef a, const Tb tb, int l, LAS unsigned char* lds) {
;     ...
;             for (int jp = 0; jp < 16; ++jp) {
;                 const int r0 = 4 * jp;
;                 const f32x4 d1 = *(LAS const f32x4*)(Lm + (r0 + 1) * 64 + r0), d2 = *(LAS const f32x4*)(Lm + (r0 + 2) * 64 + r0), d3 = *(LAS const f32x4*)(Lm + (r0 + 3) * 64 + r0);
;                 const float x0 = acc[r0];
;                 const float x1 = acc[r0 + 1] - d1[0] * x0;
;                 const float x2 = (acc[r0 + 2] - d2[0] * x0) - d2[1] * x1;
;                 const float x3 = ((acc[r0 + 3] - d3[0] * x0) - d3[1] * x1) - d3[2] * x2;
;                 rhs[(r0 + 0) * 256 + col] = x0; rhs[(r0 + 1) * 256 + col] = x1; rhs[(r0 + 2) * 256 + col] = x2; rhs[(r0 + 3) * 256 + col] = x3;
; #pragma unroll
;                 for (int i = r0 + 4; i < 64; ++i) {
;                     const f32x4 l4 = *(LAS const f32x4*)(Lm + i * 64 + r0);
;                     acc[i] = (((acc[i] - l4[0] * x0) - l4[1] * x1) - l4[2] * x2) - l4[3] * x3;
;                 }
	v_fma_f32 v64, -v58, v212, v64
	v_fma_f32 v65, -v58, v144, v65
	v_fma_f32 v64, -v59, v213, v64
	v_fma_f32 v65, -v59, v145, v65
	v_fma_f32 v64, -v60, v214, v64
	v_fma_f32 v65, -v60, v146, v65
	v_fma_f32 v64, -v61, v215, v64
	v_fma_f32 v65, -v61, v147, v65
	ds_read_b128 v[212:215], v181 offset:10848
	ds_read_b128 v[144:147], v181 offset:11104
	s_waitcnt lgkmcnt(14)
	v_fma_f32 v66, -v58, v148, v66
	v_fma_f32 v67, -v58, v152, v67
	v_fma_f32 v66, -v59, v149, v66
	v_fma_f32 v67, -v59, v153, v67
	v_fma_f32 v66, -v60, v150, v66
	v_fma_f32 v67, -v60, v154, v67
	v_fma_f32 v66, -v61, v151, v66
	v_fma_f32 v67, -v61, v155, v67
	ds_read_b128 v[148:151], v181 offset:11360
	ds_read_b128 v[152:155], v181 offset:11616
	s_waitcnt lgkmcnt(14)
	v_fma_f32 v68, -v58, v156, v68
	v_fma_f32 v69, -v58, v160, v69
	v_fma_f32 v68, -v59, v157, v68
	v_fma_f32 v69, -v59, v161, v69
	v_fma_f32 v68, -v60, v158, v68
	v_fma_f32 v69, -v60, v162, v69
	v_fma_f32 v68, -v61, v159, v68
	v_fma_f32 v69, -v61, v163, v69
	ds_read_b128 v[156:159], v181 offset:11872
	ds_read_b128 v[160:163], v181 offset:12128
	s_waitcnt lgkmcnt(10)
	v_fma_f32 v70, -v58, v164, v70
	v_fma_f32 v71, -v58, v168, v71
	v_fma_f32 v70, -v59, v165, v70
	v_fma_f32 v71, -v59, v169, v71
	v_fma_f32 v70, -v60, v166, v70
	v_fma_f32 v71, -v60, v170, v71
	v_fma_f32 v70, -v61, v167, v70
	v_fma_f32 v71, -v61, v171, v71
	ds_read_b128 v[164:167], v181 offset:12384
	ds_read_b128 v[168:171], v181 offset:12640
	s_waitcnt lgkmcnt(10)
	v_fma_f32 v72, -v58, v172, v72
	v_fma_f32 v73, -v58, v176, v73
	v_fma_f32 v72, -v59, v173, v72
	v_fma_f32 v73, -v59, v177, v73
	v_fma_f32 v72, -v60, v174, v72
	v_fma_f32 v73, -v60, v178, v73
	v_fma_f32 v72, -v61, v175, v72
	v_fma_f32 v73, -v61, v179, v73
	ds_read_b128 v[172:175], v181 offset:12896
	ds_read_b128 v[176:179], v181 offset:13152
	s_waitcnt lgkmcnt(10)
	v_fma_f32 v74, -v58, v204, v74
	v_fma_f32 v75, -v58, v208, v75
	v_fma_f32 v74, -v59, v205, v74
	v_fma_f32 v75, -v59, v209, v75
	v_fma_f32 v74, -v60, v206, v74
	v_fma_f32 v75, -v60, v210, v75
	v_fma_f32 v74, -v61, v207, v74
	v_fma_f32 v75, -v61, v211, v75
	ds_read_b128 v[204:207], v181 offset:13408
	ds_read_b128 v[208:211], v181 offset:13664
	s_waitcnt lgkmcnt(10)
	v_fma_f32 v76, -v58, v212, v76
	v_fma_f32 v77, -v58, v144, v77
	v_fma_f32 v76, -v59, v213, v76
	v_fma_f32 v77, -v59, v145, v77
	v_fma_f32 v76, -v60, v214, v76
	v_fma_f32 v77, -v60, v146, v77
	v_fma_f32 v76, -v61, v215, v76
	v_fma_f32 v77, -v61, v147, v77
	ds_read_b128 v[212:215], v181 offset:13920
	ds_read_b128 v[144:147], v181 offset:14176
	s_waitcnt lgkmcnt(10)
	v_fma_f32 v116, -v58, v148, v116
	v_fma_f32 v117, -v58, v152, v117
	v_fma_f32 v116, -v59, v149, v116
	v_fma_f32 v117, -v59, v153, v117
	v_fma_f32 v116, -v60, v150, v116
	v_fma_f32 v117, -v60, v154, v117
	v_fma_f32 v116, -v61, v151, v116
	v_fma_f32 v117, -v61, v155, v117
	ds_read_b128 v[148:151], v181 offset:14432
	ds_read_b128 v[152:155], v181 offset:14688
	s_waitcnt lgkmcnt(10)
	v_fma_f32 v118, -v58, v156, v118
	v_fma_f32 v119, -v58, v160, v119
	v_fma_f32 v118, -v59, v157, v118
	v_fma_f32 v119, -v59, v161, v119
	v_fma_f32 v118, -v60, v158, v118
	v_fma_f32 v119, -v60, v162, v119
	v_fma_f32 v118, -v61, v159, v118
	v_fma_f32 v119, -v61, v163, v119
	ds_read_b128 v[156:159], v181 offset:14944
	ds_read_b128 v[160:163], v181 offset:15200
	s_waitcnt lgkmcnt(10)
	v_fma_f32 v120, -v58, v164, v120
	v_fma_f32 v121, -v58, v168, v121
	v_fma_f32 v120, -v59, v165, v120
	v_fma_f32 v121, -v59, v169, v121
	v_fma_f32 v120, -v60, v166, v120
	v_fma_f32 v121, -v60, v170, v121
	v_fma_f32 v120, -v61, v167, v120
	v_fma_f32 v121, -v61, v171, v121
	ds_read_b128 v[164:167], v181 offset:15456
	ds_read_b128 v[168:171], v181 offset:15712
	s_waitcnt lgkmcnt(10)
	v_fma_f32 v122, -v58, v172, v122
	v_fma_f32 v123, -v58, v176, v123
	v_fma_f32 v122, -v59, v173, v122
	v_fma_f32 v123, -v59, v177, v123
	v_fma_f32 v122, -v60, v174, v122
	v_fma_f32 v123, -v60, v178, v123
	v_fma_f32 v122, -v61, v175, v122
	v_fma_f32 v123, -v61, v179, v123
	ds_read_b128 v[172:175], v181 offset:15968
	ds_read_b128 v[176:179], v181 offset:16224
	s_waitcnt lgkmcnt(10)
	v_fma_f32 v124, -v58, v204, v124
	v_fma_f32 v125, -v58, v208, v125
	v_fma_f32 v124, -v59, v205, v124
	v_fma_f32 v125, -v59, v209, v125
	v_fma_f32 v124, -v60, v206, v124
	v_fma_f32 v125, -v60, v210, v125
	v_fma_f32 v124, -v61, v207, v124
	v_fma_f32 v125, -v61, v211, v125
	ds_read_b128 v[204:207], v181 offset:7536
	ds_read_b128 v[208:211], v181 offset:7792
	s_waitcnt lgkmcnt(10)
	v_fma_f32 v126, -v58, v212, v126
	v_fma_f32 v127, -v58, v144, v127
	v_fma_f32 v126, -v59, v213, v126
	v_fma_f32 v127, -v59, v145, v127
	v_fma_f32 v126, -v60, v214, v126
	v_fma_f32 v127, -v60, v146, v127
	v_fma_f32 v126, -v61, v215, v126
	v_fma_f32 v127, -v61, v147, v127
	ds_read_b128 v[212:215], v181 offset:8048
	ds_read_b128 v[144:147], v181 offset:8304
	s_waitcnt lgkmcnt(10)
	v_fma_f32 v128, -v58, v148, v128
	v_fma_f32 v129, -v58, v152, v129
	v_fma_f32 v128, -v59, v149, v128
	v_fma_f32 v129, -v59, v153, v129
	v_fma_f32 v128, -v60, v150, v128
	v_fma_f32 v129, -v60, v154, v129
	v_fma_f32 v128, -v61, v151, v128
	v_fma_f32 v129, -v61, v155, v129
	ds_read_b128 v[148:151], v181 offset:8560
	ds_read_b128 v[152:155], v181 offset:8816
	s_waitcnt lgkmcnt(10)
	v_fma_f32 v130, -v58, v156, v130
	v_fma_f32 v131, -v58, v160, v131
	v_fma_f32 v130, -v59, v157, v130
	v_fma_f32 v131, -v59, v161, v131
	v_fma_f32 v130, -v60, v158, v130
	v_fma_f32 v131, -v60, v162, v131
	v_fma_f32 v130, -v61, v159, v130
	v_fma_f32 v131, -v61, v163, v131
	ds_read_b128 v[156:159], v181 offset:9072
	ds_read_b128 v[160:163], v181 offset:9328
	s_waitcnt lgkmcnt(10)
; #define LAS __attribute__((address_space(3)))
; __device__ __forceinline__ void phase_dnprep(ArgsRef a, const Tb tb, int l, LAS unsigned char* lds) {
;     ...
;             for (int jp = 0; jp < 16; ++jp) {
;                 const int r0 = 4 * jp;
;                 const f32x4 d1 = *(LAS const f32x4*)(Lm + (r0 + 1) * 64 + r0), d2 = *(LAS const f32x4*)(Lm + (r0 + 2) * 64 + r0), d3 = *(LAS const f32x4*)(Lm + (r0 + 3) * 64 + r0);
;                 const float x0 = acc[r0];
;                 const float x1 = acc[r0 + 1] - d1[0] * x0;
;                 const float x2 = (acc[r0 + 2] - d2[0] * x0) - d2[1] * x1;
;                 const float x3 = ((acc[r0 + 3] - d3[0] * x0) - d3[1] * x1) - d3[2] * x2;
;                 rhs[(r0 + 0) * 256 + col] = x0; rhs[(r0 + 1) * 256 + col] = x1; rhs[(r0 + 2) * 256 + col] = x2; rhs[(r0 + 3) * 256 + col] = x3;
; #pragma unroll
;                 for (int i = r0 + 4; i < 64; ++i) {
;                     const f32x4 l4 = *(LAS const f32x4*)(Lm + i * 64 + r0);
;                     acc[i] = (((acc[i] - l4[0] * x0) - l4[1] * x1) - l4[2] * x2) - l4[3] * x3;
;                 }
	v_fma_f32 v132, -v58, v164, v132
	v_fma_f32 v133, -v58, v168, v133
	v_fma_f32 v132, -v59, v165, v132
	v_fma_f32 v133, -v59, v169, v133
	v_fma_f32 v132, -v60, v166, v132
	v_fma_f32 v133, -v60, v170, v133
	v_fma_f32 v132, -v61, v167, v132
	v_fma_f32 v133, -v61, v171, v133
	ds_read_b128 v[164:167], v181 offset:9584
	ds_read_b128 v[168:171], v181 offset:9840
	s_waitcnt lgkmcnt(10)
	v_fma_f32 v134, -v58, v172, v134
	v_fma_f32 v135, -v58, v176, v135
	v_fma_f32 v134, -v59, v173, v134
	v_fma_f32 v135, -v59, v177, v135
	v_fma_f32 v134, -v60, v174, v134
	v_fma_f32 v135, -v60, v178, v135
	v_fma_f32 v134, -v61, v175, v134
	v_fma_f32 v135, -v61, v179, v135
	ds_read_b128 v[172:175], v181 offset:10096
	ds_read_b128 v[176:179], v181 offset:10352
	s_waitcnt lgkmcnt(9)
	v_fma_f32 v63, -v62, v204, v63
	v_fma_f32 v64, -v62, v208, v64
	v_fma_f32 v65, -v62, v212, v65
	v_fma_f32 v64, -v209, v63, v64
	v_fma_f32 v65, -v213, v63, v65
	v_fma_f32 v65, -v214, v64, v65
	ds_write_b32 v91, v62 offset:28672
	ds_write_b32 v91, v63 offset:29696
	ds_write_b32 v91, v64 offset:30720
	ds_write_b32 v91, v65 offset:31744
	ds_read_b128 v[204:207], v181 offset:10608
	ds_read_b128 v[208:211], v181 offset:10864
	ds_read_b128 v[212:215], v181 offset:11120
	s_waitcnt lgkmcnt(14)
	v_fma_f32 v66, -v62, v144, v66
	v_fma_f32 v67, -v62, v148, v67
	v_fma_f32 v66, -v63, v145, v66
	v_fma_f32 v67, -v63, v149, v67
	v_fma_f32 v66, -v64, v146, v66
	v_fma_f32 v67, -v64, v150, v67
	v_fma_f32 v66, -v65, v147, v66
	v_fma_f32 v67, -v65, v151, v67
	ds_read_b128 v[144:147], v181 offset:11376
	ds_read_b128 v[148:151], v181 offset:11632
	s_waitcnt lgkmcnt(14)
	v_fma_f32 v68, -v62, v152, v68
	v_fma_f32 v69, -v62, v156, v69
	v_fma_f32 v68, -v63, v153, v68
	v_fma_f32 v69, -v63, v157, v69
	v_fma_f32 v68, -v64, v154, v68
	v_fma_f32 v69, -v64, v158, v69
	v_fma_f32 v68, -v65, v155, v68
	v_fma_f32 v69, -v65, v159, v69
	ds_read_b128 v[152:155], v181 offset:11888
	ds_read_b128 v[156:159], v181 offset:12144
	s_waitcnt lgkmcnt(14)
	v_fma_f32 v70, -v62, v160, v70
	v_fma_f32 v71, -v62, v164, v71
	v_fma_f32 v70, -v63, v161, v70
	v_fma_f32 v71, -v63, v165, v71
	v_fma_f32 v70, -v64, v162, v70
	v_fma_f32 v71, -v64, v166, v71
	v_fma_f32 v70, -v65, v163, v70
	v_fma_f32 v71, -v65, v167, v71
	ds_read_b128 v[160:163], v181 offset:12400
	ds_read_b128 v[164:167], v181 offset:12656
	s_waitcnt lgkmcnt(14)
	v_fma_f32 v72, -v62, v168, v72
	v_fma_f32 v73, -v62, v172, v73
	v_fma_f32 v72, -v63, v169, v72
	v_fma_f32 v73, -v63, v173, v73
	v_fma_f32 v72, -v64, v170, v72
	v_fma_f32 v73, -v64, v174, v73
	v_fma_f32 v72, -v65, v171, v72
	v_fma_f32 v73, -v65, v175, v73
	ds_read_b128 v[168:171], v181 offset:12912
	ds_read_b128 v[172:175], v181 offset:13168
	s_waitcnt lgkmcnt(10)
	v_fma_f32 v74, -v62, v176, v74
	v_fma_f32 v75, -v62, v204, v75
	v_fma_f32 v74, -v63, v177, v74
	v_fma_f32 v75, -v63, v205, v75
	v_fma_f32 v74, -v64, v178, v74
	v_fma_f32 v75, -v64, v206, v75
	v_fma_f32 v74, -v65, v179, v74
	v_fma_f32 v75, -v65, v207, v75
	ds_read_b128 v[176:179], v181 offset:13424
	ds_read_b128 v[204:207], v181 offset:13680
	s_waitcnt lgkmcnt(10)
	v_fma_f32 v76, -v62, v208, v76
	v_fma_f32 v77, -v62, v212, v77
	v_fma_f32 v76, -v63, v209, v76
	v_fma_f32 v77, -v63, v213, v77
	v_fma_f32 v76, -v64, v210, v76
	v_fma_f32 v77, -v64, v214, v77
	v_fma_f32 v76, -v65, v211, v76
	v_fma_f32 v77, -v65, v215, v77
	ds_read_b128 v[208:211], v181 offset:13936
	ds_read_b128 v[212:215], v181 offset:14192
	s_waitcnt lgkmcnt(10)
	v_fma_f32 v116, -v62, v144, v116
	v_fma_f32 v117, -v62, v148, v117
	v_fma_f32 v116, -v63, v145, v116
	v_fma_f32 v117, -v63, v149, v117
	v_fma_f32 v116, -v64, v146, v116
	v_fma_f32 v117, -v64, v150, v117
	v_fma_f32 v116, -v65, v147, v116
	v_fma_f32 v117, -v65, v151, v117
	ds_read_b128 v[144:147], v181 offset:14448
	ds_read_b128 v[148:151], v181 offset:14704
	s_waitcnt lgkmcnt(10)
	v_fma_f32 v118, -v62, v152, v118
	v_fma_f32 v119, -v62, v156, v119
	v_fma_f32 v118, -v63, v153, v118
	v_fma_f32 v119, -v63, v157, v119
	v_fma_f32 v118, -v64, v154, v118
	v_fma_f32 v119, -v64, v158, v119
	v_fma_f32 v118, -v65, v155, v118
	v_fma_f32 v119, -v65, v159, v119
	ds_read_b128 v[152:155], v181 offset:14960
	ds_read_b128 v[156:159], v181 offset:15216
	s_waitcnt lgkmcnt(10)
	v_fma_f32 v120, -v62, v160, v120
	v_fma_f32 v121, -v62, v164, v121
	v_fma_f32 v120, -v63, v161, v120
	v_fma_f32 v121, -v63, v165, v121
	v_fma_f32 v120, -v64, v162, v120
	v_fma_f32 v121, -v64, v166, v121
	v_fma_f32 v120, -v65, v163, v120
	v_fma_f32 v121, -v65, v167, v121
	ds_read_b128 v[160:163], v181 offset:15472
	ds_read_b128 v[164:167], v181 offset:15728
	s_waitcnt lgkmcnt(10)
	v_fma_f32 v122, -v62, v168, v122
	v_fma_f32 v123, -v62, v172, v123
	v_fma_f32 v122, -v63, v169, v122
	v_fma_f32 v123, -v63, v173, v123
	v_fma_f32 v122, -v64, v170, v122
	v_fma_f32 v123, -v64, v174, v123
	v_fma_f32 v122, -v65, v171, v122
	v_fma_f32 v123, -v65, v175, v123
	ds_read_b128 v[168:171], v181 offset:15984
	ds_read_b128 v[172:175], v181 offset:16240
	s_waitcnt lgkmcnt(10)
	v_fma_f32 v124, -v62, v176, v124
	v_fma_f32 v125, -v62, v204, v125
	v_fma_f32 v124, -v63, v177, v124
	v_fma_f32 v125, -v63, v205, v125
	v_fma_f32 v124, -v64, v178, v124
	v_fma_f32 v125, -v64, v206, v125
	v_fma_f32 v124, -v65, v179, v124
	v_fma_f32 v125, -v65, v207, v125
	ds_read_b128 v[176:179], v181 offset:8576
	ds_read_b128 v[204:207], v181 offset:8832
	s_waitcnt lgkmcnt(10)
	v_fma_f32 v126, -v62, v208, v126
	v_fma_f32 v127, -v62, v212, v127
	v_fma_f32 v126, -v63, v209, v126
	v_fma_f32 v127, -v63, v213, v127
	v_fma_f32 v126, -v64, v210, v126
	v_fma_f32 v127, -v64, v214, v127
	v_fma_f32 v126, -v65, v211, v126
	v_fma_f32 v127, -v65, v215, v127
	ds_read_b128 v[208:211], v181 offset:9088
	ds_read_b128 v[212:215], v181 offset:9344
	s_waitcnt lgkmcnt(10)
; #define LAS __attribute__((address_space(3)))
; __device__ __forceinline__ void phase_dnprep(ArgsRef a, const Tb tb, int l, LAS unsigned char* lds) {
;     ...
;             for (int jp = 0; jp < 16; ++jp) {
;                 const int r0 = 4 * jp;
;                 const f32x4 d1 = *(LAS const f32x4*)(Lm + (r0 + 1) * 64 + r0), d2 = *(LAS const f32x4*)(Lm + (r0 + 2) * 64 + r0), d3 = *(LAS const f32x4*)(Lm + (r0 + 3) * 64 + r0);
;                 const float x0 = acc[r0];
;                 const float x1 = acc[r0 + 1] - d1[0] * x0;
;                 const float x2 = (acc[r0 + 2] - d2[0] * x0) - d2[1] * x1;
;                 const float x3 = ((acc[r0 + 3] - d3[0] * x0) - d3[1] * x1) - d3[2] * x2;
;                 rhs[(r0 + 0) * 256 + col] = x0; rhs[(r0 + 1) * 256 + col] = x1; rhs[(r0 + 2) * 256 + col] = x2; rhs[(r0 + 3) * 256 + col] = x3;
; #pragma unroll
;                 for (int i = r0 + 4; i < 64; ++i) {
;                     const f32x4 l4 = *(LAS const f32x4*)(Lm + i * 64 + r0);
;                     acc[i] = (((acc[i] - l4[0] * x0) - l4[1] * x1) - l4[2] * x2) - l4[3] * x3;
;                 }
	v_fma_f32 v128, -v62, v144, v128
	v_fma_f32 v129, -v62, v148, v129
	v_fma_f32 v128, -v63, v145, v128
	v_fma_f32 v129, -v63, v149, v129
	v_fma_f32 v128, -v64, v146, v128
	v_fma_f32 v129, -v64, v150, v129
	v_fma_f32 v128, -v65, v147, v128
	v_fma_f32 v129, -v65, v151, v129
	ds_read_b128 v[144:147], v181 offset:9600
	ds_read_b128 v[148:151], v181 offset:9856
	s_waitcnt lgkmcnt(10)
	v_fma_f32 v130, -v62, v152, v130
	v_fma_f32 v131, -v62, v156, v131
	v_fma_f32 v130, -v63, v153, v130
	v_fma_f32 v131, -v63, v157, v131
	v_fma_f32 v130, -v64, v154, v130
	v_fma_f32 v131, -v64, v158, v131
	v_fma_f32 v130, -v65, v155, v130
	v_fma_f32 v131, -v65, v159, v131
	ds_read_b128 v[152:155], v181 offset:10112
	ds_read_b128 v[156:159], v181 offset:10368
	s_waitcnt lgkmcnt(10)
	v_fma_f32 v132, -v62, v160, v132
	v_fma_f32 v133, -v62, v164, v133
	v_fma_f32 v132, -v63, v161, v132
	v_fma_f32 v133, -v63, v165, v133
	v_fma_f32 v132, -v64, v162, v132
	v_fma_f32 v133, -v64, v166, v133
	v_fma_f32 v132, -v65, v163, v132
	v_fma_f32 v133, -v65, v167, v133
	ds_read_b128 v[160:163], v181 offset:10624
	ds_read_b128 v[164:167], v181 offset:10880
	s_waitcnt lgkmcnt(10)
	v_fma_f32 v134, -v62, v168, v134
	v_fma_f32 v135, -v62, v172, v135
	v_fma_f32 v134, -v63, v169, v134
	v_fma_f32 v135, -v63, v173, v135
	v_fma_f32 v134, -v64, v170, v134
	v_fma_f32 v135, -v64, v174, v135
	v_fma_f32 v134, -v65, v171, v134
	v_fma_f32 v135, -v65, v175, v135
	ds_read_b128 v[168:171], v181 offset:11136
	ds_read_b128 v[172:175], v181 offset:11392
	s_waitcnt lgkmcnt(9)
	v_fma_f32 v67, -v66, v176, v67
	v_fma_f32 v68, -v66, v204, v68
	v_fma_f32 v69, -v66, v208, v69
	v_fma_f32 v68, -v205, v67, v68
	v_fma_f32 v69, -v209, v67, v69
	v_fma_f32 v69, -v210, v68, v69
	ds_write_b32 v91, v66 offset:32768
	ds_write_b32 v91, v67 offset:33792
	ds_write_b32 v91, v68 offset:34816
	ds_write_b32 v91, v69 offset:35840
	ds_read_b128 v[176:179], v181 offset:11648
	ds_read_b128 v[204:207], v181 offset:11904
	ds_read_b128 v[208:211], v181 offset:12160
	s_waitcnt lgkmcnt(14)
	v_fma_f32 v70, -v66, v212, v70
	v_fma_f32 v71, -v66, v144, v71
	v_fma_f32 v70, -v67, v213, v70
	v_fma_f32 v71, -v67, v145, v71
	v_fma_f32 v70, -v68, v214, v70
	v_fma_f32 v71, -v68, v146, v71
	v_fma_f32 v70, -v69, v215, v70
	v_fma_f32 v71, -v69, v147, v71
	ds_read_b128 v[212:215], v181 offset:12416
	ds_read_b128 v[144:147], v181 offset:12672
	s_waitcnt lgkmcnt(14)
	v_fma_f32 v72, -v66, v148, v72
	v_fma_f32 v73, -v66, v152, v73
	v_fma_f32 v72, -v67, v149, v72
	v_fma_f32 v73, -v67, v153, v73
	v_fma_f32 v72, -v68, v150, v72
	v_fma_f32 v73, -v68, v154, v73
	v_fma_f32 v72, -v69, v151, v72
	v_fma_f32 v73, -v69, v155, v73
	ds_read_b128 v[148:151], v181 offset:12928
	ds_read_b128 v[152:155], v181 offset:13184
	s_waitcnt lgkmcnt(14)
	v_fma_f32 v74, -v66, v156, v74
	v_fma_f32 v75, -v66, v160, v75
	v_fma_f32 v74, -v67, v157, v74
	v_fma_f32 v75, -v67, v161, v75
	v_fma_f32 v74, -v68, v158, v74
	v_fma_f32 v75, -v68, v162, v75
	v_fma_f32 v74, -v69, v159, v74
	v_fma_f32 v75, -v69, v163, v75
	ds_read_b128 v[156:159], v181 offset:13440
	ds_read_b128 v[160:163], v181 offset:13696
	s_waitcnt lgkmcnt(14)
	v_fma_f32 v76, -v66, v164, v76
	v_fma_f32 v77, -v66, v168, v77
	v_fma_f32 v76, -v67, v165, v76
	v_fma_f32 v77, -v67, v169, v77
	v_fma_f32 v76, -v68, v166, v76
	v_fma_f32 v77, -v68, v170, v77
	v_fma_f32 v76, -v69, v167, v76
	v_fma_f32 v77, -v69, v171, v77
	ds_read_b128 v[164:167], v181 offset:13952
	ds_read_b128 v[168:171], v181 offset:14208
	s_waitcnt lgkmcnt(10)
	v_fma_f32 v116, -v66, v172, v116
	v_fma_f32 v117, -v66, v176, v117
	v_fma_f32 v116, -v67, v173, v116
	v_fma_f32 v117, -v67, v177, v117
	v_fma_f32 v116, -v68, v174, v116
	v_fma_f32 v117, -v68, v178, v117
	v_fma_f32 v116, -v69, v175, v116
	v_fma_f32 v117, -v69, v179, v117
	ds_read_b128 v[172:175], v181 offset:14464
	ds_read_b128 v[176:179], v181 offset:14720
	s_waitcnt lgkmcnt(10)
	v_fma_f32 v118, -v66, v204, v118
	v_fma_f32 v119, -v66, v208, v119
	v_fma_f32 v118, -v67, v205, v118
	v_fma_f32 v119, -v67, v209, v119
	v_fma_f32 v118, -v68, v206, v118
	v_fma_f32 v119, -v68, v210, v119
	v_fma_f32 v118, -v69, v207, v118
	v_fma_f32 v119, -v69, v211, v119
	ds_read_b128 v[204:207], v181 offset:14976
	ds_read_b128 v[208:211], v181 offset:15232
	s_waitcnt lgkmcnt(10)
	v_fma_f32 v120, -v66, v212, v120
	v_fma_f32 v121, -v66, v144, v121
	v_fma_f32 v120, -v67, v213, v120
	v_fma_f32 v121, -v67, v145, v121
	v_fma_f32 v120, -v68, v214, v120
	v_fma_f32 v121, -v68, v146, v121
	v_fma_f32 v120, -v69, v215, v120
	v_fma_f32 v121, -v69, v147, v121
	ds_read_b128 v[212:215], v181 offset:15488
	ds_read_b128 v[144:147], v181 offset:15744
	s_waitcnt lgkmcnt(10)
	v_fma_f32 v122, -v66, v148, v122
	v_fma_f32 v123, -v66, v152, v123
	v_fma_f32 v122, -v67, v149, v122
	v_fma_f32 v123, -v67, v153, v123
	v_fma_f32 v122, -v68, v150, v122
	v_fma_f32 v123, -v68, v154, v123
	v_fma_f32 v122, -v69, v151, v122
	v_fma_f32 v123, -v69, v155, v123
	ds_read_b128 v[148:151], v181 offset:16000
	ds_read_b128 v[152:155], v181 offset:16256
	s_waitcnt lgkmcnt(10)
	v_fma_f32 v124, -v66, v156, v124
	v_fma_f32 v125, -v66, v160, v125
	v_fma_f32 v124, -v67, v157, v124
	v_fma_f32 v125, -v67, v161, v125
	v_fma_f32 v124, -v68, v158, v124
	v_fma_f32 v125, -v68, v162, v125
	v_fma_f32 v124, -v69, v159, v124
	v_fma_f32 v125, -v69, v163, v125
	ds_read_b128 v[156:159], v181 offset:9616
	ds_read_b128 v[160:163], v181 offset:9872
	s_waitcnt lgkmcnt(10)
	v_fma_f32 v126, -v66, v164, v126
	v_fma_f32 v127, -v66, v168, v127
	v_fma_f32 v126, -v67, v165, v126
	v_fma_f32 v127, -v67, v169, v127
	v_fma_f32 v126, -v68, v166, v126
	v_fma_f32 v127, -v68, v170, v127
	v_fma_f32 v126, -v69, v167, v126
	v_fma_f32 v127, -v69, v171, v127
	ds_read_b128 v[164:167], v181 offset:10128
	ds_read_b128 v[168:171], v181 offset:10384
	s_waitcnt lgkmcnt(10)
; #define LAS __attribute__((address_space(3)))
; __device__ __forceinline__ void phase_dnprep(ArgsRef a, const Tb tb, int l, LAS unsigned char* lds) {
;     ...
;             for (int jp = 0; jp < 16; ++jp) {
;                 const int r0 = 4 * jp;
;                 const f32x4 d1 = *(LAS const f32x4*)(Lm + (r0 + 1) * 64 + r0), d2 = *(LAS const f32x4*)(Lm + (r0 + 2) * 64 + r0), d3 = *(LAS const f32x4*)(Lm + (r0 + 3) * 64 + r0);
;                 const float x0 = acc[r0];
;                 const float x1 = acc[r0 + 1] - d1[0] * x0;
;                 const float x2 = (acc[r0 + 2] - d2[0] * x0) - d2[1] * x1;
;                 const float x3 = ((acc[r0 + 3] - d3[0] * x0) - d3[1] * x1) - d3[2] * x2;
;                 rhs[(r0 + 0) * 256 + col] = x0; rhs[(r0 + 1) * 256 + col] = x1; rhs[(r0 + 2) * 256 + col] = x2; rhs[(r0 + 3) * 256 + col] = x3;
; #pragma unroll
;                 for (int i = r0 + 4; i < 64; ++i) {
;                     const f32x4 l4 = *(LAS const f32x4*)(Lm + i * 64 + r0);
;                     acc[i] = (((acc[i] - l4[0] * x0) - l4[1] * x1) - l4[2] * x2) - l4[3] * x3;
;                 }
	v_fma_f32 v128, -v66, v172, v128
	v_fma_f32 v129, -v66, v176, v129
	v_fma_f32 v128, -v67, v173, v128
	v_fma_f32 v129, -v67, v177, v129
	v_fma_f32 v128, -v68, v174, v128
	v_fma_f32 v129, -v68, v178, v129
	v_fma_f32 v128, -v69, v175, v128
	v_fma_f32 v129, -v69, v179, v129
	ds_read_b128 v[172:175], v181 offset:10640
	ds_read_b128 v[176:179], v181 offset:10896
	s_waitcnt lgkmcnt(10)
	v_fma_f32 v130, -v66, v204, v130
	v_fma_f32 v131, -v66, v208, v131
	v_fma_f32 v130, -v67, v205, v130
	v_fma_f32 v131, -v67, v209, v131
	v_fma_f32 v130, -v68, v206, v130
	v_fma_f32 v131, -v68, v210, v131
	v_fma_f32 v130, -v69, v207, v130
	v_fma_f32 v131, -v69, v211, v131
	ds_read_b128 v[204:207], v181 offset:11152
	ds_read_b128 v[208:211], v181 offset:11408
	s_waitcnt lgkmcnt(10)
	v_fma_f32 v132, -v66, v212, v132
	v_fma_f32 v133, -v66, v144, v133
	v_fma_f32 v132, -v67, v213, v132
	v_fma_f32 v133, -v67, v145, v133
	v_fma_f32 v132, -v68, v214, v132
	v_fma_f32 v133, -v68, v146, v133
	v_fma_f32 v132, -v69, v215, v132
	v_fma_f32 v133, -v69, v147, v133
	ds_read_b128 v[212:215], v181 offset:11664
	ds_read_b128 v[144:147], v181 offset:11920
	s_waitcnt lgkmcnt(10)
	v_fma_f32 v134, -v66, v148, v134
	v_fma_f32 v135, -v66, v152, v135
	v_fma_f32 v134, -v67, v149, v134
	v_fma_f32 v135, -v67, v153, v135
	v_fma_f32 v134, -v68, v150, v134
	v_fma_f32 v135, -v68, v154, v135
	v_fma_f32 v134, -v69, v151, v134
	v_fma_f32 v135, -v69, v155, v135
	ds_read_b128 v[148:151], v181 offset:12176
	ds_read_b128 v[152:155], v181 offset:12432
	s_waitcnt lgkmcnt(9)
	v_fma_f32 v71, -v70, v156, v71
	v_fma_f32 v72, -v70, v160, v72
	v_fma_f32 v73, -v70, v164, v73
	v_fma_f32 v72, -v161, v71, v72
	v_fma_f32 v73, -v165, v71, v73
	v_fma_f32 v73, -v166, v72, v73
	ds_write_b32 v91, v70 offset:36864
	ds_write_b32 v91, v71 offset:37888
	ds_write_b32 v91, v72 offset:38912
	ds_write_b32 v91, v73 offset:39936
	ds_read_b128 v[156:159], v181 offset:12688
	ds_read_b128 v[160:163], v181 offset:12944
	ds_read_b128 v[164:167], v181 offset:13200
	s_waitcnt lgkmcnt(14)
	v_fma_f32 v74, -v70, v168, v74
	v_fma_f32 v75, -v70, v172, v75
	v_fma_f32 v74, -v71, v169, v74
	v_fma_f32 v75, -v71, v173, v75
	v_fma_f32 v74, -v72, v170, v74
	v_fma_f32 v75, -v72, v174, v75
	v_fma_f32 v74, -v73, v171, v74
	v_fma_f32 v75, -v73, v175, v75
	ds_read_b128 v[168:171], v181 offset:13456
	ds_read_b128 v[172:175], v181 offset:13712
	s_waitcnt lgkmcnt(14)
	v_fma_f32 v76, -v70, v176, v76
	v_fma_f32 v77, -v70, v204, v77
	v_fma_f32 v76, -v71, v177, v76
	v_fma_f32 v77, -v71, v205, v77
	v_fma_f32 v76, -v72, v178, v76
	v_fma_f32 v77, -v72, v206, v77
	v_fma_f32 v76, -v73, v179, v76
	v_fma_f32 v77, -v73, v207, v77
	ds_read_b128 v[176:179], v181 offset:13968
	ds_read_b128 v[204:207], v181 offset:14224
	s_waitcnt lgkmcnt(14)
	v_fma_f32 v116, -v70, v208, v116
	v_fma_f32 v117, -v70, v212, v117
	v_fma_f32 v116, -v71, v209, v116
	v_fma_f32 v117, -v71, v213, v117
	v_fma_f32 v116, -v72, v210, v116
	v_fma_f32 v117, -v72, v214, v117
	v_fma_f32 v116, -v73, v211, v116
	v_fma_f32 v117, -v73, v215, v117
	ds_read_b128 v[208:211], v181 offset:14480
	ds_read_b128 v[212:215], v181 offset:14736
	s_waitcnt lgkmcnt(14)
	v_fma_f32 v118, -v70, v144, v118
	v_fma_f32 v119, -v70, v148, v119
	v_fma_f32 v118, -v71, v145, v118
	v_fma_f32 v119, -v71, v149, v119
	v_fma_f32 v118, -v72, v146, v118
	v_fma_f32 v119, -v72, v150, v119
	v_fma_f32 v118, -v73, v147, v118
	v_fma_f32 v119, -v73, v151, v119
	ds_read_b128 v[144:147], v181 offset:14992
	ds_read_b128 v[148:151], v181 offset:15248
	s_waitcnt lgkmcnt(10)
	v_fma_f32 v120, -v70, v152, v120
	v_fma_f32 v121, -v70, v156, v121
	v_fma_f32 v120, -v71, v153, v120
	v_fma_f32 v121, -v71, v157, v121
	v_fma_f32 v120, -v72, v154, v120
	v_fma_f32 v121, -v72, v158, v121
	v_fma_f32 v120, -v73, v155, v120
	v_fma_f32 v121, -v73, v159, v121
	ds_read_b128 v[152:155], v181 offset:15504
	ds_read_b128 v[156:159], v181 offset:15760
	s_waitcnt lgkmcnt(10)
	v_fma_f32 v122, -v70, v160, v122
	v_fma_f32 v123, -v70, v164, v123
	v_fma_f32 v122, -v71, v161, v122
	v_fma_f32 v123, -v71, v165, v123
	v_fma_f32 v122, -v72, v162, v122
	v_fma_f32 v123, -v72, v166, v123
	v_fma_f32 v122, -v73, v163, v122
	v_fma_f32 v123, -v73, v167, v123
	ds_read_b128 v[160:163], v181 offset:16016
	ds_read_b128 v[164:167], v181 offset:16272
	s_waitcnt lgkmcnt(10)
	v_fma_f32 v124, -v70, v168, v124
	v_fma_f32 v125, -v70, v172, v125
	v_fma_f32 v124, -v71, v169, v124
	v_fma_f32 v125, -v71, v173, v125
	v_fma_f32 v124, -v72, v170, v124
	v_fma_f32 v125, -v72, v174, v125
	v_fma_f32 v124, -v73, v171, v124
	v_fma_f32 v125, -v73, v175, v125
	ds_read_b128 v[168:171], v181 offset:10656
	ds_read_b128 v[172:175], v181 offset:10912
	s_waitcnt lgkmcnt(10)
	v_fma_f32 v126, -v70, v176, v126
	v_fma_f32 v127, -v70, v204, v127
	v_fma_f32 v126, -v71, v177, v126
	v_fma_f32 v127, -v71, v205, v127
	v_fma_f32 v126, -v72, v178, v126
	v_fma_f32 v127, -v72, v206, v127
	v_fma_f32 v126, -v73, v179, v126
	v_fma_f32 v127, -v73, v207, v127
	ds_read_b128 v[176:179], v181 offset:11168
	ds_read_b128 v[204:207], v181 offset:11424
	s_waitcnt lgkmcnt(10)
	v_fma_f32 v128, -v70, v208, v128
	v_fma_f32 v129, -v70, v212, v129
	v_fma_f32 v128, -v71, v209, v128
	v_fma_f32 v129, -v71, v213, v129
	v_fma_f32 v128, -v72, v210, v128
	v_fma_f32 v129, -v72, v214, v129
	v_fma_f32 v128, -v73, v211, v128
	v_fma_f32 v129, -v73, v215, v129
	ds_read_b128 v[208:211], v181 offset:11680
	ds_read_b128 v[212:215], v181 offset:11936
	s_waitcnt lgkmcnt(10)
	v_fma_f32 v130, -v70, v144, v130
	v_fma_f32 v131, -v70, v148, v131
	v_fma_f32 v130, -v71, v145, v130
	v_fma_f32 v131, -v71, v149, v131
	v_fma_f32 v130, -v72, v146, v130
	v_fma_f32 v131, -v72, v150, v131
	v_fma_f32 v130, -v73, v147, v130
	v_fma_f32 v131, -v73, v151, v131
	ds_read_b128 v[144:147], v181 offset:12192
	ds_read_b128 v[148:151], v181 offset:12448
	s_waitcnt lgkmcnt(10)
; #define LAS __attribute__((address_space(3)))
; __device__ __forceinline__ void phase_dnprep(ArgsRef a, const Tb tb, int l, LAS unsigned char* lds) {
;     ...
;             for (int jp = 0; jp < 16; ++jp) {
;                 const int r0 = 4 * jp;
;                 const f32x4 d1 = *(LAS const f32x4*)(Lm + (r0 + 1) * 64 + r0), d2 = *(LAS const f32x4*)(Lm + (r0 + 2) * 64 + r0), d3 = *(LAS const f32x4*)(Lm + (r0 + 3) * 64 + r0);
;                 const float x0 = acc[r0];
;                 const float x1 = acc[r0 + 1] - d1[0] * x0;
;                 const float x2 = (acc[r0 + 2] - d2[0] * x0) - d2[1] * x1;
;                 const float x3 = ((acc[r0 + 3] - d3[0] * x0) - d3[1] * x1) - d3[2] * x2;
;                 rhs[(r0 + 0) * 256 + col] = x0; rhs[(r0 + 1) * 256 + col] = x1; rhs[(r0 + 2) * 256 + col] = x2; rhs[(r0 + 3) * 256 + col] = x3;
; #pragma unroll
;                 for (int i = r0 + 4; i < 64; ++i) {
;                     const f32x4 l4 = *(LAS const f32x4*)(Lm + i * 64 + r0);
;                     acc[i] = (((acc[i] - l4[0] * x0) - l4[1] * x1) - l4[2] * x2) - l4[3] * x3;
;                 }
	v_fma_f32 v132, -v70, v152, v132
	v_fma_f32 v133, -v70, v156, v133
	v_fma_f32 v132, -v71, v153, v132
	v_fma_f32 v133, -v71, v157, v133
	v_fma_f32 v132, -v72, v154, v132
	v_fma_f32 v133, -v72, v158, v133
	v_fma_f32 v132, -v73, v155, v132
	v_fma_f32 v133, -v73, v159, v133
	ds_read_b128 v[152:155], v181 offset:12704
	ds_read_b128 v[156:159], v181 offset:12960
	s_waitcnt lgkmcnt(10)
	v_fma_f32 v134, -v70, v160, v134
	v_fma_f32 v135, -v70, v164, v135
	v_fma_f32 v134, -v71, v161, v134
	v_fma_f32 v135, -v71, v165, v135
	v_fma_f32 v134, -v72, v162, v134
	v_fma_f32 v135, -v72, v166, v135
	v_fma_f32 v134, -v73, v163, v134
	v_fma_f32 v135, -v73, v167, v135
	ds_read_b128 v[160:163], v181 offset:13216
	ds_read_b128 v[164:167], v181 offset:13472
	s_waitcnt lgkmcnt(9)
	v_fma_f32 v75, -v74, v168, v75
	v_fma_f32 v76, -v74, v172, v76
	v_fma_f32 v77, -v74, v176, v77
	v_fma_f32 v76, -v173, v75, v76
	v_fma_f32 v77, -v177, v75, v77
	v_fma_f32 v77, -v178, v76, v77
	ds_write_b32 v91, v74 offset:40960
	ds_write_b32 v91, v75 offset:41984
	ds_write_b32 v91, v76 offset:43008
	ds_write_b32 v91, v77 offset:44032
	ds_read_b128 v[168:171], v181 offset:13728
	ds_read_b128 v[172:175], v181 offset:13984
	ds_read_b128 v[176:179], v181 offset:14240
	s_waitcnt lgkmcnt(14)
	v_fma_f32 v116, -v74, v204, v116
	v_fma_f32 v117, -v74, v208, v117
	v_fma_f32 v116, -v75, v205, v116
	v_fma_f32 v117, -v75, v209, v117
	v_fma_f32 v116, -v76, v206, v116
	v_fma_f32 v117, -v76, v210, v117
	v_fma_f32 v116, -v77, v207, v116
	v_fma_f32 v117, -v77, v211, v117
	ds_read_b128 v[204:207], v181 offset:14496
	ds_read_b128 v[208:211], v181 offset:14752
	s_waitcnt lgkmcnt(14)
	v_fma_f32 v118, -v74, v212, v118
	v_fma_f32 v119, -v74, v144, v119
	v_fma_f32 v118, -v75, v213, v118
	v_fma_f32 v119, -v75, v145, v119
	v_fma_f32 v118, -v76, v214, v118
	v_fma_f32 v119, -v76, v146, v119
	v_fma_f32 v118, -v77, v215, v118
	v_fma_f32 v119, -v77, v147, v119
	ds_read_b128 v[212:215], v181 offset:15008
	ds_read_b128 v[144:147], v181 offset:15264
	s_waitcnt lgkmcnt(14)
	v_fma_f32 v120, -v74, v148, v120
	v_fma_f32 v121, -v74, v152, v121
	v_fma_f32 v120, -v75, v149, v120
	v_fma_f32 v121, -v75, v153, v121
	v_fma_f32 v120, -v76, v150, v120
	v_fma_f32 v121, -v76, v154, v121
	v_fma_f32 v120, -v77, v151, v120
	v_fma_f32 v121, -v77, v155, v121
	ds_read_b128 v[148:151], v181 offset:15520
	ds_read_b128 v[152:155], v181 offset:15776
	s_waitcnt lgkmcnt(14)
	v_fma_f32 v122, -v74, v156, v122
	v_fma_f32 v123, -v74, v160, v123
	v_fma_f32 v122, -v75, v157, v122
	v_fma_f32 v123, -v75, v161, v123
	v_fma_f32 v122, -v76, v158, v122
	v_fma_f32 v123, -v76, v162, v123
	v_fma_f32 v122, -v77, v159, v122
	v_fma_f32 v123, -v77, v163, v123
	ds_read_b128 v[156:159], v181 offset:16032
	ds_read_b128 v[160:163], v181 offset:16288
	s_waitcnt lgkmcnt(10)
	v_fma_f32 v124, -v74, v164, v124
	v_fma_f32 v125, -v74, v168, v125
	v_fma_f32 v124, -v75, v165, v124
	v_fma_f32 v125, -v75, v169, v125
	v_fma_f32 v124, -v76, v166, v124
	v_fma_f32 v125, -v76, v170, v125
	v_fma_f32 v124, -v77, v167, v124
	v_fma_f32 v125, -v77, v171, v125
	ds_read_b128 v[164:167], v181 offset:11696
	ds_read_b128 v[168:171], v181 offset:11952
	s_waitcnt lgkmcnt(10)
	v_fma_f32 v126, -v74, v172, v126
	v_fma_f32 v127, -v74, v176, v127
	v_fma_f32 v126, -v75, v173, v126
	v_fma_f32 v127, -v75, v177, v127
	v_fma_f32 v126, -v76, v174, v126
	v_fma_f32 v127, -v76, v178, v127
	v_fma_f32 v126, -v77, v175, v126
	v_fma_f32 v127, -v77, v179, v127
	ds_read_b128 v[172:175], v181 offset:12208
	ds_read_b128 v[176:179], v181 offset:12464
	s_waitcnt lgkmcnt(10)
	v_fma_f32 v128, -v74, v204, v128
	v_fma_f32 v129, -v74, v208, v129
	v_fma_f32 v128, -v75, v205, v128
	v_fma_f32 v129, -v75, v209, v129
	v_fma_f32 v128, -v76, v206, v128
	v_fma_f32 v129, -v76, v210, v129
	v_fma_f32 v128, -v77, v207, v128
	v_fma_f32 v129, -v77, v211, v129
	ds_read_b128 v[204:207], v181 offset:12720
	ds_read_b128 v[208:211], v181 offset:12976
	s_waitcnt lgkmcnt(10)
	v_fma_f32 v130, -v74, v212, v130
	v_fma_f32 v131, -v74, v144, v131
	v_fma_f32 v130, -v75, v213, v130
	v_fma_f32 v131, -v75, v145, v131
	v_fma_f32 v130, -v76, v214, v130
	v_fma_f32 v131, -v76, v146, v131
	v_fma_f32 v130, -v77, v215, v130
	v_fma_f32 v131, -v77, v147, v131
	ds_read_b128 v[212:215], v181 offset:13232
	ds_read_b128 v[144:147], v181 offset:13488
	s_waitcnt lgkmcnt(10)
	v_fma_f32 v132, -v74, v148, v132
	v_fma_f32 v133, -v74, v152, v133
	v_fma_f32 v132, -v75, v149, v132
	v_fma_f32 v133, -v75, v153, v133
	v_fma_f32 v132, -v76, v150, v132
	v_fma_f32 v133, -v76, v154, v133
	v_fma_f32 v132, -v77, v151, v132
	v_fma_f32 v133, -v77, v155, v133
	ds_read_b128 v[148:151], v181 offset:13744
	ds_read_b128 v[152:155], v181 offset:14000
	s_waitcnt lgkmcnt(10)
	v_fma_f32 v134, -v74, v156, v134
	v_fma_f32 v135, -v74, v160, v135
	v_fma_f32 v134, -v75, v157, v134
	v_fma_f32 v135, -v75, v161, v135
	v_fma_f32 v134, -v76, v158, v134
	v_fma_f32 v135, -v76, v162, v135
	v_fma_f32 v134, -v77, v159, v134
	v_fma_f32 v135, -v77, v163, v135
	ds_read_b128 v[156:159], v181 offset:14256
	ds_read_b128 v[160:163], v181 offset:14512
	s_waitcnt lgkmcnt(9)
	v_fma_f32 v117, -v116, v164, v117
	v_fma_f32 v118, -v116, v168, v118
	v_fma_f32 v119, -v116, v172, v119
	v_fma_f32 v118, -v169, v117, v118
	v_fma_f32 v119, -v173, v117, v119
	v_fma_f32 v119, -v174, v118, v119
	ds_write_b32 v91, v116 offset:45056
	ds_write_b32 v91, v117 offset:46080
	ds_write_b32 v91, v118 offset:47104
	ds_write_b32 v91, v119 offset:48128
	ds_read_b128 v[164:167], v181 offset:14768
	ds_read_b128 v[168:171], v181 offset:15024
	ds_read_b128 v[172:175], v181 offset:15280
	s_waitcnt lgkmcnt(14)
; #define LAS __attribute__((address_space(3)))
; __device__ __forceinline__ void phase_dnprep(ArgsRef a, const Tb tb, int l, LAS unsigned char* lds) {
;     ...
;             for (int jp = 0; jp < 16; ++jp) {
;                 const int r0 = 4 * jp;
;                 const f32x4 d1 = *(LAS const f32x4*)(Lm + (r0 + 1) * 64 + r0), d2 = *(LAS const f32x4*)(Lm + (r0 + 2) * 64 + r0), d3 = *(LAS const f32x4*)(Lm + (r0 + 3) * 64 + r0);
;                 const float x0 = acc[r0];
;                 const float x1 = acc[r0 + 1] - d1[0] * x0;
;                 const float x2 = (acc[r0 + 2] - d2[0] * x0) - d2[1] * x1;
;                 const float x3 = ((acc[r0 + 3] - d3[0] * x0) - d3[1] * x1) - d3[2] * x2;
;                 rhs[(r0 + 0) * 256 + col] = x0; rhs[(r0 + 1) * 256 + col] = x1; rhs[(r0 + 2) * 256 + col] = x2; rhs[(r0 + 3) * 256 + col] = x3;
; #pragma unroll
;                 for (int i = r0 + 4; i < 64; ++i) {
;                     const f32x4 l4 = *(LAS const f32x4*)(Lm + i * 64 + r0);
;                     acc[i] = (((acc[i] - l4[0] * x0) - l4[1] * x1) - l4[2] * x2) - l4[3] * x3;
;                 }
	v_fma_f32 v120, -v116, v176, v120
	v_fma_f32 v121, -v116, v204, v121
	v_fma_f32 v120, -v117, v177, v120
	v_fma_f32 v121, -v117, v205, v121
	v_fma_f32 v120, -v118, v178, v120
	v_fma_f32 v121, -v118, v206, v121
	v_fma_f32 v120, -v119, v179, v120
	v_fma_f32 v121, -v119, v207, v121
	ds_read_b128 v[176:179], v181 offset:15536
	ds_read_b128 v[204:207], v181 offset:15792
	s_waitcnt lgkmcnt(14)
	v_fma_f32 v122, -v116, v208, v122
	v_fma_f32 v123, -v116, v212, v123
	v_fma_f32 v122, -v117, v209, v122
	v_fma_f32 v123, -v117, v213, v123
	v_fma_f32 v122, -v118, v210, v122
	v_fma_f32 v123, -v118, v214, v123
	v_fma_f32 v122, -v119, v211, v122
	v_fma_f32 v123, -v119, v215, v123
	ds_read_b128 v[208:211], v181 offset:16048
	ds_read_b128 v[212:215], v181 offset:16304
	s_waitcnt lgkmcnt(14)
	v_fma_f32 v124, -v116, v144, v124
	v_fma_f32 v125, -v116, v148, v125
	v_fma_f32 v124, -v117, v145, v124
	v_fma_f32 v125, -v117, v149, v125
	v_fma_f32 v124, -v118, v146, v124
	v_fma_f32 v125, -v118, v150, v125
	v_fma_f32 v124, -v119, v147, v124
	v_fma_f32 v125, -v119, v151, v125
	ds_read_b128 v[144:147], v181 offset:12736
	ds_read_b128 v[148:151], v181 offset:12992
	s_waitcnt lgkmcnt(14)
	v_fma_f32 v126, -v116, v152, v126
	v_fma_f32 v127, -v116, v156, v127
	v_fma_f32 v126, -v117, v153, v126
	v_fma_f32 v127, -v117, v157, v127
	v_fma_f32 v126, -v118, v154, v126
	v_fma_f32 v127, -v118, v158, v127
	v_fma_f32 v126, -v119, v155, v126
	v_fma_f32 v127, -v119, v159, v127
	ds_read_b128 v[152:155], v181 offset:13248
	ds_read_b128 v[156:159], v181 offset:13504
	s_waitcnt lgkmcnt(10)
	v_fma_f32 v128, -v116, v160, v128
	v_fma_f32 v129, -v116, v164, v129
	v_fma_f32 v128, -v117, v161, v128
	v_fma_f32 v129, -v117, v165, v129
	v_fma_f32 v128, -v118, v162, v128
	v_fma_f32 v129, -v118, v166, v129
	v_fma_f32 v128, -v119, v163, v128
	v_fma_f32 v129, -v119, v167, v129
	ds_read_b128 v[160:163], v181 offset:13760
	ds_read_b128 v[164:167], v181 offset:14016
	s_waitcnt lgkmcnt(10)
	v_fma_f32 v130, -v116, v168, v130
	v_fma_f32 v131, -v116, v172, v131
	v_fma_f32 v130, -v117, v169, v130
	v_fma_f32 v131, -v117, v173, v131
	v_fma_f32 v130, -v118, v170, v130
	v_fma_f32 v131, -v118, v174, v131
	v_fma_f32 v130, -v119, v171, v130
	v_fma_f32 v131, -v119, v175, v131
	ds_read_b128 v[168:171], v181 offset:14272
	ds_read_b128 v[172:175], v181 offset:14528
	s_waitcnt lgkmcnt(10)
	v_fma_f32 v132, -v116, v176, v132
	v_fma_f32 v133, -v116, v204, v133
	v_fma_f32 v132, -v117, v177, v132
	v_fma_f32 v133, -v117, v205, v133
	v_fma_f32 v132, -v118, v178, v132
	v_fma_f32 v133, -v118, v206, v133
	v_fma_f32 v132, -v119, v179, v132
	v_fma_f32 v133, -v119, v207, v133
	ds_read_b128 v[176:179], v181 offset:14784
	ds_read_b128 v[204:207], v181 offset:15040
	s_waitcnt lgkmcnt(10)
	v_fma_f32 v134, -v116, v208, v134
	v_fma_f32 v135, -v116, v212, v135
	v_fma_f32 v134, -v117, v209, v134
	v_fma_f32 v135, -v117, v213, v135
	v_fma_f32 v134, -v118, v210, v134
	v_fma_f32 v135, -v118, v214, v135
	v_fma_f32 v134, -v119, v211, v134
	v_fma_f32 v135, -v119, v215, v135
	ds_read_b128 v[208:211], v181 offset:15296
	ds_read_b128 v[212:215], v181 offset:15552
	s_waitcnt lgkmcnt(9)
	v_fma_f32 v121, -v120, v144, v121
	v_fma_f32 v122, -v120, v148, v122
	v_fma_f32 v123, -v120, v152, v123
	v_fma_f32 v122, -v149, v121, v122
	v_fma_f32 v123, -v153, v121, v123
	v_fma_f32 v123, -v154, v122, v123
	ds_write_b32 v91, v120 offset:49152
	ds_write_b32 v91, v121 offset:50176
	ds_write_b32 v91, v122 offset:51200
	ds_write_b32 v91, v123 offset:52224
	ds_read_b128 v[144:147], v181 offset:15808
	ds_read_b128 v[148:151], v181 offset:16064
	ds_read_b128 v[152:155], v181 offset:16320
	s_waitcnt lgkmcnt(14)
	v_fma_f32 v124, -v120, v156, v124
	v_fma_f32 v125, -v120, v160, v125
	v_fma_f32 v124, -v121, v157, v124
	v_fma_f32 v125, -v121, v161, v125
	v_fma_f32 v124, -v122, v158, v124
	v_fma_f32 v125, -v122, v162, v125
	v_fma_f32 v124, -v123, v159, v124
	v_fma_f32 v125, -v123, v163, v125
	ds_read_b128 v[156:159], v181 offset:13776
	ds_read_b128 v[160:163], v181 offset:14032
	s_waitcnt lgkmcnt(14)
	v_fma_f32 v126, -v120, v164, v126
	v_fma_f32 v127, -v120, v168, v127
	v_fma_f32 v126, -v121, v165, v126
	v_fma_f32 v127, -v121, v169, v127
	v_fma_f32 v126, -v122, v166, v126
	v_fma_f32 v127, -v122, v170, v127
	v_fma_f32 v126, -v123, v167, v126
	v_fma_f32 v127, -v123, v171, v127
	ds_read_b128 v[164:167], v181 offset:14288
	ds_read_b128 v[168:171], v181 offset:14544
	s_waitcnt lgkmcnt(14)
	v_fma_f32 v128, -v120, v172, v128
	v_fma_f32 v129, -v120, v176, v129
	v_fma_f32 v128, -v121, v173, v128
	v_fma_f32 v129, -v121, v177, v129
	v_fma_f32 v128, -v122, v174, v128
	v_fma_f32 v129, -v122, v178, v129
	v_fma_f32 v128, -v123, v175, v128
	v_fma_f32 v129, -v123, v179, v129
	ds_read_b128 v[172:175], v181 offset:14800
	ds_read_b128 v[176:179], v181 offset:15056
	s_waitcnt lgkmcnt(14)
; #define LAS __attribute__((address_space(3)))
; __device__ __forceinline__ void phase_dnprep(ArgsRef a, const Tb tb, int l, LAS unsigned char* lds) {
;     ...
;             for (int jp = 0; jp < 16; ++jp) {
;                 const int r0 = 4 * jp;
;                 const f32x4 d1 = *(LAS const f32x4*)(Lm + (r0 + 1) * 64 + r0), d2 = *(LAS const f32x4*)(Lm + (r0 + 2) * 64 + r0), d3 = *(LAS const f32x4*)(Lm + (r0 + 3) * 64 + r0);
;                 const float x0 = acc[r0];
;                 const float x1 = acc[r0 + 1] - d1[0] * x0;
;                 const float x2 = (acc[r0 + 2] - d2[0] * x0) - d2[1] * x1;
;                 const float x3 = ((acc[r0 + 3] - d3[0] * x0) - d3[1] * x1) - d3[2] * x2;
;                 rhs[(r0 + 0) * 256 + col] = x0; rhs[(r0 + 1) * 256 + col] = x1; rhs[(r0 + 2) * 256 + col] = x2; rhs[(r0 + 3) * 256 + col] = x3;
; #pragma unroll
;                 for (int i = r0 + 4; i < 64; ++i) {
;                     const f32x4 l4 = *(LAS const f32x4*)(Lm + i * 64 + r0);
;                     acc[i] = (((acc[i] - l4[0] * x0) - l4[1] * x1) - l4[2] * x2) - l4[3] * x3;
;                 }
	v_fma_f32 v130, -v120, v204, v130
	v_fma_f32 v131, -v120, v208, v131
	v_fma_f32 v130, -v121, v205, v130
	v_fma_f32 v131, -v121, v209, v131
	v_fma_f32 v130, -v122, v206, v130
	v_fma_f32 v131, -v122, v210, v131
	v_fma_f32 v130, -v123, v207, v130
	v_fma_f32 v131, -v123, v211, v131
	ds_read_b128 v[204:207], v181 offset:15312
	ds_read_b128 v[208:211], v181 offset:15568
	s_waitcnt lgkmcnt(10)
	v_fma_f32 v132, -v120, v212, v132
	v_fma_f32 v133, -v120, v144, v133
	v_fma_f32 v132, -v121, v213, v132
	v_fma_f32 v133, -v121, v145, v133
	v_fma_f32 v132, -v122, v214, v132
	v_fma_f32 v133, -v122, v146, v133
	v_fma_f32 v132, -v123, v215, v132
	v_fma_f32 v133, -v123, v147, v133
	ds_read_b128 v[212:215], v181 offset:15824
	ds_read_b128 v[144:147], v181 offset:16080
	s_waitcnt lgkmcnt(10)
	v_fma_f32 v134, -v120, v148, v134
	v_fma_f32 v135, -v120, v152, v135
	v_fma_f32 v134, -v121, v149, v134
	v_fma_f32 v135, -v121, v153, v135
	v_fma_f32 v134, -v122, v150, v134
	v_fma_f32 v135, -v122, v154, v135
	v_fma_f32 v134, -v123, v151, v134
	v_fma_f32 v135, -v123, v155, v135
	ds_read_b128 v[148:151], v181 offset:16336
	ds_read_b128 v[152:155], v181 offset:14816
	s_waitcnt lgkmcnt(9)
	v_fma_f32 v125, -v124, v156, v125
	v_fma_f32 v126, -v124, v160, v126
	v_fma_f32 v127, -v124, v164, v127
	v_fma_f32 v126, -v161, v125, v126
	v_fma_f32 v127, -v165, v125, v127
	v_fma_f32 v127, -v166, v126, v127
	ds_write_b32 v91, v124 offset:53248
	ds_write_b32 v91, v125 offset:54272
	ds_write_b32 v91, v126 offset:55296
	ds_write_b32 v91, v127 offset:56320
	ds_read_b128 v[156:159], v181 offset:15072
	ds_read_b128 v[160:163], v181 offset:15328
	ds_read_b128 v[164:167], v181 offset:15584
	s_waitcnt lgkmcnt(14)
	v_fma_f32 v128, -v124, v168, v128
	v_fma_f32 v129, -v124, v172, v129
	v_fma_f32 v128, -v125, v169, v128
	v_fma_f32 v129, -v125, v173, v129
	v_fma_f32 v128, -v126, v170, v128
	v_fma_f32 v129, -v126, v174, v129
	v_fma_f32 v128, -v127, v171, v128
	v_fma_f32 v129, -v127, v175, v129
	ds_read_b128 v[168:171], v181 offset:15840
	ds_read_b128 v[172:175], v181 offset:16096
	s_waitcnt lgkmcnt(14)
	v_fma_f32 v130, -v124, v176, v130
	v_fma_f32 v131, -v124, v204, v131
	v_fma_f32 v130, -v125, v177, v130
	v_fma_f32 v131, -v125, v205, v131
	v_fma_f32 v130, -v126, v178, v130
	v_fma_f32 v131, -v126, v206, v131
	v_fma_f32 v130, -v127, v179, v130
	v_fma_f32 v131, -v127, v207, v131
	ds_read_b128 v[176:179], v181 offset:16352
	ds_read_b128 v[204:207], v181 offset:15856
	s_waitcnt lgkmcnt(14)
	v_fma_f32 v132, -v124, v208, v132
	v_fma_f32 v133, -v124, v212, v133
	v_fma_f32 v132, -v125, v209, v132
	v_fma_f32 v133, -v125, v213, v133
	v_fma_f32 v132, -v126, v210, v132
	v_fma_f32 v133, -v126, v214, v133
	v_fma_f32 v132, -v127, v211, v132
	v_fma_f32 v133, -v127, v215, v133
	ds_read_b128 v[208:211], v181 offset:16112
	ds_read_b128 v[212:215], v181 offset:16368
	s_waitcnt lgkmcnt(14)
	v_fma_f32 v134, -v124, v144, v134
	v_fma_f32 v135, -v124, v148, v135
	v_fma_f32 v134, -v125, v145, v134
	v_fma_f32 v135, -v125, v149, v135
	v_fma_f32 v134, -v126, v146, v134
	v_fma_f32 v135, -v126, v150, v135
	v_fma_f32 v134, -v127, v147, v134
	v_fma_f32 v135, -v127, v151, v135
	s_waitcnt lgkmcnt(7)
	v_fma_f32 v129, -v128, v152, v129
	v_fma_f32 v130, -v128, v156, v130
	v_fma_f32 v131, -v128, v160, v131
	v_fma_f32 v130, -v157, v129, v130
	v_fma_f32 v131, -v161, v129, v131
	v_fma_f32 v131, -v162, v130, v131
	ds_write_b32 v91, v128 offset:57344
	ds_write_b32 v91, v129 offset:58368
	ds_write_b32 v91, v130 offset:59392
	ds_write_b32 v91, v131 offset:60416
	s_waitcnt lgkmcnt(9)
	v_fma_f32 v132, -v128, v164, v132
	v_fma_f32 v133, -v128, v168, v133
	v_fma_f32 v132, -v129, v165, v132
	v_fma_f32 v133, -v129, v169, v133
	v_fma_f32 v132, -v130, v166, v132
	v_fma_f32 v133, -v130, v170, v133
	v_fma_f32 v132, -v131, v167, v132
	v_fma_f32 v133, -v131, v171, v133
	s_waitcnt lgkmcnt(7)
	v_fma_f32 v134, -v128, v172, v134
	v_fma_f32 v135, -v128, v176, v135
	v_fma_f32 v134, -v129, v173, v134
	v_fma_f32 v135, -v129, v177, v135
	v_fma_f32 v134, -v130, v174, v134
	v_fma_f32 v135, -v130, v178, v135
	v_fma_f32 v134, -v131, v175, v134
	v_fma_f32 v135, -v131, v179, v135
	s_waitcnt lgkmcnt(4)
	v_fma_f32 v133, -v132, v204, v133
	v_fma_f32 v134, -v132, v208, v134
	v_fma_f32 v135, -v132, v212, v135
	v_fma_f32 v134, -v209, v133, v134
	v_fma_f32 v135, -v213, v133, v135
	v_fma_f32 v135, -v214, v134, v135
	ds_write_b32 v91, v132 offset:61440
	ds_write_b32 v91, v133 offset:62464
	ds_write_b32 v91, v134 offset:63488
	ds_write_b32 v91, v135 offset:64512
	s_branch .LBB0_1024

; __device__ __forceinline__ unsigned pk2(float lo, float hi) { const f32x2_t v = {lo, hi}; const bf16x2_t b = __builtin_convertvector(v, bf16x2_t); return __builtin_bit_cast(unsigned, b); }
; __device__ __forceinline__ float bflo(unsigned w) { return __uint_as_float(w << 16); }
; __device__ __forceinline__ float bfhi(unsigned w) { return __uint_as_float(w & 0xffff0000u); }
;     __device__ __forceinline__ void operator()(const f32x4 (&acc)[2][2][4][2], const pg8::Unit& u, int wr, int wc, int fr, int fq) const {
;     ...
;                 const int row = row0 + ai * 128 + m * 16; float mu, rstd; row_stats(stats_prev, row, mu, rstd);
;                 float s = 0.f, q = 0.f;
; #pragma unroll
;                 for (int bj = 0; bj < 2; ++bj)
; #pragma unroll
;                     for (int n = 0; n < 2; ++n) {
;                         const int col = col0 + bj * 128 + n * 16;
;                         const u32x2 rb = *(const u32x2*)(YB + (size_t)row * D_ + col);
;                         f32x4 r = (f32x4){bflo(rb.x), bfhi(rb.x), bflo(rb.y), bfhi(rb.y)};
;                         if (stats_prev) { const f32x4 g4 = *(const f32x4*)(lng + col), b4 = *(const f32x4*)(lnb + col); r = (r - mu) * rstd * g4 + b4; }
;                         const f32x4 y = r * ALPHA_ + acc[ai][bj][m][n] * coef;
;                         if (Yout) *(f32x4*)(Yout + (size_t)row * D_ + col) = y;
;                         else { u32x2 w; w.x = pk2(y[0], y[1]); w.y = pk2(y[2], y[3]); *(u32x2*)(YB + (size_t)row * D_ + col) = w; }
.LBB0_1469:
	v_lshl_or_b32 v138, s33, 8, v154
	v_lshlrev_b64 v[134:135], 11, v[140:141]
	v_lshl_add_u64 v[134:135], s[12:13], 0, v[134:135]
	v_ashrrev_i32_e32 v139, 31, v138
	v_lshl_add_u64 v[142:143], v[138:139], 1, v[134:135]
	global_load_dwordx2 v[136:137], v[142:143], off
	global_load_dwordx2 v[220:221], v[142:143], off offset:32
	global_load_dwordx2 v[222:223], v[142:143], off offset:256
	global_load_dwordx2 v[224:225], v[142:143], off offset:288
	v_lshlrev_b64 v[156:157], 2, v[138:139]
	v_mov_b32_e32 v147, v146
	s_and_b64 vcc, exec, s[6:7]
	v_lshl_add_u64 v[134:135], s[14:15], 0, v[156:157]
	s_waitcnt vmcnt(3)
	v_lshlrev_b32_e32 v148, 16, v136
	v_and_b32_e32 v149, 0xffff0000, v136
	v_lshlrev_b32_e32 v150, 16, v137
	v_and_b32_e32 v151, 0xffff0000, v137
	v_lshl_add_u64 v[136:137], s[16:17], 0, v[156:157]
	s_cbranch_vccnz .LBB0_1471
	v_sub_f32_e32 v149, v149, v144
	v_sub_f32_e32 v148, v148, v144
	v_sub_f32_e32 v151, v151, v144
	v_sub_f32_e32 v150, v150, v144
	v_pk_mul_f32 v[160:161], v[146:147], v[148:149]
	v_mov_b32_e32 v148, v146
	v_mov_b32_e32 v149, v146
	v_pk_mul_f32 v[162:163], v[148:149], v[150:151]
	global_load_dwordx4 v[164:167], v[134:135], off
	global_load_dwordx4 v[204:207], v[136:137], off
	global_load_dwordx4 v[168:171], v[134:135], off offset:64
	global_load_dwordx4 v[208:211], v[136:137], off offset:64
	global_load_dwordx4 v[172:175], v[134:135], off offset:512
	global_load_dwordx4 v[212:215], v[136:137], off offset:512
	global_load_dwordx4 v[176:179], v[134:135], off offset:576
	global_load_dwordx4 v[216:219], v[136:137], off offset:576
	s_waitcnt vmcnt(0)
	v_pk_fma_f32 v[150:151], v[162:163], v[166:167], v[206:207]
	v_pk_fma_f32 v[148:149], v[160:161], v[164:165], v[204:205]
.LBB0_1471:
	s_mov_b32 s22, 0x3fb504f3
	v_pk_mul_f32 v[150:151], v[150:151], s[22:23] op_sel_hi:[1,0]
	v_pk_mul_f32 v[148:149], v[148:149], s[22:23] op_sel_hi:[1,0]
	v_pk_fma_f32 v[126:127], v[126:127], 0.5, v[150:151] op_sel_hi:[1,0,1]
	v_pk_fma_f32 v[124:125], v[124:125], 0.5, v[148:149] op_sel_hi:[1,0,1]
	v_cvt_pk_bf16_f32 v149, v126, v127
	v_cvt_pk_bf16_f32 v148, v124, v125
	global_store_dwordx2 v[142:143], v[148:149], off
	s_and_b64 vcc, exec, s[6:7]
	s_waitcnt vmcnt(3)
	v_lshlrev_b32_e32 v148, 16, v220
	v_and_b32_e32 v149, 0xffff0000, v220
	v_lshlrev_b32_e32 v150, 16, v221
	v_and_b32_e32 v151, 0xffff0000, v221
	s_cbranch_vccnz .LBB0_1473
	v_sub_f32_e32 v149, v149, v144
	v_sub_f32_e32 v148, v148, v144
	v_sub_f32_e32 v151, v151, v144
	v_sub_f32_e32 v150, v150, v144
	v_pk_mul_f32 v[160:161], v[146:147], v[148:149]
	v_mov_b32_e32 v148, v146
	v_mov_b32_e32 v149, v146
	v_pk_mul_f32 v[162:163], v[148:149], v[150:151]
	v_pk_fma_f32 v[150:151], v[162:163], v[170:171], v[210:211]
	v_pk_fma_f32 v[148:149], v[160:161], v[168:169], v[208:209]
.LBB0_1473:
	v_pk_mul_f32 v[150:151], v[150:151], s[22:23] op_sel_hi:[1,0]
	v_pk_mul_f32 v[148:149], v[148:149], s[22:23] op_sel_hi:[1,0]
	v_pk_fma_f32 v[122:123], v[122:123], 0.5, v[150:151] op_sel_hi:[1,0,1]
	v_pk_fma_f32 v[120:121], v[120:121], 0.5, v[148:149] op_sel_hi:[1,0,1]
	v_cvt_pk_bf16_f32 v149, v122, v123
	v_cvt_pk_bf16_f32 v148, v120, v121
	global_store_dwordx2 v[142:143], v[148:149], off offset:32
	s_and_b64 vcc, exec, s[6:7]
	s_waitcnt vmcnt(3)
	v_lshlrev_b32_e32 v148, 16, v222
	v_and_b32_e32 v149, 0xffff0000, v222
	v_lshlrev_b32_e32 v150, 16, v223
	v_and_b32_e32 v151, 0xffff0000, v223
	s_cbranch_vccnz .LBB0_1475
	v_sub_f32_e32 v149, v149, v144
	v_sub_f32_e32 v148, v148, v144
	v_sub_f32_e32 v151, v151, v144
	v_sub_f32_e32 v150, v150, v144
	v_pk_mul_f32 v[160:161], v[146:147], v[148:149]
	v_mov_b32_e32 v148, v146
	v_mov_b32_e32 v149, v146
	v_pk_mul_f32 v[162:163], v[148:149], v[150:151]
	v_pk_fma_f32 v[150:151], v[162:163], v[174:175], v[214:215]
	v_pk_fma_f32 v[148:149], v[160:161], v[172:173], v[212:213]
.LBB0_1475:
	v_pk_mul_f32 v[150:151], v[150:151], s[22:23] op_sel_hi:[1,0]
	v_pk_mul_f32 v[148:149], v[148:149], s[22:23] op_sel_hi:[1,0]
	v_pk_fma_f32 v[118:119], v[118:119], 0.5, v[150:151] op_sel_hi:[1,0,1]
	v_pk_fma_f32 v[116:117], v[116:117], 0.5, v[148:149] op_sel_hi:[1,0,1]
	v_cvt_pk_bf16_f32 v149, v118, v119
	v_cvt_pk_bf16_f32 v148, v116, v117
	global_store_dwordx2 v[142:143], v[148:149], off offset:256
	s_and_b64 vcc, exec, s[6:7]
	s_waitcnt vmcnt(3)
	v_lshlrev_b32_e32 v148, 16, v224
	v_and_b32_e32 v149, 0xffff0000, v224
	v_lshlrev_b32_e32 v150, 16, v225
	v_and_b32_e32 v151, 0xffff0000, v225
	s_cbranch_vccnz .LBB0_1477
	v_sub_f32_e32 v151, v151, v144
	v_sub_f32_e32 v150, v150, v144
	v_sub_f32_e32 v145, v149, v144
	v_sub_f32_e32 v144, v148, v144
	v_pk_mul_f32 v[156:157], v[146:147], v[144:145]
	v_mov_b32_e32 v147, v146
	v_pk_mul_f32 v[158:159], v[146:147], v[150:151]
	v_pk_fma_f32 v[150:151], v[158:159], v[178:179], v[218:219]
	v_pk_fma_f32 v[148:149], v[156:157], v[176:177], v[216:217]

; __device__ __forceinline__ unsigned pk2(float lo, float hi) { const f32x2_t v = {lo, hi}; const bf16x2_t b = __builtin_convertvector(v, bf16x2_t); return __builtin_bit_cast(unsigned, b); }
; __device__ __forceinline__ float bflo(unsigned w) { return __uint_as_float(w << 16); }
; __device__ __forceinline__ float bfhi(unsigned w) { return __uint_as_float(w & 0xffff0000u); }
;     __device__ __forceinline__ void operator()(const f32x4 (&acc)[2][2][4][2], const pg8::Unit& u, int wr, int wc, int fr, int fq) const {
;     ...
;                 const int row = row0 + ai * 128 + m * 16; float mu, rstd; row_stats(stats_prev, row, mu, rstd);
;                 float s = 0.f, q = 0.f;
; #pragma unroll
;                 for (int bj = 0; bj < 2; ++bj)
; #pragma unroll
;                     for (int n = 0; n < 2; ++n) {
;                         const int col = col0 + bj * 128 + n * 16;
;                         const u32x2 rb = *(const u32x2*)(YB + (size_t)row * D_ + col);
;                         f32x4 r = (f32x4){bflo(rb.x), bfhi(rb.x), bflo(rb.y), bfhi(rb.y)};
;                         if (stats_prev) { const f32x4 g4 = *(const f32x4*)(lng + col), b4 = *(const f32x4*)(lnb + col); r = (r - mu) * rstd * g4 + b4; }
;                         const f32x4 y = r * ALPHA_ + acc[ai][bj][m][n] * coef;
;                         if (Yout) *(f32x4*)(Yout + (size_t)row * D_ + col) = y;
;                         else { u32x2 w; w.x = pk2(y[0], y[1]); w.y = pk2(y[2], y[3]); *(u32x2*)(YB + (size_t)row * D_ + col) = w; }
.LBB0_1482:
	s_waitcnt lgkmcnt(0)
	v_lshlrev_b64 v[114:115], 11, v[112:113]
	v_lshl_add_u64 v[114:115], s[12:13], 0, v[114:115]
	v_lshl_add_u64 v[114:115], v[138:139], 1, v[114:115]
	global_load_dwordx2 v[122:123], v[114:115], off
	global_load_dwordx2 v[220:221], v[114:115], off offset:32
	global_load_dwordx2 v[222:223], v[114:115], off offset:256
	global_load_dwordx2 v[224:225], v[114:115], off offset:288
	v_mov_b32_e32 v119, v118
	s_and_b64 vcc, exec, s[6:7]
	s_waitcnt vmcnt(3)
	v_lshlrev_b32_e32 v120, 16, v122
	v_and_b32_e32 v121, 0xffff0000, v122
	v_lshlrev_b32_e32 v122, 16, v123
	v_and_b32_e32 v123, 0xffff0000, v123
	s_cbranch_vccnz .LBB0_1484
	v_sub_f32_e32 v121, v121, v116
	v_sub_f32_e32 v120, v120, v116
	v_sub_f32_e32 v123, v123, v116
	v_sub_f32_e32 v122, v122, v116
	v_pk_mul_f32 v[126:127], v[118:119], v[120:121]
	v_mov_b32_e32 v120, v118
	v_mov_b32_e32 v121, v118
	v_pk_mul_f32 v[146:147], v[120:121], v[122:123]
	v_pk_fma_f32 v[122:123], v[146:147], v[166:167], v[206:207]
	v_pk_fma_f32 v[120:121], v[126:127], v[164:165], v[204:205]
.LBB0_1484:
	s_mov_b32 s24, 0x3fb504f3
	v_pk_mul_f32 v[122:123], v[122:123], s[24:25] op_sel_hi:[1,0]
	v_pk_mul_f32 v[120:121], v[120:121], s[24:25] op_sel_hi:[1,0]
	v_pk_fma_f32 v[110:111], v[110:111], 0.5, v[122:123] op_sel_hi:[1,0,1]
	v_pk_fma_f32 v[108:109], v[108:109], 0.5, v[120:121] op_sel_hi:[1,0,1]
	v_cvt_pk_bf16_f32 v121, v110, v111
	v_cvt_pk_bf16_f32 v120, v108, v109
	global_store_dwordx2 v[114:115], v[120:121], off
	s_and_b64 vcc, exec, s[6:7]
	s_waitcnt vmcnt(3)
	v_lshlrev_b32_e32 v120, 16, v220
	v_and_b32_e32 v121, 0xffff0000, v220
	v_lshlrev_b32_e32 v122, 16, v221
	v_and_b32_e32 v123, 0xffff0000, v221
	s_cbranch_vccnz .LBB0_1486
	v_sub_f32_e32 v121, v121, v116
	v_sub_f32_e32 v120, v120, v116
	v_sub_f32_e32 v123, v123, v116
	v_sub_f32_e32 v122, v122, v116
	v_pk_mul_f32 v[126:127], v[118:119], v[120:121]
	v_mov_b32_e32 v120, v118
	v_mov_b32_e32 v121, v118
	v_pk_mul_f32 v[146:147], v[120:121], v[122:123]
	v_pk_fma_f32 v[122:123], v[146:147], v[170:171], v[210:211]
	v_pk_fma_f32 v[120:121], v[126:127], v[168:169], v[208:209]
.LBB0_1486:
	v_pk_mul_f32 v[122:123], v[122:123], s[24:25] op_sel_hi:[1,0]
	v_pk_mul_f32 v[120:121], v[120:121], s[24:25] op_sel_hi:[1,0]
	v_pk_fma_f32 v[106:107], v[106:107], 0.5, v[122:123] op_sel_hi:[1,0,1]
	v_pk_fma_f32 v[104:105], v[104:105], 0.5, v[120:121] op_sel_hi:[1,0,1]
	v_cvt_pk_bf16_f32 v121, v106, v107
	v_cvt_pk_bf16_f32 v120, v104, v105
	global_store_dwordx2 v[114:115], v[120:121], off offset:32
	s_and_b64 vcc, exec, s[6:7]
	s_waitcnt vmcnt(3)
	v_lshlrev_b32_e32 v120, 16, v222
	v_and_b32_e32 v121, 0xffff0000, v222
	v_lshlrev_b32_e32 v122, 16, v223
	v_and_b32_e32 v123, 0xffff0000, v223
	s_cbranch_vccnz .LBB0_1488
	v_sub_f32_e32 v121, v121, v116
	v_sub_f32_e32 v120, v120, v116
	v_sub_f32_e32 v123, v123, v116
	v_sub_f32_e32 v122, v122, v116
	v_pk_mul_f32 v[126:127], v[118:119], v[120:121]
	v_mov_b32_e32 v120, v118
	v_mov_b32_e32 v121, v118
	v_pk_mul_f32 v[146:147], v[120:121], v[122:123]
	v_pk_fma_f32 v[122:123], v[146:147], v[174:175], v[214:215]
	v_pk_fma_f32 v[120:121], v[126:127], v[172:173], v[212:213]
.LBB0_1488:
	v_pk_mul_f32 v[122:123], v[122:123], s[24:25] op_sel_hi:[1,0]
	v_pk_mul_f32 v[120:121], v[120:121], s[24:25] op_sel_hi:[1,0]
	v_pk_fma_f32 v[102:103], v[102:103], 0.5, v[122:123] op_sel_hi:[1,0,1]
	v_pk_fma_f32 v[100:101], v[100:101], 0.5, v[120:121] op_sel_hi:[1,0,1]
	v_cvt_pk_bf16_f32 v121, v102, v103
	v_cvt_pk_bf16_f32 v120, v100, v101
	global_store_dwordx2 v[114:115], v[120:121], off offset:256
	s_and_b64 vcc, exec, s[6:7]
	s_waitcnt vmcnt(3)
	v_lshlrev_b32_e32 v120, 16, v224
	v_and_b32_e32 v121, 0xffff0000, v224
	v_lshlrev_b32_e32 v122, 16, v225
	v_and_b32_e32 v123, 0xffff0000, v225
	s_cbranch_vccnz .LBB0_1490
	v_sub_f32_e32 v123, v123, v116
	v_sub_f32_e32 v122, v122, v116
	v_sub_f32_e32 v117, v121, v116
	v_sub_f32_e32 v116, v120, v116
	v_pk_mul_f32 v[126:127], v[118:119], v[116:117]
	v_mov_b32_e32 v119, v118
	v_pk_mul_f32 v[142:143], v[118:119], v[122:123]
	v_pk_fma_f32 v[122:123], v[142:143], v[178:179], v[218:219]
	v_pk_fma_f32 v[120:121], v[126:127], v[176:177], v[216:217]

; __device__ __forceinline__ unsigned pk2(float lo, float hi) { const f32x2_t v = {lo, hi}; const bf16x2_t b = __builtin_convertvector(v, bf16x2_t); return __builtin_bit_cast(unsigned, b); }
; __device__ __forceinline__ float bflo(unsigned w) { return __uint_as_float(w << 16); }
; __device__ __forceinline__ float bfhi(unsigned w) { return __uint_as_float(w & 0xffff0000u); }
;     __device__ __forceinline__ void operator()(const f32x4 (&acc)[2][2][4][2], const pg8::Unit& u, int wr, int wc, int fr, int fq) const {
;     ...
;                 const int row = row0 + ai * 128 + m * 16; float mu, rstd; row_stats(stats_prev, row, mu, rstd);
;                 float s = 0.f, q = 0.f;
; #pragma unroll
;                 for (int bj = 0; bj < 2; ++bj)
; #pragma unroll
;                     for (int n = 0; n < 2; ++n) {
;                         const int col = col0 + bj * 128 + n * 16;
;                         const u32x2 rb = *(const u32x2*)(YB + (size_t)row * D_ + col);
;                         f32x4 r = (f32x4){bflo(rb.x), bfhi(rb.x), bflo(rb.y), bfhi(rb.y)};
;                         if (stats_prev) { const f32x4 g4 = *(const f32x4*)(lng + col), b4 = *(const f32x4*)(lnb + col); r = (r - mu) * rstd * g4 + b4; }
;                         const f32x4 y = r * ALPHA_ + acc[ai][bj][m][n] * coef;
;                         if (Yout) *(f32x4*)(Yout + (size_t)row * D_ + col) = y;
;                         else { u32x2 w; w.x = pk2(y[0], y[1]); w.y = pk2(y[2], y[3]); *(u32x2*)(YB + (size_t)row * D_ + col) = w; }
.LBB0_1495:
	s_waitcnt lgkmcnt(0)
	v_lshlrev_b64 v[98:99], 11, v[96:97]
	v_lshl_add_u64 v[98:99], s[12:13], 0, v[98:99]
	v_lshl_add_u64 v[98:99], v[138:139], 1, v[98:99]
	global_load_dwordx2 v[106:107], v[98:99], off
	global_load_dwordx2 v[220:221], v[98:99], off offset:32
	global_load_dwordx2 v[222:223], v[98:99], off offset:256
	global_load_dwordx2 v[224:225], v[98:99], off offset:288
	v_mov_b32_e32 v103, v102
	s_and_b64 vcc, exec, s[6:7]
	s_waitcnt vmcnt(3)
	v_lshlrev_b32_e32 v104, 16, v106
	v_and_b32_e32 v105, 0xffff0000, v106
	v_lshlrev_b32_e32 v106, 16, v107
	v_and_b32_e32 v107, 0xffff0000, v107
	s_cbranch_vccnz .LBB0_1497
	v_sub_f32_e32 v105, v105, v100
	v_sub_f32_e32 v104, v104, v100
	v_sub_f32_e32 v107, v107, v100
	v_sub_f32_e32 v106, v106, v100
	v_pk_mul_f32 v[112:113], v[102:103], v[104:105]
	v_mov_b32_e32 v104, v102
	v_mov_b32_e32 v105, v102
	v_pk_mul_f32 v[114:115], v[104:105], v[106:107]
	v_pk_fma_f32 v[106:107], v[114:115], v[166:167], v[206:207]
	v_pk_fma_f32 v[104:105], v[112:113], v[164:165], v[204:205]
.LBB0_1497:
	s_mov_b32 s24, 0x3fb504f3
	v_pk_mul_f32 v[106:107], v[106:107], s[24:25] op_sel_hi:[1,0]
	v_pk_mul_f32 v[104:105], v[104:105], s[24:25] op_sel_hi:[1,0]
	v_pk_fma_f32 v[94:95], v[94:95], 0.5, v[106:107] op_sel_hi:[1,0,1]
	v_pk_fma_f32 v[92:93], v[92:93], 0.5, v[104:105] op_sel_hi:[1,0,1]
	v_cvt_pk_bf16_f32 v105, v94, v95
	v_cvt_pk_bf16_f32 v104, v92, v93
	global_store_dwordx2 v[98:99], v[104:105], off
	s_and_b64 vcc, exec, s[6:7]
	s_waitcnt vmcnt(3)
	v_lshlrev_b32_e32 v104, 16, v220
	v_and_b32_e32 v105, 0xffff0000, v220
	v_lshlrev_b32_e32 v106, 16, v221
	v_and_b32_e32 v107, 0xffff0000, v221
	s_cbranch_vccnz .LBB0_1499
	v_sub_f32_e32 v105, v105, v100
	v_sub_f32_e32 v104, v104, v100
	v_sub_f32_e32 v107, v107, v100
	v_sub_f32_e32 v106, v106, v100
	v_pk_mul_f32 v[112:113], v[102:103], v[104:105]
	v_mov_b32_e32 v104, v102
	v_mov_b32_e32 v105, v102
	v_pk_mul_f32 v[114:115], v[104:105], v[106:107]
	v_pk_fma_f32 v[106:107], v[114:115], v[170:171], v[210:211]
	v_pk_fma_f32 v[104:105], v[112:113], v[168:169], v[208:209]
.LBB0_1499:
	v_pk_mul_f32 v[106:107], v[106:107], s[24:25] op_sel_hi:[1,0]
	v_pk_mul_f32 v[104:105], v[104:105], s[24:25] op_sel_hi:[1,0]
	v_pk_fma_f32 v[90:91], v[90:91], 0.5, v[106:107] op_sel_hi:[1,0,1]
	v_pk_fma_f32 v[88:89], v[88:89], 0.5, v[104:105] op_sel_hi:[1,0,1]
	v_cvt_pk_bf16_f32 v105, v90, v91
	v_cvt_pk_bf16_f32 v104, v88, v89
	global_store_dwordx2 v[98:99], v[104:105], off offset:32
	s_and_b64 vcc, exec, s[6:7]
	s_waitcnt vmcnt(3)
	v_lshlrev_b32_e32 v104, 16, v222
	v_and_b32_e32 v105, 0xffff0000, v222
	v_lshlrev_b32_e32 v106, 16, v223
	v_and_b32_e32 v107, 0xffff0000, v223
	s_cbranch_vccnz .LBB0_1501
	v_sub_f32_e32 v105, v105, v100
	v_sub_f32_e32 v104, v104, v100
	v_sub_f32_e32 v107, v107, v100
	v_sub_f32_e32 v106, v106, v100
	v_pk_mul_f32 v[112:113], v[102:103], v[104:105]
	v_mov_b32_e32 v104, v102
	v_mov_b32_e32 v105, v102
	v_pk_mul_f32 v[114:115], v[104:105], v[106:107]
	v_pk_fma_f32 v[106:107], v[114:115], v[174:175], v[214:215]
	v_pk_fma_f32 v[104:105], v[112:113], v[172:173], v[212:213]
.LBB0_1501:
	v_pk_mul_f32 v[106:107], v[106:107], s[24:25] op_sel_hi:[1,0]
	v_pk_mul_f32 v[104:105], v[104:105], s[24:25] op_sel_hi:[1,0]
	v_pk_fma_f32 v[86:87], v[86:87], 0.5, v[106:107] op_sel_hi:[1,0,1]
	v_pk_fma_f32 v[84:85], v[84:85], 0.5, v[104:105] op_sel_hi:[1,0,1]
	v_cvt_pk_bf16_f32 v105, v86, v87
	v_cvt_pk_bf16_f32 v104, v84, v85
	global_store_dwordx2 v[98:99], v[104:105], off offset:256
	s_and_b64 vcc, exec, s[6:7]
	s_waitcnt vmcnt(3)
	v_lshlrev_b32_e32 v104, 16, v224
	v_and_b32_e32 v105, 0xffff0000, v224
	v_lshlrev_b32_e32 v106, 16, v225
	v_and_b32_e32 v107, 0xffff0000, v225
	s_cbranch_vccnz .LBB0_1503
	v_sub_f32_e32 v107, v107, v100
	v_sub_f32_e32 v106, v106, v100
	v_sub_f32_e32 v101, v105, v100
	v_sub_f32_e32 v100, v104, v100
	v_pk_mul_f32 v[108:109], v[102:103], v[100:101]
	v_mov_b32_e32 v103, v102
	v_pk_mul_f32 v[110:111], v[102:103], v[106:107]
	v_pk_fma_f32 v[106:107], v[110:111], v[178:179], v[218:219]
	v_pk_fma_f32 v[104:105], v[108:109], v[176:177], v[216:217]

; __device__ __forceinline__ unsigned pk2(float lo, float hi) { const f32x2_t v = {lo, hi}; const bf16x2_t b = __builtin_convertvector(v, bf16x2_t); return __builtin_bit_cast(unsigned, b); }
; __device__ __forceinline__ float bflo(unsigned w) { return __uint_as_float(w << 16); }
; __device__ __forceinline__ float bfhi(unsigned w) { return __uint_as_float(w & 0xffff0000u); }
;     __device__ __forceinline__ void operator()(const f32x4 (&acc)[2][2][4][2], const pg8::Unit& u, int wr, int wc, int fr, int fq) const {
;     ...
;                 const int row = row0 + ai * 128 + m * 16; float mu, rstd; row_stats(stats_prev, row, mu, rstd);
;                 float s = 0.f, q = 0.f;
; #pragma unroll
;                 for (int bj = 0; bj < 2; ++bj)
; #pragma unroll
;                     for (int n = 0; n < 2; ++n) {
;                         const int col = col0 + bj * 128 + n * 16;
;                         const u32x2 rb = *(const u32x2*)(YB + (size_t)row * D_ + col);
;                         f32x4 r = (f32x4){bflo(rb.x), bfhi(rb.x), bflo(rb.y), bfhi(rb.y)};
;                         if (stats_prev) { const f32x4 g4 = *(const f32x4*)(lng + col), b4 = *(const f32x4*)(lnb + col); r = (r - mu) * rstd * g4 + b4; }
;                         const f32x4 y = r * ALPHA_ + acc[ai][bj][m][n] * coef;
;                         if (Yout) *(f32x4*)(Yout + (size_t)row * D_ + col) = y;
;                         else { u32x2 w; w.x = pk2(y[0], y[1]); w.y = pk2(y[2], y[3]); *(u32x2*)(YB + (size_t)row * D_ + col) = w; }
.LBB0_1508:
	s_waitcnt lgkmcnt(0)
	v_lshlrev_b64 v[82:83], 11, v[80:81]
	v_lshl_add_u64 v[82:83], s[12:13], 0, v[82:83]
	v_lshl_add_u64 v[82:83], v[138:139], 1, v[82:83]
	global_load_dwordx2 v[90:91], v[82:83], off
	global_load_dwordx2 v[220:221], v[82:83], off offset:32
	global_load_dwordx2 v[222:223], v[82:83], off offset:256
	global_load_dwordx2 v[224:225], v[82:83], off offset:288
	v_mov_b32_e32 v87, v86
	s_and_b64 vcc, exec, s[6:7]
	s_waitcnt vmcnt(3)
	v_lshlrev_b32_e32 v88, 16, v90
	v_and_b32_e32 v89, 0xffff0000, v90
	v_lshlrev_b32_e32 v90, 16, v91
	v_and_b32_e32 v91, 0xffff0000, v91
	s_cbranch_vccnz .LBB0_1510
	v_sub_f32_e32 v89, v89, v84
	v_sub_f32_e32 v88, v88, v84
	v_sub_f32_e32 v91, v91, v84
	v_sub_f32_e32 v90, v90, v84
	v_pk_mul_f32 v[96:97], v[86:87], v[88:89]
	v_mov_b32_e32 v88, v86
	v_mov_b32_e32 v89, v86
	v_pk_mul_f32 v[98:99], v[88:89], v[90:91]
	v_pk_fma_f32 v[90:91], v[98:99], v[166:167], v[206:207]
	v_pk_fma_f32 v[88:89], v[96:97], v[164:165], v[204:205]
.LBB0_1510:
	s_mov_b32 s24, 0x3fb504f3
	v_pk_mul_f32 v[90:91], v[90:91], s[24:25] op_sel_hi:[1,0]
	v_pk_mul_f32 v[88:89], v[88:89], s[24:25] op_sel_hi:[1,0]
	v_pk_fma_f32 v[78:79], v[78:79], 0.5, v[90:91] op_sel_hi:[1,0,1]
	v_pk_fma_f32 v[76:77], v[76:77], 0.5, v[88:89] op_sel_hi:[1,0,1]
	v_cvt_pk_bf16_f32 v89, v78, v79
	v_cvt_pk_bf16_f32 v88, v76, v77
	global_store_dwordx2 v[82:83], v[88:89], off
	s_and_b64 vcc, exec, s[6:7]
	s_waitcnt vmcnt(3)
	v_lshlrev_b32_e32 v88, 16, v220
	v_and_b32_e32 v89, 0xffff0000, v220
	v_lshlrev_b32_e32 v90, 16, v221
	v_and_b32_e32 v91, 0xffff0000, v221
	s_cbranch_vccnz .LBB0_1512
	v_sub_f32_e32 v89, v89, v84
	v_sub_f32_e32 v88, v88, v84
	v_sub_f32_e32 v91, v91, v84
	v_sub_f32_e32 v90, v90, v84
	v_pk_mul_f32 v[96:97], v[86:87], v[88:89]
	v_mov_b32_e32 v88, v86
	v_mov_b32_e32 v89, v86
	v_pk_mul_f32 v[98:99], v[88:89], v[90:91]
	v_pk_fma_f32 v[90:91], v[98:99], v[170:171], v[210:211]
	v_pk_fma_f32 v[88:89], v[96:97], v[168:169], v[208:209]
.LBB0_1512:
	v_pk_mul_f32 v[90:91], v[90:91], s[24:25] op_sel_hi:[1,0]
	v_pk_mul_f32 v[88:89], v[88:89], s[24:25] op_sel_hi:[1,0]
	v_pk_fma_f32 v[74:75], v[74:75], 0.5, v[90:91] op_sel_hi:[1,0,1]
	v_pk_fma_f32 v[72:73], v[72:73], 0.5, v[88:89] op_sel_hi:[1,0,1]
	v_cvt_pk_bf16_f32 v89, v74, v75
	v_cvt_pk_bf16_f32 v88, v72, v73
	global_store_dwordx2 v[82:83], v[88:89], off offset:32
	s_and_b64 vcc, exec, s[6:7]
	s_waitcnt vmcnt(3)
	v_lshlrev_b32_e32 v88, 16, v222
	v_and_b32_e32 v89, 0xffff0000, v222
	v_lshlrev_b32_e32 v90, 16, v223
	v_and_b32_e32 v91, 0xffff0000, v223
	s_cbranch_vccnz .LBB0_1514
	v_sub_f32_e32 v89, v89, v84
	v_sub_f32_e32 v88, v88, v84
	v_sub_f32_e32 v91, v91, v84
	v_sub_f32_e32 v90, v90, v84
	v_pk_mul_f32 v[96:97], v[86:87], v[88:89]
	v_mov_b32_e32 v88, v86
	v_mov_b32_e32 v89, v86
	v_pk_mul_f32 v[98:99], v[88:89], v[90:91]
	v_pk_fma_f32 v[90:91], v[98:99], v[174:175], v[214:215]
	v_pk_fma_f32 v[88:89], v[96:97], v[172:173], v[212:213]
.LBB0_1514:
	v_pk_mul_f32 v[90:91], v[90:91], s[24:25] op_sel_hi:[1,0]
	v_pk_mul_f32 v[88:89], v[88:89], s[24:25] op_sel_hi:[1,0]
	v_pk_fma_f32 v[70:71], v[70:71], 0.5, v[90:91] op_sel_hi:[1,0,1]
	v_pk_fma_f32 v[68:69], v[68:69], 0.5, v[88:89] op_sel_hi:[1,0,1]
	v_cvt_pk_bf16_f32 v89, v70, v71
	v_cvt_pk_bf16_f32 v88, v68, v69
	global_store_dwordx2 v[82:83], v[88:89], off offset:256
	s_and_b64 vcc, exec, s[6:7]
	s_waitcnt vmcnt(3)
	v_lshlrev_b32_e32 v88, 16, v224
	v_and_b32_e32 v89, 0xffff0000, v224
	v_lshlrev_b32_e32 v90, 16, v225
	v_and_b32_e32 v91, 0xffff0000, v225
	s_cbranch_vccnz .LBB0_1516
	v_sub_f32_e32 v91, v91, v84
	v_sub_f32_e32 v90, v90, v84
	v_sub_f32_e32 v85, v89, v84
	v_sub_f32_e32 v84, v88, v84
	v_pk_mul_f32 v[92:93], v[86:87], v[84:85]
	v_mov_b32_e32 v87, v86
	v_pk_mul_f32 v[94:95], v[86:87], v[90:91]
	v_pk_fma_f32 v[90:91], v[94:95], v[178:179], v[218:219]
	v_pk_fma_f32 v[88:89], v[92:93], v[176:177], v[216:217]

; __device__ __forceinline__ unsigned pk2(float lo, float hi) { const f32x2_t v = {lo, hi}; const bf16x2_t b = __builtin_convertvector(v, bf16x2_t); return __builtin_bit_cast(unsigned, b); }
; __device__ __forceinline__ float bflo(unsigned w) { return __uint_as_float(w << 16); }
; __device__ __forceinline__ float bfhi(unsigned w) { return __uint_as_float(w & 0xffff0000u); }
;     __device__ __forceinline__ void operator()(const f32x4 (&acc)[2][2][4][2], const pg8::Unit& u, int wr, int wc, int fr, int fq) const {
;     ...
;                 const int row = row0 + ai * 128 + m * 16; float mu, rstd; row_stats(stats_prev, row, mu, rstd);
;                 float s = 0.f, q = 0.f;
; #pragma unroll
;                 for (int bj = 0; bj < 2; ++bj)
; #pragma unroll
;                     for (int n = 0; n < 2; ++n) {
;                         const int col = col0 + bj * 128 + n * 16;
;                         const u32x2 rb = *(const u32x2*)(YB + (size_t)row * D_ + col);
;                         f32x4 r = (f32x4){bflo(rb.x), bfhi(rb.x), bflo(rb.y), bfhi(rb.y)};
;                         if (stats_prev) { const f32x4 g4 = *(const f32x4*)(lng + col), b4 = *(const f32x4*)(lnb + col); r = (r - mu) * rstd * g4 + b4; }
;                         const f32x4 y = r * ALPHA_ + acc[ai][bj][m][n] * coef;
;                         if (Yout) *(f32x4*)(Yout + (size_t)row * D_ + col) = y;
;                         else { u32x2 w; w.x = pk2(y[0], y[1]); w.y = pk2(y[2], y[3]); *(u32x2*)(YB + (size_t)row * D_ + col) = w; }
.LBB0_1521:
	s_waitcnt lgkmcnt(0)
	v_lshlrev_b64 v[66:67], 11, v[64:65]
	v_lshl_add_u64 v[66:67], s[12:13], 0, v[66:67]
	v_lshl_add_u64 v[66:67], v[138:139], 1, v[66:67]
	global_load_dwordx2 v[74:75], v[66:67], off
	global_load_dwordx2 v[220:221], v[66:67], off offset:32
	global_load_dwordx2 v[222:223], v[66:67], off offset:256
	global_load_dwordx2 v[224:225], v[66:67], off offset:288
	v_mov_b32_e32 v71, v70
	s_and_b64 vcc, exec, s[6:7]
	s_waitcnt vmcnt(3)
	v_lshlrev_b32_e32 v72, 16, v74
	v_and_b32_e32 v73, 0xffff0000, v74
	v_lshlrev_b32_e32 v74, 16, v75
	v_and_b32_e32 v75, 0xffff0000, v75
	s_cbranch_vccnz .LBB0_1523
	v_sub_f32_e32 v73, v73, v68
	v_sub_f32_e32 v72, v72, v68
	v_sub_f32_e32 v75, v75, v68
	v_sub_f32_e32 v74, v74, v68
	v_pk_mul_f32 v[80:81], v[70:71], v[72:73]
	v_mov_b32_e32 v72, v70
	v_mov_b32_e32 v73, v70
	v_pk_mul_f32 v[82:83], v[72:73], v[74:75]
	v_pk_fma_f32 v[74:75], v[82:83], v[166:167], v[206:207]
	v_pk_fma_f32 v[72:73], v[80:81], v[164:165], v[204:205]
.LBB0_1523:
	s_mov_b32 s24, 0x3fb504f3
	v_pk_mul_f32 v[74:75], v[74:75], s[24:25] op_sel_hi:[1,0]
	v_pk_mul_f32 v[72:73], v[72:73], s[24:25] op_sel_hi:[1,0]
	v_pk_fma_f32 v[62:63], v[62:63], 0.5, v[74:75] op_sel_hi:[1,0,1]
	v_pk_fma_f32 v[60:61], v[60:61], 0.5, v[72:73] op_sel_hi:[1,0,1]
	v_cvt_pk_bf16_f32 v73, v62, v63
	v_cvt_pk_bf16_f32 v72, v60, v61
	global_store_dwordx2 v[66:67], v[72:73], off
	s_and_b64 vcc, exec, s[6:7]
	s_waitcnt vmcnt(3)
	v_lshlrev_b32_e32 v72, 16, v220
	v_and_b32_e32 v73, 0xffff0000, v220
	v_lshlrev_b32_e32 v74, 16, v221
	v_and_b32_e32 v75, 0xffff0000, v221
	s_cbranch_vccnz .LBB0_1525
	v_sub_f32_e32 v73, v73, v68
	v_sub_f32_e32 v72, v72, v68
	v_sub_f32_e32 v75, v75, v68
	v_sub_f32_e32 v74, v74, v68
	v_pk_mul_f32 v[80:81], v[70:71], v[72:73]
	v_mov_b32_e32 v72, v70
	v_mov_b32_e32 v73, v70
	v_pk_mul_f32 v[82:83], v[72:73], v[74:75]
	v_pk_fma_f32 v[74:75], v[82:83], v[170:171], v[210:211]
	v_pk_fma_f32 v[72:73], v[80:81], v[168:169], v[208:209]
.LBB0_1525:
	v_pk_mul_f32 v[74:75], v[74:75], s[24:25] op_sel_hi:[1,0]
	v_pk_mul_f32 v[72:73], v[72:73], s[24:25] op_sel_hi:[1,0]
	v_pk_fma_f32 v[58:59], v[58:59], 0.5, v[74:75] op_sel_hi:[1,0,1]
	v_pk_fma_f32 v[56:57], v[56:57], 0.5, v[72:73] op_sel_hi:[1,0,1]
	v_cvt_pk_bf16_f32 v73, v58, v59
	v_cvt_pk_bf16_f32 v72, v56, v57
	global_store_dwordx2 v[66:67], v[72:73], off offset:32
	s_and_b64 vcc, exec, s[6:7]
	s_waitcnt vmcnt(3)
	v_lshlrev_b32_e32 v72, 16, v222
	v_and_b32_e32 v73, 0xffff0000, v222
	v_lshlrev_b32_e32 v74, 16, v223
	v_and_b32_e32 v75, 0xffff0000, v223
	s_cbranch_vccnz .LBB0_1527
	v_sub_f32_e32 v73, v73, v68
	v_sub_f32_e32 v72, v72, v68
	v_sub_f32_e32 v75, v75, v68
	v_sub_f32_e32 v74, v74, v68
	v_pk_mul_f32 v[80:81], v[70:71], v[72:73]
	v_mov_b32_e32 v72, v70
	v_mov_b32_e32 v73, v70
	v_pk_mul_f32 v[82:83], v[72:73], v[74:75]
	v_pk_fma_f32 v[74:75], v[82:83], v[174:175], v[214:215]
	v_pk_fma_f32 v[72:73], v[80:81], v[172:173], v[212:213]
.LBB0_1527:
	v_pk_mul_f32 v[74:75], v[74:75], s[24:25] op_sel_hi:[1,0]
	v_pk_mul_f32 v[72:73], v[72:73], s[24:25] op_sel_hi:[1,0]
	v_pk_fma_f32 v[54:55], v[54:55], 0.5, v[74:75] op_sel_hi:[1,0,1]
	v_pk_fma_f32 v[52:53], v[52:53], 0.5, v[72:73] op_sel_hi:[1,0,1]
	v_cvt_pk_bf16_f32 v73, v54, v55
	v_cvt_pk_bf16_f32 v72, v52, v53
	global_store_dwordx2 v[66:67], v[72:73], off offset:256
	s_and_b64 vcc, exec, s[6:7]
	s_waitcnt vmcnt(3)
	v_lshlrev_b32_e32 v72, 16, v224
	v_and_b32_e32 v73, 0xffff0000, v224
	v_lshlrev_b32_e32 v74, 16, v225
	v_and_b32_e32 v75, 0xffff0000, v225
	s_cbranch_vccnz .LBB0_1529
	v_sub_f32_e32 v75, v75, v68
	v_sub_f32_e32 v74, v74, v68
	v_sub_f32_e32 v69, v73, v68
	v_sub_f32_e32 v68, v72, v68
	v_pk_mul_f32 v[76:77], v[70:71], v[68:69]
	v_mov_b32_e32 v71, v70
	v_pk_mul_f32 v[78:79], v[70:71], v[74:75]
	v_pk_fma_f32 v[74:75], v[78:79], v[178:179], v[218:219]
	v_pk_fma_f32 v[72:73], v[76:77], v[176:177], v[216:217]

; __device__ __forceinline__ unsigned pk2(float lo, float hi) { const f32x2_t v = {lo, hi}; const bf16x2_t b = __builtin_convertvector(v, bf16x2_t); return __builtin_bit_cast(unsigned, b); }
; __device__ __forceinline__ float bflo(unsigned w) { return __uint_as_float(w << 16); }
; __device__ __forceinline__ float bfhi(unsigned w) { return __uint_as_float(w & 0xffff0000u); }
;     __device__ __forceinline__ void operator()(const f32x4 (&acc)[2][2][4][2], const pg8::Unit& u, int wr, int wc, int fr, int fq) const {
;     ...
;                 const int row = row0 + ai * 128 + m * 16; float mu, rstd; row_stats(stats_prev, row, mu, rstd);
;                 float s = 0.f, q = 0.f;
; #pragma unroll
;                 for (int bj = 0; bj < 2; ++bj)
; #pragma unroll
;                     for (int n = 0; n < 2; ++n) {
;                         const int col = col0 + bj * 128 + n * 16;
;                         const u32x2 rb = *(const u32x2*)(YB + (size_t)row * D_ + col);
;                         f32x4 r = (f32x4){bflo(rb.x), bfhi(rb.x), bflo(rb.y), bfhi(rb.y)};
;                         if (stats_prev) { const f32x4 g4 = *(const f32x4*)(lng + col), b4 = *(const f32x4*)(lnb + col); r = (r - mu) * rstd * g4 + b4; }
;                         const f32x4 y = r * ALPHA_ + acc[ai][bj][m][n] * coef;
;                         if (Yout) *(f32x4*)(Yout + (size_t)row * D_ + col) = y;
;                         else { u32x2 w; w.x = pk2(y[0], y[1]); w.y = pk2(y[2], y[3]); *(u32x2*)(YB + (size_t)row * D_ + col) = w; }
.LBB0_1534:
	s_waitcnt lgkmcnt(0)
	v_lshlrev_b64 v[50:51], 11, v[48:49]
	v_lshl_add_u64 v[50:51], s[12:13], 0, v[50:51]
	v_lshl_add_u64 v[50:51], v[138:139], 1, v[50:51]
	global_load_dwordx2 v[58:59], v[50:51], off
	global_load_dwordx2 v[220:221], v[50:51], off offset:32
	global_load_dwordx2 v[222:223], v[50:51], off offset:256
	global_load_dwordx2 v[224:225], v[50:51], off offset:288
	v_mov_b32_e32 v55, v54
	s_and_b64 vcc, exec, s[6:7]
	s_waitcnt vmcnt(3)
	v_lshlrev_b32_e32 v56, 16, v58
	v_and_b32_e32 v57, 0xffff0000, v58
	v_lshlrev_b32_e32 v58, 16, v59
	v_and_b32_e32 v59, 0xffff0000, v59
	s_cbranch_vccnz .LBB0_1536
	v_sub_f32_e32 v57, v57, v52
	v_sub_f32_e32 v56, v56, v52
	v_sub_f32_e32 v59, v59, v52
	v_sub_f32_e32 v58, v58, v52
	v_pk_mul_f32 v[64:65], v[54:55], v[56:57]
	v_mov_b32_e32 v56, v54
	v_mov_b32_e32 v57, v54
	v_pk_mul_f32 v[66:67], v[56:57], v[58:59]
	v_pk_fma_f32 v[58:59], v[66:67], v[166:167], v[206:207]
	v_pk_fma_f32 v[56:57], v[64:65], v[164:165], v[204:205]
.LBB0_1536:
	s_mov_b32 s24, 0x3fb504f3
	v_pk_mul_f32 v[58:59], v[58:59], s[24:25] op_sel_hi:[1,0]
	v_pk_mul_f32 v[56:57], v[56:57], s[24:25] op_sel_hi:[1,0]
	v_pk_fma_f32 v[46:47], v[46:47], 0.5, v[58:59] op_sel_hi:[1,0,1]
	v_pk_fma_f32 v[44:45], v[44:45], 0.5, v[56:57] op_sel_hi:[1,0,1]
	v_cvt_pk_bf16_f32 v57, v46, v47
	v_cvt_pk_bf16_f32 v56, v44, v45
	global_store_dwordx2 v[50:51], v[56:57], off
	s_and_b64 vcc, exec, s[6:7]
	s_waitcnt vmcnt(3)
	v_lshlrev_b32_e32 v56, 16, v220
	v_and_b32_e32 v57, 0xffff0000, v220
	v_lshlrev_b32_e32 v58, 16, v221
	v_and_b32_e32 v59, 0xffff0000, v221
	s_cbranch_vccnz .LBB0_1538
	v_sub_f32_e32 v57, v57, v52
	v_sub_f32_e32 v56, v56, v52
	v_sub_f32_e32 v59, v59, v52
	v_sub_f32_e32 v58, v58, v52
	v_pk_mul_f32 v[64:65], v[54:55], v[56:57]
	v_mov_b32_e32 v56, v54
	v_mov_b32_e32 v57, v54
	v_pk_mul_f32 v[66:67], v[56:57], v[58:59]
	v_pk_fma_f32 v[58:59], v[66:67], v[170:171], v[210:211]
	v_pk_fma_f32 v[56:57], v[64:65], v[168:169], v[208:209]
.LBB0_1538:
	v_pk_mul_f32 v[58:59], v[58:59], s[24:25] op_sel_hi:[1,0]
	v_pk_mul_f32 v[56:57], v[56:57], s[24:25] op_sel_hi:[1,0]
	v_pk_fma_f32 v[42:43], v[42:43], 0.5, v[58:59] op_sel_hi:[1,0,1]
	v_pk_fma_f32 v[40:41], v[40:41], 0.5, v[56:57] op_sel_hi:[1,0,1]
	v_cvt_pk_bf16_f32 v57, v42, v43
	v_cvt_pk_bf16_f32 v56, v40, v41
	global_store_dwordx2 v[50:51], v[56:57], off offset:32
	s_and_b64 vcc, exec, s[6:7]
	s_waitcnt vmcnt(3)
	v_lshlrev_b32_e32 v56, 16, v222
	v_and_b32_e32 v57, 0xffff0000, v222
	v_lshlrev_b32_e32 v58, 16, v223
	v_and_b32_e32 v59, 0xffff0000, v223
	s_cbranch_vccnz .LBB0_1540
	v_sub_f32_e32 v57, v57, v52
	v_sub_f32_e32 v56, v56, v52
	v_sub_f32_e32 v59, v59, v52
	v_sub_f32_e32 v58, v58, v52
	v_pk_mul_f32 v[64:65], v[54:55], v[56:57]
	v_mov_b32_e32 v56, v54
	v_mov_b32_e32 v57, v54
	v_pk_mul_f32 v[66:67], v[56:57], v[58:59]
	v_pk_fma_f32 v[58:59], v[66:67], v[174:175], v[214:215]
	v_pk_fma_f32 v[56:57], v[64:65], v[172:173], v[212:213]
.LBB0_1540:
	v_pk_mul_f32 v[58:59], v[58:59], s[24:25] op_sel_hi:[1,0]
	v_pk_mul_f32 v[56:57], v[56:57], s[24:25] op_sel_hi:[1,0]
	v_pk_fma_f32 v[38:39], v[38:39], 0.5, v[58:59] op_sel_hi:[1,0,1]
	v_pk_fma_f32 v[36:37], v[36:37], 0.5, v[56:57] op_sel_hi:[1,0,1]
	v_cvt_pk_bf16_f32 v57, v38, v39
	v_cvt_pk_bf16_f32 v56, v36, v37
	global_store_dwordx2 v[50:51], v[56:57], off offset:256
	s_and_b64 vcc, exec, s[6:7]
	s_waitcnt vmcnt(3)
	v_lshlrev_b32_e32 v56, 16, v224
	v_and_b32_e32 v57, 0xffff0000, v224
	v_lshlrev_b32_e32 v58, 16, v225
	v_and_b32_e32 v59, 0xffff0000, v225
	s_cbranch_vccnz .LBB0_1542
	v_sub_f32_e32 v59, v59, v52
	v_sub_f32_e32 v58, v58, v52
	v_sub_f32_e32 v53, v57, v52
	v_sub_f32_e32 v52, v56, v52
	v_pk_mul_f32 v[60:61], v[54:55], v[52:53]
	v_mov_b32_e32 v55, v54
	v_pk_mul_f32 v[62:63], v[54:55], v[58:59]
	v_pk_fma_f32 v[58:59], v[62:63], v[178:179], v[218:219]
	v_pk_fma_f32 v[56:57], v[60:61], v[176:177], v[216:217]

; __device__ __forceinline__ unsigned pk2(float lo, float hi) { const f32x2_t v = {lo, hi}; const bf16x2_t b = __builtin_convertvector(v, bf16x2_t); return __builtin_bit_cast(unsigned, b); }
; __device__ __forceinline__ float bflo(unsigned w) { return __uint_as_float(w << 16); }
; __device__ __forceinline__ float bfhi(unsigned w) { return __uint_as_float(w & 0xffff0000u); }
;     __device__ __forceinline__ void operator()(const f32x4 (&acc)[2][2][4][2], const pg8::Unit& u, int wr, int wc, int fr, int fq) const {
;     ...
;                 const int row = row0 + ai * 128 + m * 16; float mu, rstd; row_stats(stats_prev, row, mu, rstd);
;                 float s = 0.f, q = 0.f;
; #pragma unroll
;                 for (int bj = 0; bj < 2; ++bj)
; #pragma unroll
;                     for (int n = 0; n < 2; ++n) {
;                         const int col = col0 + bj * 128 + n * 16;
;                         const u32x2 rb = *(const u32x2*)(YB + (size_t)row * D_ + col);
;                         f32x4 r = (f32x4){bflo(rb.x), bfhi(rb.x), bflo(rb.y), bfhi(rb.y)};
;                         if (stats_prev) { const f32x4 g4 = *(const f32x4*)(lng + col), b4 = *(const f32x4*)(lnb + col); r = (r - mu) * rstd * g4 + b4; }
;                         const f32x4 y = r * ALPHA_ + acc[ai][bj][m][n] * coef;
;                         if (Yout) *(f32x4*)(Yout + (size_t)row * D_ + col) = y;
;                         else { u32x2 w; w.x = pk2(y[0], y[1]); w.y = pk2(y[2], y[3]); *(u32x2*)(YB + (size_t)row * D_ + col) = w; }
.LBB0_1547:
	s_waitcnt lgkmcnt(0)
	v_lshlrev_b64 v[34:35], 11, v[32:33]
	v_lshl_add_u64 v[34:35], s[12:13], 0, v[34:35]
	v_lshl_add_u64 v[34:35], v[138:139], 1, v[34:35]
	global_load_dwordx2 v[42:43], v[34:35], off
	global_load_dwordx2 v[220:221], v[34:35], off offset:32
	global_load_dwordx2 v[222:223], v[34:35], off offset:256
	global_load_dwordx2 v[224:225], v[34:35], off offset:288
	v_mov_b32_e32 v39, v38
	s_and_b64 vcc, exec, s[6:7]
	s_waitcnt vmcnt(3)
	v_lshlrev_b32_e32 v40, 16, v42
	v_and_b32_e32 v41, 0xffff0000, v42
	v_lshlrev_b32_e32 v42, 16, v43
	v_and_b32_e32 v43, 0xffff0000, v43
	s_cbranch_vccnz .LBB0_1549
	v_sub_f32_e32 v41, v41, v36
	v_sub_f32_e32 v40, v40, v36
	v_sub_f32_e32 v43, v43, v36
	v_sub_f32_e32 v42, v42, v36
	v_pk_mul_f32 v[48:49], v[38:39], v[40:41]
	v_mov_b32_e32 v40, v38
	v_mov_b32_e32 v41, v38
	v_pk_mul_f32 v[50:51], v[40:41], v[42:43]
	v_pk_fma_f32 v[42:43], v[50:51], v[166:167], v[206:207]
	v_pk_fma_f32 v[40:41], v[48:49], v[164:165], v[204:205]
.LBB0_1549:
	s_mov_b32 s24, 0x3fb504f3
	v_pk_mul_f32 v[42:43], v[42:43], s[24:25] op_sel_hi:[1,0]
	v_pk_mul_f32 v[40:41], v[40:41], s[24:25] op_sel_hi:[1,0]
	v_pk_fma_f32 v[30:31], v[30:31], 0.5, v[42:43] op_sel_hi:[1,0,1]
	v_pk_fma_f32 v[28:29], v[28:29], 0.5, v[40:41] op_sel_hi:[1,0,1]
	v_cvt_pk_bf16_f32 v41, v30, v31
	v_cvt_pk_bf16_f32 v40, v28, v29
	global_store_dwordx2 v[34:35], v[40:41], off
	s_and_b64 vcc, exec, s[6:7]
	s_waitcnt vmcnt(3)
	v_lshlrev_b32_e32 v40, 16, v220
	v_and_b32_e32 v41, 0xffff0000, v220
	v_lshlrev_b32_e32 v42, 16, v221
	v_and_b32_e32 v43, 0xffff0000, v221
	s_cbranch_vccnz .LBB0_1551
	v_sub_f32_e32 v41, v41, v36
	v_sub_f32_e32 v40, v40, v36
	v_sub_f32_e32 v43, v43, v36
	v_sub_f32_e32 v42, v42, v36
	v_pk_mul_f32 v[48:49], v[38:39], v[40:41]
	v_mov_b32_e32 v40, v38
	v_mov_b32_e32 v41, v38
	v_pk_mul_f32 v[50:51], v[40:41], v[42:43]
	v_pk_fma_f32 v[42:43], v[50:51], v[170:171], v[210:211]
	v_pk_fma_f32 v[40:41], v[48:49], v[168:169], v[208:209]
.LBB0_1551:
	v_pk_mul_f32 v[42:43], v[42:43], s[24:25] op_sel_hi:[1,0]
	v_pk_mul_f32 v[40:41], v[40:41], s[24:25] op_sel_hi:[1,0]
	v_pk_fma_f32 v[26:27], v[26:27], 0.5, v[42:43] op_sel_hi:[1,0,1]
	v_pk_fma_f32 v[24:25], v[24:25], 0.5, v[40:41] op_sel_hi:[1,0,1]
	v_cvt_pk_bf16_f32 v41, v26, v27
	v_cvt_pk_bf16_f32 v40, v24, v25
	global_store_dwordx2 v[34:35], v[40:41], off offset:32
	s_and_b64 vcc, exec, s[6:7]
	s_waitcnt vmcnt(3)
	v_lshlrev_b32_e32 v40, 16, v222
	v_and_b32_e32 v41, 0xffff0000, v222
	v_lshlrev_b32_e32 v42, 16, v223
	v_and_b32_e32 v43, 0xffff0000, v223
	s_cbranch_vccnz .LBB0_1553
	v_sub_f32_e32 v41, v41, v36
	v_sub_f32_e32 v40, v40, v36
	v_sub_f32_e32 v43, v43, v36
	v_sub_f32_e32 v42, v42, v36
	v_pk_mul_f32 v[48:49], v[38:39], v[40:41]
	v_mov_b32_e32 v40, v38
	v_mov_b32_e32 v41, v38
	v_pk_mul_f32 v[50:51], v[40:41], v[42:43]
	v_pk_fma_f32 v[42:43], v[50:51], v[174:175], v[214:215]
	v_pk_fma_f32 v[40:41], v[48:49], v[172:173], v[212:213]
.LBB0_1553:
	v_pk_mul_f32 v[42:43], v[42:43], s[24:25] op_sel_hi:[1,0]
	v_pk_mul_f32 v[40:41], v[40:41], s[24:25] op_sel_hi:[1,0]
	v_pk_fma_f32 v[22:23], v[22:23], 0.5, v[42:43] op_sel_hi:[1,0,1]
	v_pk_fma_f32 v[20:21], v[20:21], 0.5, v[40:41] op_sel_hi:[1,0,1]
	v_cvt_pk_bf16_f32 v41, v22, v23
	v_cvt_pk_bf16_f32 v40, v20, v21
	global_store_dwordx2 v[34:35], v[40:41], off offset:256
	s_and_b64 vcc, exec, s[6:7]
	s_waitcnt vmcnt(3)
	v_lshlrev_b32_e32 v40, 16, v224
	v_and_b32_e32 v41, 0xffff0000, v224
	v_lshlrev_b32_e32 v42, 16, v225
	v_and_b32_e32 v43, 0xffff0000, v225
	s_cbranch_vccnz .LBB0_1555
	v_sub_f32_e32 v43, v43, v36
	v_sub_f32_e32 v42, v42, v36
	v_sub_f32_e32 v37, v41, v36
	v_sub_f32_e32 v36, v40, v36
	v_pk_mul_f32 v[44:45], v[38:39], v[36:37]
	v_mov_b32_e32 v39, v38
	v_pk_mul_f32 v[46:47], v[38:39], v[42:43]
	v_pk_fma_f32 v[42:43], v[46:47], v[178:179], v[218:219]
	v_pk_fma_f32 v[40:41], v[44:45], v[176:177], v[216:217]

; __device__ __forceinline__ unsigned pk2(float lo, float hi) { const f32x2_t v = {lo, hi}; const bf16x2_t b = __builtin_convertvector(v, bf16x2_t); return __builtin_bit_cast(unsigned, b); }
; __device__ __forceinline__ float bflo(unsigned w) { return __uint_as_float(w << 16); }
; __device__ __forceinline__ float bfhi(unsigned w) { return __uint_as_float(w & 0xffff0000u); }
;     __device__ __forceinline__ void operator()(const f32x4 (&acc)[2][2][4][2], const pg8::Unit& u, int wr, int wc, int fr, int fq) const {
;     ...
;                 const int row = row0 + ai * 128 + m * 16; float mu, rstd; row_stats(stats_prev, row, mu, rstd);
;                 float s = 0.f, q = 0.f;
; #pragma unroll
;                 for (int bj = 0; bj < 2; ++bj)
; #pragma unroll
;                     for (int n = 0; n < 2; ++n) {
;                         const int col = col0 + bj * 128 + n * 16;
;                         const u32x2 rb = *(const u32x2*)(YB + (size_t)row * D_ + col);
;                         f32x4 r = (f32x4){bflo(rb.x), bfhi(rb.x), bflo(rb.y), bfhi(rb.y)};
;                         if (stats_prev) { const f32x4 g4 = *(const f32x4*)(lng + col), b4 = *(const f32x4*)(lnb + col); r = (r - mu) * rstd * g4 + b4; }
;                         const f32x4 y = r * ALPHA_ + acc[ai][bj][m][n] * coef;
;                         if (Yout) *(f32x4*)(Yout + (size_t)row * D_ + col) = y;
;                         else { u32x2 w; w.x = pk2(y[0], y[1]); w.y = pk2(y[2], y[3]); *(u32x2*)(YB + (size_t)row * D_ + col) = w; }
.LBB0_1560:
	s_waitcnt lgkmcnt(0)
	v_lshlrev_b64 v[18:19], 11, v[16:17]
	v_lshl_add_u64 v[18:19], s[12:13], 0, v[18:19]
	v_lshl_add_u64 v[18:19], v[138:139], 1, v[18:19]
	global_load_dwordx2 v[26:27], v[18:19], off
	global_load_dwordx2 v[220:221], v[18:19], off offset:32
	global_load_dwordx2 v[222:223], v[18:19], off offset:256
	global_load_dwordx2 v[224:225], v[18:19], off offset:288
	v_mov_b32_e32 v23, v22
	s_and_b64 vcc, exec, s[6:7]
	s_waitcnt vmcnt(3)
	v_lshlrev_b32_e32 v24, 16, v26
	v_and_b32_e32 v25, 0xffff0000, v26
	v_lshlrev_b32_e32 v26, 16, v27
	v_and_b32_e32 v27, 0xffff0000, v27
	s_cbranch_vccnz .LBB0_1562
	v_sub_f32_e32 v25, v25, v20
	v_sub_f32_e32 v24, v24, v20
	v_sub_f32_e32 v27, v27, v20
	v_sub_f32_e32 v26, v26, v20
	v_pk_mul_f32 v[32:33], v[22:23], v[24:25]
	v_mov_b32_e32 v24, v22
	v_mov_b32_e32 v25, v22
	v_pk_mul_f32 v[34:35], v[24:25], v[26:27]
	v_pk_fma_f32 v[26:27], v[34:35], v[166:167], v[206:207]
	v_pk_fma_f32 v[24:25], v[32:33], v[164:165], v[204:205]
.LBB0_1562:
	s_mov_b32 s24, 0x3fb504f3
	v_pk_mul_f32 v[26:27], v[26:27], s[24:25] op_sel_hi:[1,0]
	v_pk_mul_f32 v[24:25], v[24:25], s[24:25] op_sel_hi:[1,0]
	v_pk_fma_f32 v[14:15], v[14:15], 0.5, v[26:27] op_sel_hi:[1,0,1]
	v_pk_fma_f32 v[12:13], v[12:13], 0.5, v[24:25] op_sel_hi:[1,0,1]
	v_cvt_pk_bf16_f32 v25, v14, v15
	v_cvt_pk_bf16_f32 v24, v12, v13
	global_store_dwordx2 v[18:19], v[24:25], off
	s_and_b64 vcc, exec, s[6:7]
	s_waitcnt vmcnt(3)
	v_lshlrev_b32_e32 v24, 16, v220
	v_and_b32_e32 v25, 0xffff0000, v220
	v_lshlrev_b32_e32 v26, 16, v221
	v_and_b32_e32 v27, 0xffff0000, v221
	s_cbranch_vccnz .LBB0_1564
	v_sub_f32_e32 v25, v25, v20
	v_sub_f32_e32 v24, v24, v20
	v_sub_f32_e32 v27, v27, v20
	v_sub_f32_e32 v26, v26, v20
	v_pk_mul_f32 v[32:33], v[22:23], v[24:25]
	v_mov_b32_e32 v24, v22
	v_mov_b32_e32 v25, v22
	v_pk_mul_f32 v[34:35], v[24:25], v[26:27]
	v_pk_fma_f32 v[26:27], v[34:35], v[170:171], v[210:211]
	v_pk_fma_f32 v[24:25], v[32:33], v[168:169], v[208:209]
.LBB0_1564:
	v_pk_mul_f32 v[26:27], v[26:27], s[24:25] op_sel_hi:[1,0]
	v_pk_mul_f32 v[24:25], v[24:25], s[24:25] op_sel_hi:[1,0]
	v_pk_fma_f32 v[10:11], v[10:11], 0.5, v[26:27] op_sel_hi:[1,0,1]
	v_pk_fma_f32 v[8:9], v[8:9], 0.5, v[24:25] op_sel_hi:[1,0,1]
	v_cvt_pk_bf16_f32 v25, v10, v11
	v_cvt_pk_bf16_f32 v24, v8, v9
	global_store_dwordx2 v[18:19], v[24:25], off offset:32
	s_and_b64 vcc, exec, s[6:7]
	s_waitcnt vmcnt(3)
	v_lshlrev_b32_e32 v24, 16, v222
	v_and_b32_e32 v25, 0xffff0000, v222
	v_lshlrev_b32_e32 v26, 16, v223
	v_and_b32_e32 v27, 0xffff0000, v223
	s_cbranch_vccnz .LBB0_1566
	v_sub_f32_e32 v25, v25, v20
	v_sub_f32_e32 v24, v24, v20
	v_sub_f32_e32 v27, v27, v20
	v_sub_f32_e32 v26, v26, v20
	v_pk_mul_f32 v[32:33], v[22:23], v[24:25]
	v_mov_b32_e32 v24, v22
	v_mov_b32_e32 v25, v22
	v_pk_mul_f32 v[34:35], v[24:25], v[26:27]
	v_pk_fma_f32 v[26:27], v[34:35], v[174:175], v[214:215]
	v_pk_fma_f32 v[24:25], v[32:33], v[172:173], v[212:213]
.LBB0_1566:
	v_pk_mul_f32 v[26:27], v[26:27], s[24:25] op_sel_hi:[1,0]
	v_pk_mul_f32 v[24:25], v[24:25], s[24:25] op_sel_hi:[1,0]
	v_pk_fma_f32 v[6:7], v[6:7], 0.5, v[26:27] op_sel_hi:[1,0,1]
	v_pk_fma_f32 v[4:5], v[4:5], 0.5, v[24:25] op_sel_hi:[1,0,1]
	v_cvt_pk_bf16_f32 v25, v6, v7
	v_cvt_pk_bf16_f32 v24, v4, v5
	global_store_dwordx2 v[18:19], v[24:25], off offset:256
	s_and_b64 vcc, exec, s[6:7]
	s_waitcnt vmcnt(3)
	v_lshlrev_b32_e32 v24, 16, v224
	v_and_b32_e32 v25, 0xffff0000, v224
	v_lshlrev_b32_e32 v26, 16, v225
	v_and_b32_e32 v27, 0xffff0000, v225
	s_cbranch_vccnz .LBB0_1568
	v_sub_f32_e32 v27, v27, v20
	v_sub_f32_e32 v26, v26, v20
	v_sub_f32_e32 v21, v25, v20
	v_sub_f32_e32 v20, v24, v20
	v_pk_mul_f32 v[28:29], v[22:23], v[20:21]
	v_mov_b32_e32 v23, v22
	v_pk_mul_f32 v[30:31], v[22:23], v[26:27]
	v_pk_fma_f32 v[26:27], v[30:31], v[178:179], v[218:219]
	v_pk_fma_f32 v[24:25], v[28:29], v[176:177], v[216:217]
